# v73 + phase-5 epilogue fully pipelined (rolling 9-step window of x loads); deleted loads replaced by s_nop to keep store-data wait states
# baseline (speedup 1.0000x reference)
.LBB0_332:
	ds_read_b128 v[142:145], v163
	ds_read_b128 v[146:149], v163 offset:1024
	ds_read_b128 v[166:169], v163 offset:2048
	ds_read_b128 v[170:173], v163 offset:3072
	s_add_u32 s34, s30, 0xfffc0080
	s_addc_u32 s35, s31, -1
	s_cmp_eq_u32 s63, 12
	s_cselect_b32 s37, s27, s35
	s_cselect_b32 s36, s26, s34
	s_cselect_b32 s35, s29, s62
	s_cselect_b32 s34, s28, s61
	v_lshl_add_u64 v[206:207], s[30:31], 0, v[136:137]
	s_add_i32 m0, s43, 0xc000
	ds_read_b128 v[174:177], v164
	ds_read_b128 v[178:181], v164 offset:1024
	ds_read_b128 v[182:185], v164 offset:2048
	ds_read_b128 v[186:189], v164 offset:3072
	ds_read_b128 v[190:193], v164 offset:4096
	ds_read_b128 v[194:197], v164 offset:5120
	ds_read_b128 v[198:201], v164 offset:6144
	ds_read_b128 v[202:205], v164 offset:7168
	global_load_lds_dwordx4 v[206:207], off
	v_lshl_add_u64 v[206:207], s[30:31], 0, v[138:139]
	s_add_i32 m0, s43, 0xe000
	s_nop 0
	global_load_lds_dwordx4 v[206:207], off
	s_waitcnt lgkmcnt(8)
	s_barrier
	s_waitcnt lgkmcnt(0)
	s_setprio 1
	s_waitcnt lgkmcnt(0)
	v_mfma_f32_16x16x32_bf16 v[124:127], v[142:145], v[174:177], v[124:127]
	v_mfma_f32_16x16x32_bf16 v[120:123], v[166:169], v[174:177], v[120:123]
	v_mfma_f32_16x16x32_bf16 v[112:115], v[142:145], v[182:185], v[112:115]
	v_mfma_f32_16x16x32_bf16 v[104:107], v[166:169], v[182:185], v[104:107]
	v_mfma_f32_16x16x32_bf16 v[96:99], v[142:145], v[190:193], v[96:99]
	v_mfma_f32_16x16x32_bf16 v[88:91], v[166:169], v[190:193], v[88:91]
	v_mfma_f32_16x16x32_bf16 v[80:83], v[142:145], v[198:201], v[80:83]
	v_mfma_f32_16x16x32_bf16 v[72:75], v[166:169], v[198:201], v[72:75]
	v_mfma_f32_16x16x32_bf16 v[124:127], v[146:149], v[178:181], v[124:127]
	v_mfma_f32_16x16x32_bf16 v[120:123], v[170:173], v[178:181], v[120:123]
	v_mfma_f32_16x16x32_bf16 v[112:115], v[146:149], v[186:189], v[112:115]
	v_mfma_f32_16x16x32_bf16 v[104:107], v[170:173], v[186:189], v[104:107]
	v_mfma_f32_16x16x32_bf16 v[96:99], v[146:149], v[194:197], v[96:99]
	v_mfma_f32_16x16x32_bf16 v[88:91], v[170:173], v[194:197], v[88:91]
	v_mfma_f32_16x16x32_bf16 v[80:83], v[146:149], v[202:205], v[80:83]
	v_mfma_f32_16x16x32_bf16 v[72:75], v[170:173], v[202:205], v[72:75]
	s_setprio 0
	s_barrier
	s_add_i32 s64, s57, s42
	v_lshl_add_u64 v[222:223], s[34:35], 0, v[130:131]
	s_mov_b32 m0, s64
	ds_read_b128 v[206:209], v165
	ds_read_b128 v[210:213], v165 offset:1024
	ds_read_b128 v[214:217], v165 offset:2048
	ds_read_b128 v[218:221], v165 offset:3072
	global_load_lds_dwordx4 v[222:223], off
	v_lshl_add_u64 v[224:225], s[34:35], 0, v[134:135]
	s_add_i32 m0, s64, 0x2000
	s_nop 0
	global_load_lds_dwordx4 v[224:225], off
	s_barrier
	s_waitcnt lgkmcnt(0)
	s_setprio 1
	s_waitcnt lgkmcnt(0)
	v_mfma_f32_16x16x32_bf16 v[116:119], v[206:209], v[174:177], v[116:119]
	v_mfma_f32_16x16x32_bf16 v[108:111], v[214:217], v[174:177], v[108:111]
	v_mfma_f32_16x16x32_bf16 v[100:103], v[206:209], v[182:185], v[100:103]
	v_mfma_f32_16x16x32_bf16 v[92:95], v[214:217], v[182:185], v[92:95]
	v_mfma_f32_16x16x32_bf16 v[84:87], v[206:209], v[190:193], v[84:87]
	v_mfma_f32_16x16x32_bf16 v[76:79], v[214:217], v[190:193], v[76:79]
	v_mfma_f32_16x16x32_bf16 v[68:71], v[206:209], v[198:201], v[68:71]
	v_mfma_f32_16x16x32_bf16 v[64:67], v[214:217], v[198:201], v[64:67]
	v_mfma_f32_16x16x32_bf16 v[116:119], v[210:213], v[178:181], v[116:119]
	v_mfma_f32_16x16x32_bf16 v[108:111], v[218:221], v[178:181], v[108:111]
	v_mfma_f32_16x16x32_bf16 v[100:103], v[210:213], v[186:189], v[100:103]
	v_mfma_f32_16x16x32_bf16 v[92:95], v[218:221], v[186:189], v[92:95]
	v_mfma_f32_16x16x32_bf16 v[84:87], v[210:213], v[194:197], v[84:87]
	v_mfma_f32_16x16x32_bf16 v[76:79], v[218:221], v[194:197], v[76:79]
	v_mfma_f32_16x16x32_bf16 v[68:71], v[210:213], v[202:205], v[68:71]
	v_mfma_f32_16x16x32_bf16 v[64:67], v[218:221], v[202:205], v[64:67]
	s_setprio 0
	s_mov_b32 m0, s43
	v_lshl_add_u64 v[226:227], s[36:37], 0, v[128:129]
	s_barrier
	ds_read_b128 v[174:177], v164 offset:16384
	ds_read_b128 v[178:181], v164 offset:17408
	ds_read_b128 v[182:185], v164 offset:18432
	ds_read_b128 v[186:189], v164 offset:19456
	ds_read_b128 v[190:193], v164 offset:20480
	ds_read_b128 v[194:197], v164 offset:21504
	ds_read_b128 v[198:201], v164 offset:22528
	ds_read_b128 v[202:205], v164 offset:23552
	global_load_lds_dwordx4 v[226:227], off
	v_lshl_add_u64 v[228:229], s[36:37], 0, v[132:133]
	s_mov_b32 m0, s44
	s_nop 0
	global_load_lds_dwordx4 v[228:229], off
	s_barrier
	s_waitcnt lgkmcnt(0)
	s_setprio 1
	s_waitcnt lgkmcnt(0)
	v_mfma_f32_16x16x32_bf16 v[60:63], v[142:145], v[174:177], v[60:63]
	v_mfma_f32_16x16x32_bf16 v[56:59], v[166:169], v[174:177], v[56:59]
	v_mfma_f32_16x16x32_bf16 v[48:51], v[142:145], v[182:185], v[48:51]
	v_mfma_f32_16x16x32_bf16 v[40:43], v[166:169], v[182:185], v[40:43]
	v_mfma_f32_16x16x32_bf16 v[32:35], v[142:145], v[190:193], v[32:35]
	v_mfma_f32_16x16x32_bf16 v[24:27], v[166:169], v[190:193], v[24:27]
	v_mfma_f32_16x16x32_bf16 v[12:15], v[142:145], v[198:201], v[12:15]
	v_mfma_f32_16x16x32_bf16 v[8:11], v[166:169], v[198:201], v[8:11]
	v_mfma_f32_16x16x32_bf16 v[60:63], v[146:149], v[178:181], v[60:63]
	v_mfma_f32_16x16x32_bf16 v[56:59], v[170:173], v[178:181], v[56:59]
	v_mfma_f32_16x16x32_bf16 v[48:51], v[146:149], v[186:189], v[48:51]
	v_mfma_f32_16x16x32_bf16 v[40:43], v[170:173], v[186:189], v[40:43]
	v_mfma_f32_16x16x32_bf16 v[32:35], v[146:149], v[194:197], v[32:35]
	v_mfma_f32_16x16x32_bf16 v[24:27], v[170:173], v[194:197], v[24:27]
	v_mfma_f32_16x16x32_bf16 v[12:15], v[146:149], v[202:205], v[12:15]
	v_mfma_f32_16x16x32_bf16 v[8:11], v[170:173], v[202:205], v[8:11]
	s_setprio 0
	s_barrier
	s_add_u32 s64, s34, 0x40000
	s_addc_u32 s65, s35, 0
	s_add_i32 s66, s58, s42
	v_lshl_add_u64 v[142:143], s[64:65], 0, v[130:131]
	s_mov_b32 m0, s66
	s_nop 0
	global_load_lds_dwordx4 v[142:143], off
	v_lshl_add_u64 v[142:143], s[64:65], 0, v[134:135]
	s_add_i32 m0, s66, 0x2000
	s_nop 0
	global_load_lds_dwordx4 v[142:143], off
	s_waitcnt vmcnt(6)
	s_barrier
	s_setprio 1
	v_mfma_f32_16x16x32_bf16 v[52:55], v[206:209], v[174:177], v[52:55]
	v_mfma_f32_16x16x32_bf16 v[44:47], v[214:217], v[174:177], v[44:47]
	v_mfma_f32_16x16x32_bf16 v[36:39], v[206:209], v[182:185], v[36:39]
	v_mfma_f32_16x16x32_bf16 v[28:31], v[214:217], v[182:185], v[28:31]
	v_mfma_f32_16x16x32_bf16 v[20:23], v[206:209], v[190:193], v[20:23]
	v_mfma_f32_16x16x32_bf16 v[16:19], v[214:217], v[190:193], v[16:19]
	v_mfma_f32_16x16x32_bf16 v[4:7], v[206:209], v[198:201], v[4:7]
	v_mfma_f32_16x16x32_bf16 v[0:3], v[214:217], v[198:201], v[0:3]
	v_mfma_f32_16x16x32_bf16 v[52:55], v[210:213], v[178:181], v[52:55]
	v_mfma_f32_16x16x32_bf16 v[44:47], v[218:221], v[178:181], v[44:47]
	v_mfma_f32_16x16x32_bf16 v[36:39], v[210:213], v[186:189], v[36:39]
	v_mfma_f32_16x16x32_bf16 v[28:31], v[218:221], v[186:189], v[28:31]
	v_mfma_f32_16x16x32_bf16 v[20:23], v[210:213], v[194:197], v[20:23]
	v_mfma_f32_16x16x32_bf16 v[16:19], v[218:221], v[194:197], v[16:19]
	v_mfma_f32_16x16x32_bf16 v[4:7], v[210:213], v[202:205], v[4:7]
	v_mfma_f32_16x16x32_bf16 v[0:3], v[218:221], v[202:205], v[0:3]
	s_setprio 0
	s_add_i32 s64, 0, 0x18000
	v_add_u32_e32 v170, s64, v151
	s_barrier
	ds_read_b128 v[142:145], v170
	ds_read_b128 v[146:149], v170 offset:1024
	ds_read_b128 v[166:169], v170 offset:2048
	ds_read_b128 v[170:173], v170 offset:3072
	s_add_u32 s36, s36, 0x40000
	s_addc_u32 s37, s37, 0
	s_mov_b32 m0, s45
	v_lshl_add_u64 v[206:207], s[36:37], 0, v[128:129]
	ds_read_b128 v[174:177], v164 offset:32768
	ds_read_b128 v[178:181], v164 offset:33792
	ds_read_b128 v[182:185], v164 offset:34816
	ds_read_b128 v[186:189], v164 offset:35840
	ds_read_b128 v[190:193], v164 offset:36864
	ds_read_b128 v[194:197], v164 offset:37888
	ds_read_b128 v[198:201], v164 offset:38912
	ds_read_b128 v[202:205], v164 offset:39936
	global_load_lds_dwordx4 v[206:207], off
	v_lshl_add_u64 v[206:207], s[36:37], 0, v[132:133]
	s_mov_b32 m0, s46
	s_nop 0
	global_load_lds_dwordx4 v[206:207], off
	s_waitcnt lgkmcnt(8)
	s_barrier
	s_waitcnt lgkmcnt(0)
	s_setprio 1
	s_waitcnt lgkmcnt(0)
	v_mfma_f32_16x16x32_bf16 v[124:127], v[142:145], v[174:177], v[124:127]
	v_mfma_f32_16x16x32_bf16 v[120:123], v[166:169], v[174:177], v[120:123]
	v_mfma_f32_16x16x32_bf16 v[112:115], v[142:145], v[182:185], v[112:115]
	v_mfma_f32_16x16x32_bf16 v[104:107], v[166:169], v[182:185], v[104:107]
	v_mfma_f32_16x16x32_bf16 v[96:99], v[142:145], v[190:193], v[96:99]
	v_mfma_f32_16x16x32_bf16 v[88:91], v[166:169], v[190:193], v[88:91]
	v_mfma_f32_16x16x32_bf16 v[80:83], v[142:145], v[198:201], v[80:83]
	v_mfma_f32_16x16x32_bf16 v[72:75], v[166:169], v[198:201], v[72:75]
	v_mfma_f32_16x16x32_bf16 v[124:127], v[146:149], v[178:181], v[124:127]
	v_mfma_f32_16x16x32_bf16 v[120:123], v[170:173], v[178:181], v[120:123]
	v_mfma_f32_16x16x32_bf16 v[112:115], v[146:149], v[186:189], v[112:115]
	v_mfma_f32_16x16x32_bf16 v[104:107], v[170:173], v[186:189], v[104:107]
	v_mfma_f32_16x16x32_bf16 v[96:99], v[146:149], v[194:197], v[96:99]
	v_mfma_f32_16x16x32_bf16 v[88:91], v[170:173], v[194:197], v[88:91]
	v_mfma_f32_16x16x32_bf16 v[80:83], v[146:149], v[202:205], v[80:83]
	v_mfma_f32_16x16x32_bf16 v[72:75], v[170:173], v[202:205], v[72:75]
	s_setprio 0
	s_barrier
	s_add_i32 s36, 0, 0x1c000
	s_add_i32 s37, s64, s42
	v_add_u32_e32 v218, s36, v151
	v_lshl_add_u64 v[222:223], v[222:223], 0, s[10:11]
	s_mov_b32 m0, s37
	ds_read_b128 v[206:209], v218
	ds_read_b128 v[210:213], v218 offset:1024
	ds_read_b128 v[214:217], v218 offset:2048
	ds_read_b128 v[218:221], v218 offset:3072
	global_load_lds_dwordx4 v[222:223], off
	v_lshl_add_u64 v[222:223], v[224:225], 0, s[10:11]
	s_add_i32 m0, s37, 0x2000
	s_nop 0
	global_load_lds_dwordx4 v[222:223], off
	s_barrier
	s_waitcnt lgkmcnt(0)
	s_setprio 1
	s_waitcnt lgkmcnt(0)
	v_mfma_f32_16x16x32_bf16 v[116:119], v[206:209], v[174:177], v[116:119]
	v_mfma_f32_16x16x32_bf16 v[108:111], v[214:217], v[174:177], v[108:111]
	v_mfma_f32_16x16x32_bf16 v[100:103], v[206:209], v[182:185], v[100:103]
	v_mfma_f32_16x16x32_bf16 v[92:95], v[214:217], v[182:185], v[92:95]
	v_mfma_f32_16x16x32_bf16 v[84:87], v[206:209], v[190:193], v[84:87]
	v_mfma_f32_16x16x32_bf16 v[76:79], v[214:217], v[190:193], v[76:79]
	v_mfma_f32_16x16x32_bf16 v[68:71], v[206:209], v[198:201], v[68:71]
	v_mfma_f32_16x16x32_bf16 v[64:67], v[214:217], v[198:201], v[64:67]
	v_mfma_f32_16x16x32_bf16 v[116:119], v[210:213], v[178:181], v[116:119]
	v_mfma_f32_16x16x32_bf16 v[108:111], v[218:221], v[178:181], v[108:111]
	v_mfma_f32_16x16x32_bf16 v[100:103], v[210:213], v[186:189], v[100:103]
	v_mfma_f32_16x16x32_bf16 v[92:95], v[218:221], v[186:189], v[92:95]
	v_mfma_f32_16x16x32_bf16 v[84:87], v[210:213], v[194:197], v[84:87]
	v_mfma_f32_16x16x32_bf16 v[76:79], v[218:221], v[194:197], v[76:79]
	v_mfma_f32_16x16x32_bf16 v[68:71], v[210:213], v[202:205], v[68:71]
	v_mfma_f32_16x16x32_bf16 v[64:67], v[218:221], v[202:205], v[64:67]
	s_setprio 0
	s_mov_b32 m0, s51
	v_lshl_add_u64 v[222:223], v[226:227], 0, s[10:11]
	s_barrier
	ds_read_b128 v[174:177], v164 offset:49152
	ds_read_b128 v[178:181], v164 offset:50176
	ds_read_b128 v[182:185], v164 offset:51200
	ds_read_b128 v[186:189], v164 offset:52224
	ds_read_b128 v[190:193], v164 offset:53248
	ds_read_b128 v[194:197], v164 offset:54272
	ds_read_b128 v[198:201], v164 offset:55296
	ds_read_b128 v[202:205], v164 offset:56320
	global_load_lds_dwordx4 v[222:223], off
	v_lshl_add_u64 v[222:223], v[228:229], 0, s[10:11]
	s_mov_b32 m0, s52
	s_nop 0
	global_load_lds_dwordx4 v[222:223], off
	s_barrier
	s_waitcnt lgkmcnt(0)
	s_setprio 1
	s_waitcnt lgkmcnt(0)
	v_mfma_f32_16x16x32_bf16 v[60:63], v[142:145], v[174:177], v[60:63]
	v_mfma_f32_16x16x32_bf16 v[56:59], v[166:169], v[174:177], v[56:59]
	v_mfma_f32_16x16x32_bf16 v[48:51], v[142:145], v[182:185], v[48:51]
	v_mfma_f32_16x16x32_bf16 v[40:43], v[166:169], v[182:185], v[40:43]
	v_mfma_f32_16x16x32_bf16 v[32:35], v[142:145], v[190:193], v[32:35]
	v_mfma_f32_16x16x32_bf16 v[24:27], v[166:169], v[190:193], v[24:27]
	v_mfma_f32_16x16x32_bf16 v[12:15], v[142:145], v[198:201], v[12:15]
	v_mfma_f32_16x16x32_bf16 v[8:11], v[166:169], v[198:201], v[8:11]
	v_mfma_f32_16x16x32_bf16 v[60:63], v[146:149], v[178:181], v[60:63]
	v_mfma_f32_16x16x32_bf16 v[56:59], v[170:173], v[178:181], v[56:59]
	v_mfma_f32_16x16x32_bf16 v[48:51], v[146:149], v[186:189], v[48:51]
	v_mfma_f32_16x16x32_bf16 v[40:43], v[170:173], v[186:189], v[40:43]
	v_mfma_f32_16x16x32_bf16 v[32:35], v[146:149], v[194:197], v[32:35]
	v_mfma_f32_16x16x32_bf16 v[24:27], v[170:173], v[194:197], v[24:27]
	v_mfma_f32_16x16x32_bf16 v[12:15], v[146:149], v[202:205], v[12:15]
	v_mfma_f32_16x16x32_bf16 v[8:11], v[170:173], v[202:205], v[8:11]
	s_setprio 0
	s_barrier
	s_add_u32 s34, s34, 0x40080
	s_addc_u32 s35, s35, 0
	s_add_i32 s36, s36, s42
	v_lshl_add_u64 v[142:143], s[34:35], 0, v[130:131]
	s_mov_b32 m0, s36
	s_nop 0
	global_load_lds_dwordx4 v[142:143], off
	v_lshl_add_u64 v[142:143], s[34:35], 0, v[134:135]
	s_add_i32 m0, s36, 0x2000
	s_nop 0
	global_load_lds_dwordx4 v[142:143], off
	s_waitcnt vmcnt(6)
	s_barrier
	s_setprio 1
	v_mfma_f32_16x16x32_bf16 v[52:55], v[206:209], v[174:177], v[52:55]
	v_mfma_f32_16x16x32_bf16 v[44:47], v[214:217], v[174:177], v[44:47]
	v_mfma_f32_16x16x32_bf16 v[36:39], v[206:209], v[182:185], v[36:39]
	v_mfma_f32_16x16x32_bf16 v[28:31], v[214:217], v[182:185], v[28:31]
	v_mfma_f32_16x16x32_bf16 v[20:23], v[206:209], v[190:193], v[20:23]
	v_mfma_f32_16x16x32_bf16 v[16:19], v[214:217], v[190:193], v[16:19]
	v_mfma_f32_16x16x32_bf16 v[4:7], v[206:209], v[198:201], v[4:7]
	v_mfma_f32_16x16x32_bf16 v[0:3], v[214:217], v[198:201], v[0:3]
	v_mfma_f32_16x16x32_bf16 v[52:55], v[210:213], v[178:181], v[52:55]
	v_mfma_f32_16x16x32_bf16 v[44:47], v[218:221], v[178:181], v[44:47]
	v_mfma_f32_16x16x32_bf16 v[36:39], v[210:213], v[186:189], v[36:39]
	v_mfma_f32_16x16x32_bf16 v[28:31], v[218:221], v[186:189], v[28:31]
	v_mfma_f32_16x16x32_bf16 v[20:23], v[210:213], v[194:197], v[20:23]
	v_mfma_f32_16x16x32_bf16 v[16:19], v[218:221], v[194:197], v[16:19]
	v_mfma_f32_16x16x32_bf16 v[4:7], v[210:213], v[202:205], v[4:7]
	v_mfma_f32_16x16x32_bf16 v[0:3], v[218:221], v[202:205], v[0:3]
	s_setprio 0
	s_add_i32 s63, s63, 2
	s_add_u32 s30, s30, 0x100
	s_addc_u32 s31, s31, 0
	s_add_u32 s61, s61, 0x100
	s_addc_u32 s62, s62, 0
	s_cmp_gt_u32 s63, 13
	s_barrier
	s_cbranch_scc0 .LBB0_332
	v_add_u32_e32 v142, s60, v150
	s_cmp_lt_i32 s60, 0x8000
	v_readlane_b32 s60, v254, 0
	v_add_u32_e32 v144, s50, v152
	v_readlane_b32 s61, v254, 1
	v_ashrrev_i32_e32 v143, 31, v142
	s_mov_b64 s[36:37], s[60:61]
	v_ashrrev_i32_e32 v145, 31, v144
	v_lshlrev_b64 v[146:147], 10, v[142:143]
	s_cselect_b32 s31, s37, s56
	s_cselect_b32 s30, s36, s55
	v_lshl_add_u64 v[144:145], v[146:147], 0, v[144:145]
	v_lshl_add_u64 v[170:171], v[144:145], 2, s[30:31]
	global_load_dwordx4 v[146:149], v[170:171], off
	global_load_dwordx4 v[166:169], v[170:171], off offset:16
	global_load_dwordx4 v[178:181], v[170:171], off offset:512
	global_load_dwordx4 v[182:185], v[170:171], off offset:528
	v_lshl_add_u64 v[250:251], v[144:145], 0, s[12:13]
	v_lshl_add_u64 v[252:253], v[250:251], 2, s[30:31]
	global_load_dwordx4 v[186:189], v[252:253], off
	v_lshl_add_u64 v[250:251], v[144:145], 0, s[12:13]
	v_lshl_add_u64 v[252:253], v[250:251], 2, s[30:31]
	global_load_dwordx4 v[190:193], v[252:253], off offset:16
	v_lshl_add_u64 v[250:251], v[144:145], 0, s[12:13]
	v_lshl_add_u64 v[252:253], v[250:251], 2, s[30:31]
	global_load_dwordx4 v[194:197], v[252:253], off offset:512
	v_lshl_add_u64 v[250:251], v[144:145], 0, s[12:13]
	v_lshl_add_u64 v[252:253], v[250:251], 2, s[30:31]
	global_load_dwordx4 v[198:201], v[252:253], off offset:528
	v_lshl_add_u64 v[250:251], v[144:145], 0, s[14:15]
	v_lshl_add_u64 v[252:253], v[250:251], 2, s[30:31]
	global_load_dwordx4 v[202:205], v[252:253], off
	v_lshl_add_u64 v[250:251], v[144:145], 0, s[14:15]
	v_lshl_add_u64 v[252:253], v[250:251], 2, s[30:31]
	global_load_dwordx4 v[206:209], v[252:253], off offset:16
	v_lshl_add_u64 v[250:251], v[144:145], 0, s[14:15]
	v_lshl_add_u64 v[252:253], v[250:251], 2, s[30:31]
	global_load_dwordx4 v[210:213], v[252:253], off offset:512
	v_lshl_add_u64 v[250:251], v[144:145], 0, s[14:15]
	v_lshl_add_u64 v[252:253], v[250:251], 2, s[30:31]
	global_load_dwordx4 v[214:217], v[252:253], off offset:528
	v_lshl_add_u64 v[250:251], v[144:145], 0, s[16:17]
	v_lshl_add_u64 v[252:253], v[250:251], 2, s[30:31]
	global_load_dwordx4 v[218:221], v[252:253], off
	v_lshl_add_u64 v[250:251], v[144:145], 0, s[16:17]
	v_lshl_add_u64 v[252:253], v[250:251], 2, s[30:31]
	global_load_dwordx4 v[222:225], v[252:253], off offset:16
	v_lshl_add_u64 v[250:251], v[144:145], 0, s[16:17]
	v_lshl_add_u64 v[252:253], v[250:251], 2, s[30:31]
	global_load_dwordx4 v[226:229], v[252:253], off offset:512
	v_lshl_add_u64 v[250:251], v[144:145], 0, s[16:17]
	v_lshl_add_u64 v[252:253], v[250:251], 2, s[30:31]
	global_load_dwordx4 v[230:233], v[252:253], off offset:528
	v_lshl_add_u64 v[250:251], v[144:145], 0, s[18:19]
	v_lshl_add_u64 v[252:253], v[250:251], 2, s[30:31]
	global_load_dwordx4 v[234:237], v[252:253], off
	v_lshl_add_u64 v[250:251], v[144:145], 0, s[18:19]
	v_lshl_add_u64 v[252:253], v[250:251], 2, s[30:31]
	global_load_dwordx4 v[238:241], v[252:253], off offset:16
	v_lshl_add_u64 v[250:251], v[144:145], 0, s[18:19]
	v_lshl_add_u64 v[252:253], v[250:251], 2, s[30:31]
	global_load_dwordx4 v[242:245], v[252:253], off offset:512
	v_lshl_add_u64 v[250:251], v[144:145], 0, s[18:19]
	v_lshl_add_u64 v[252:253], v[250:251], 2, s[30:31]
	global_load_dwordx4 v[246:249], v[252:253], off offset:528
	v_readlane_b32 s34, v254, 56
	v_readlane_b32 s35, v254, 57
	v_lshl_add_u64 v[174:175], v[144:145], 0, s[12:13]
	v_lshl_add_u64 v[176:177], v[174:175], 2, s[30:31]
	v_lshl_add_u64 v[172:173], v[144:145], 1, s[34:35]
	v_lshl_add_u64 v[174:175], v[174:175], 1, s[34:35]
	v_readlane_b32 s62, v254, 2
	v_readlane_b32 s63, v254, 3
	v_readlane_b32 s64, v254, 4
	v_readlane_b32 s65, v254, 5
	v_readlane_b32 s66, v254, 6
	v_readlane_b32 s67, v254, 7
	v_readlane_b32 s68, v254, 8
	v_readlane_b32 s69, v254, 9
	v_readlane_b32 s70, v254, 10
	v_readlane_b32 s71, v254, 11
	v_readlane_b32 s72, v254, 12
	v_readlane_b32 s73, v254, 13
	v_readlane_b32 s74, v254, 14
	v_readlane_b32 s75, v254, 15
	s_waitcnt vmcnt(18)
	v_pk_add_f32 v[126:127], v[126:127], v[148:149]
	v_pk_add_f32 v[124:125], v[124:125], v[146:147]
	v_pk_add_f32 v[122:123], v[122:123], v[168:169]
	v_pk_add_f32 v[120:121], v[120:121], v[166:167]
	v_cvt_pk_bf16_f32 v146, v124, v125
	v_cvt_pk_bf16_f32 v147, v126, v127
	v_cvt_pk_bf16_f32 v149, v122, v123
	s_nop 0
	v_cvt_pk_bf16_f32 v148, v120, v121
	global_store_dwordx4 v[172:173], v[146:149], off
	s_nop 0
	s_nop 0
	s_nop 0
	s_waitcnt vmcnt(17)
	s_nop 1
	v_mov_b32_e32 v146, v178
	v_mov_b32_e32 v147, v179
	v_mov_b32_e32 v148, v180
	v_mov_b32_e32 v149, v181
	v_mov_b32_e32 v166, v182
	v_mov_b32_e32 v167, v183
	v_mov_b32_e32 v168, v184
	v_mov_b32_e32 v169, v185
	v_lshl_add_u64 v[250:251], v[144:145], 0, s[20:21]
	v_lshl_add_u64 v[252:253], v[250:251], 2, s[30:31]
	global_load_dwordx4 v[178:181], v[252:253], off
	v_lshl_add_u64 v[250:251], v[144:145], 0, s[20:21]
	v_lshl_add_u64 v[252:253], v[250:251], 2, s[30:31]
	global_load_dwordx4 v[182:185], v[252:253], off offset:16
	v_pk_add_f32 v[118:119], v[118:119], v[148:149]
	v_pk_add_f32 v[148:149], v[116:117], v[146:147]
	v_pk_add_f32 v[116:117], v[110:111], v[168:169]
	v_pk_add_f32 v[146:147], v[108:109], v[166:167]
	v_cvt_pk_bf16_f32 v108, v148, v149
	v_cvt_pk_bf16_f32 v109, v118, v119
	v_cvt_pk_bf16_f32 v111, v116, v117
	s_nop 0
	v_cvt_pk_bf16_f32 v110, v146, v147
	global_store_dwordx4 v[172:173], v[108:111], off offset:256
	s_nop 0
	s_nop 0
	s_nop 0
	s_waitcnt vmcnt(18)
	s_nop 1
	v_mov_b32_e32 v166, v186
	v_mov_b32_e32 v167, v187
	v_mov_b32_e32 v168, v188
	v_mov_b32_e32 v169, v189
	v_mov_b32_e32 v170, v190
	v_mov_b32_e32 v171, v191
	v_mov_b32_e32 v172, v192
	v_mov_b32_e32 v173, v193
	v_lshl_add_u64 v[250:251], v[144:145], 0, s[20:21]
	v_lshl_add_u64 v[252:253], v[250:251], 2, s[30:31]
	global_load_dwordx4 v[186:189], v[252:253], off offset:512
	v_lshl_add_u64 v[250:251], v[144:145], 0, s[20:21]
	v_lshl_add_u64 v[252:253], v[250:251], 2, s[30:31]
	global_load_dwordx4 v[190:193], v[252:253], off offset:528
	v_pk_add_f32 v[108:109], v[114:115], v[168:169]
	v_pk_add_f32 v[110:111], v[112:113], v[166:167]
	v_pk_add_f32 v[106:107], v[106:107], v[172:173]
	v_pk_add_f32 v[104:105], v[104:105], v[170:171]
	v_cvt_pk_bf16_f32 v112, v110, v111
	v_cvt_pk_bf16_f32 v113, v108, v109
	v_cvt_pk_bf16_f32 v115, v106, v107
	v_lshl_add_u64 v[170:171], v[144:145], 0, s[14:15]
	v_cvt_pk_bf16_f32 v114, v104, v105
	global_store_dwordx4 v[174:175], v[112:115], off
	s_nop 0
	s_nop 0
	s_nop 0
	v_lshl_add_u64 v[172:173], v[170:171], 2, s[30:31]
	v_lshl_add_u64 v[170:171], v[170:171], 1, s[34:35]
	s_waitcnt vmcnt(19)
	s_nop 1
	v_mov_b32_e32 v112, v194
	v_mov_b32_e32 v113, v195
	v_mov_b32_e32 v114, v196
	v_mov_b32_e32 v115, v197
	v_mov_b32_e32 v166, v198
	v_mov_b32_e32 v167, v199
	v_mov_b32_e32 v168, v200
	v_mov_b32_e32 v169, v201
	v_lshl_add_u64 v[250:251], v[144:145], 0, s[22:23]
	v_lshl_add_u64 v[252:253], v[250:251], 2, s[30:31]
	global_load_dwordx4 v[194:197], v[252:253], off
	v_lshl_add_u64 v[250:251], v[144:145], 0, s[22:23]
	v_lshl_add_u64 v[252:253], v[250:251], 2, s[30:31]
	global_load_dwordx4 v[198:201], v[252:253], off offset:16
	v_pk_add_f32 v[102:103], v[102:103], v[114:115]
	v_pk_add_f32 v[100:101], v[100:101], v[112:113]
	v_pk_add_f32 v[94:95], v[94:95], v[168:169]
	v_pk_add_f32 v[92:93], v[92:93], v[166:167]
	v_cvt_pk_bf16_f32 v112, v100, v101
	v_cvt_pk_bf16_f32 v113, v102, v103
	v_cvt_pk_bf16_f32 v115, v94, v95
	s_nop 0
	v_cvt_pk_bf16_f32 v114, v92, v93
	global_store_dwordx4 v[174:175], v[112:115], off offset:256
	s_nop 0
	s_nop 0
	s_nop 0
	s_waitcnt vmcnt(20)
	s_nop 1
	v_mov_b32_e32 v112, v202
	v_mov_b32_e32 v113, v203
	v_mov_b32_e32 v114, v204
	v_mov_b32_e32 v115, v205
	v_mov_b32_e32 v166, v206
	v_mov_b32_e32 v167, v207
	v_mov_b32_e32 v168, v208
	v_mov_b32_e32 v169, v209
	v_lshl_add_u64 v[250:251], v[144:145], 0, s[22:23]
	v_lshl_add_u64 v[252:253], v[250:251], 2, s[30:31]
	global_load_dwordx4 v[202:205], v[252:253], off offset:512
	v_lshl_add_u64 v[250:251], v[144:145], 0, s[22:23]
	v_lshl_add_u64 v[252:253], v[250:251], 2, s[30:31]
	global_load_dwordx4 v[206:209], v[252:253], off offset:528
	v_pk_add_f32 v[98:99], v[98:99], v[114:115]
	v_pk_add_f32 v[96:97], v[96:97], v[112:113]
	v_pk_add_f32 v[90:91], v[90:91], v[168:169]
	v_pk_add_f32 v[88:89], v[88:89], v[166:167]
	v_cvt_pk_bf16_f32 v112, v96, v97
	v_cvt_pk_bf16_f32 v113, v98, v99
	v_cvt_pk_bf16_f32 v115, v90, v91
	s_nop 0
	v_cvt_pk_bf16_f32 v114, v88, v89
	global_store_dwordx4 v[170:171], v[112:115], off
	s_nop 0
	s_nop 0
	s_nop 0
	v_lshl_add_u64 v[172:173], v[144:145], 0, s[16:17]
	v_lshl_add_u64 v[174:175], v[172:173], 2, s[30:31]
	s_waitcnt vmcnt(21)
	s_nop 1
	v_mov_b32_e32 v112, v210
	v_mov_b32_e32 v113, v211
	v_mov_b32_e32 v114, v212
	v_mov_b32_e32 v115, v213
	v_mov_b32_e32 v166, v214
	v_mov_b32_e32 v167, v215
	v_mov_b32_e32 v168, v216
	v_mov_b32_e32 v169, v217
	v_lshl_add_u64 v[250:251], v[144:145], 0, s[24:25]
	v_lshl_add_u64 v[252:253], v[250:251], 2, s[30:31]
	global_load_dwordx4 v[210:213], v[252:253], off
	v_lshl_add_u64 v[250:251], v[144:145], 0, s[24:25]
	v_lshl_add_u64 v[252:253], v[250:251], 2, s[30:31]
	global_load_dwordx4 v[214:217], v[252:253], off offset:16
	v_pk_add_f32 v[86:87], v[86:87], v[114:115]
	v_pk_add_f32 v[84:85], v[84:85], v[112:113]
	v_pk_add_f32 v[78:79], v[78:79], v[168:169]
	v_pk_add_f32 v[76:77], v[76:77], v[166:167]
	v_cvt_pk_bf16_f32 v112, v84, v85
	v_cvt_pk_bf16_f32 v113, v86, v87
	v_cvt_pk_bf16_f32 v115, v78, v79
	v_mul_f32_e32 v85, v85, v85
	v_cvt_pk_bf16_f32 v114, v76, v77
	global_store_dwordx4 v[170:171], v[112:115], off offset:256
	s_nop 0
	s_nop 0
	s_nop 0
	v_lshl_add_u64 v[170:171], v[172:173], 1, s[34:35]
	v_lshl_add_u64 v[172:173], v[144:145], 0, s[18:19]
	v_fmac_f32_e32 v85, v84, v84
	v_fmac_f32_e32 v85, v86, v86
	v_fmac_f32_e32 v85, v87, v87
	v_fmac_f32_e32 v85, v76, v76
	v_fmac_f32_e32 v85, v77, v77
	v_fmac_f32_e32 v85, v78, v78
	v_fmac_f32_e32 v85, v79, v79
	s_waitcnt vmcnt(22)
	s_nop 1
	v_mov_b32_e32 v112, v218
	v_mov_b32_e32 v113, v219
	v_mov_b32_e32 v114, v220
	v_mov_b32_e32 v115, v221
	v_mov_b32_e32 v166, v222
	v_mov_b32_e32 v167, v223
	v_mov_b32_e32 v168, v224
	v_mov_b32_e32 v169, v225
	v_lshl_add_u64 v[250:251], v[144:145], 0, s[24:25]
	v_lshl_add_u64 v[252:253], v[250:251], 2, s[30:31]
	global_load_dwordx4 v[218:221], v[252:253], off offset:528
	v_lshl_add_u64 v[250:251], v[144:145], 0, s[24:25]
	v_lshl_add_u64 v[252:253], v[250:251], 2, s[30:31]
	global_load_dwordx4 v[222:225], v[252:253], off offset:512
	v_pk_add_f32 v[82:83], v[82:83], v[114:115]
	v_pk_add_f32 v[80:81], v[80:81], v[112:113]
	v_pk_add_f32 v[74:75], v[74:75], v[168:169]
	v_pk_add_f32 v[72:73], v[72:73], v[166:167]
	v_cvt_pk_bf16_f32 v112, v80, v81
	v_cvt_pk_bf16_f32 v113, v82, v83
	v_cvt_pk_bf16_f32 v115, v74, v75
	v_mul_f32_e32 v86, v81, v81
	v_cvt_pk_bf16_f32 v114, v72, v73
	global_store_dwordx4 v[170:171], v[112:115], off
	s_nop 0
	s_nop 0
	s_nop 0
	v_lshl_add_u64 v[174:175], v[172:173], 2, s[30:31]
	v_fmac_f32_e32 v86, v80, v80
	v_fmac_f32_e32 v86, v82, v82
	v_fmac_f32_e32 v86, v83, v83
	v_fmac_f32_e32 v86, v72, v72
	v_fmac_f32_e32 v86, v73, v73
	v_fmac_f32_e32 v86, v74, v74
	v_fmac_f32_e32 v86, v75, v75
	s_waitcnt vmcnt(23)
	s_nop 1
	v_mov_b32_e32 v112, v226
	v_mov_b32_e32 v113, v227
	v_mov_b32_e32 v114, v228
	v_mov_b32_e32 v115, v229
	v_mov_b32_e32 v166, v230
	v_mov_b32_e32 v167, v231
	v_mov_b32_e32 v168, v232
	v_mov_b32_e32 v169, v233
	v_pk_add_f32 v[70:71], v[70:71], v[114:115]
	v_pk_add_f32 v[68:69], v[68:69], v[112:113]
	v_pk_add_f32 v[66:67], v[66:67], v[168:169]
	v_pk_add_f32 v[64:65], v[64:65], v[166:167]
	v_cvt_pk_bf16_f32 v112, v68, v69
	v_cvt_pk_bf16_f32 v113, v70, v71
	v_cvt_pk_bf16_f32 v115, v66, v67
	s_nop 0
	v_cvt_pk_bf16_f32 v114, v64, v65
	global_store_dwordx4 v[170:171], v[112:115], off offset:256
	s_nop 0
	s_nop 0
	s_nop 0
	v_lshl_add_u64 v[170:171], v[172:173], 1, s[34:35]
	v_lshl_add_u64 v[172:173], v[144:145], 0, s[20:21]
	s_waitcnt vmcnt(22)
	s_nop 1
	v_mov_b32_e32 v112, v234
	v_mov_b32_e32 v113, v235
	v_mov_b32_e32 v114, v236
	v_mov_b32_e32 v115, v237
	v_mov_b32_e32 v166, v238
	v_mov_b32_e32 v167, v239
	v_mov_b32_e32 v168, v240
	v_mov_b32_e32 v169, v241
	v_pk_add_f32 v[62:63], v[62:63], v[114:115]
	v_pk_add_f32 v[60:61], v[60:61], v[112:113]
	v_pk_add_f32 v[58:59], v[58:59], v[168:169]
	v_pk_add_f32 v[56:57], v[56:57], v[166:167]
	v_cvt_pk_bf16_f32 v112, v60, v61
	v_cvt_pk_bf16_f32 v113, v62, v63
	v_cvt_pk_bf16_f32 v115, v58, v59
	s_nop 0
	v_cvt_pk_bf16_f32 v114, v56, v57
	global_store_dwordx4 v[170:171], v[112:115], off
	s_nop 0
	s_nop 0
	s_nop 0
	v_lshl_add_u64 v[174:175], v[172:173], 2, s[30:31]
	s_waitcnt vmcnt(21)
	s_nop 1
	v_mov_b32_e32 v112, v242
	v_mov_b32_e32 v113, v243
	v_mov_b32_e32 v114, v244
	v_mov_b32_e32 v115, v245
	v_mov_b32_e32 v166, v246
	v_mov_b32_e32 v167, v247
	v_mov_b32_e32 v168, v248
	v_mov_b32_e32 v169, v249
	v_pk_add_f32 v[54:55], v[54:55], v[114:115]
	v_pk_add_f32 v[52:53], v[52:53], v[112:113]
	v_pk_add_f32 v[46:47], v[46:47], v[168:169]
	v_pk_add_f32 v[44:45], v[44:45], v[166:167]
	v_cvt_pk_bf16_f32 v112, v52, v53
	v_cvt_pk_bf16_f32 v113, v54, v55
	v_cvt_pk_bf16_f32 v115, v46, v47
	s_nop 0
	v_cvt_pk_bf16_f32 v114, v44, v45
	global_store_dwordx4 v[170:171], v[112:115], off offset:256
	s_nop 0
	s_nop 0
	s_nop 0
	v_lshl_add_u64 v[170:171], v[172:173], 1, s[34:35]
	v_lshl_add_u64 v[172:173], v[144:145], 0, s[22:23]
	v_lshl_add_u64 v[144:145], v[144:145], 0, s[24:25]
	s_waitcnt vmcnt(19)
	s_nop 1
	v_mov_b32_e32 v112, v178
	v_mov_b32_e32 v113, v179
	v_mov_b32_e32 v114, v180
	v_mov_b32_e32 v115, v181
	v_mov_b32_e32 v166, v182
	v_mov_b32_e32 v167, v183
	v_mov_b32_e32 v168, v184
	v_mov_b32_e32 v169, v185
	v_pk_add_f32 v[50:51], v[50:51], v[114:115]
	v_pk_add_f32 v[48:49], v[48:49], v[112:113]
	v_pk_add_f32 v[42:43], v[42:43], v[168:169]
	v_pk_add_f32 v[40:41], v[40:41], v[166:167]
	v_cvt_pk_bf16_f32 v112, v48, v49
	v_cvt_pk_bf16_f32 v113, v50, v51
	v_cvt_pk_bf16_f32 v115, v42, v43
	s_nop 0
	v_cvt_pk_bf16_f32 v114, v40, v41
	global_store_dwordx4 v[170:171], v[112:115], off
	s_nop 0
	s_nop 0
	s_nop 0
	v_lshl_add_u64 v[174:175], v[172:173], 2, s[30:31]
	s_waitcnt vmcnt(17)
	s_nop 1
	v_mov_b32_e32 v112, v186
	v_mov_b32_e32 v113, v187
	v_mov_b32_e32 v114, v188
	v_mov_b32_e32 v115, v189
	v_mov_b32_e32 v166, v190
	v_mov_b32_e32 v167, v191
	v_mov_b32_e32 v168, v192
	v_mov_b32_e32 v169, v193
	v_pk_add_f32 v[38:39], v[38:39], v[114:115]
	v_pk_add_f32 v[36:37], v[36:37], v[112:113]
	v_pk_add_f32 v[30:31], v[30:31], v[168:169]
	v_pk_add_f32 v[28:29], v[28:29], v[166:167]
	v_cvt_pk_bf16_f32 v112, v36, v37
	v_cvt_pk_bf16_f32 v113, v38, v39
	v_cvt_pk_bf16_f32 v115, v30, v31
	v_mul_f32_e32 v37, v37, v37
	v_cvt_pk_bf16_f32 v114, v28, v29
	global_store_dwordx4 v[170:171], v[112:115], off offset:256
	s_nop 0
	s_nop 0
	s_nop 0
	v_lshl_add_u64 v[170:171], v[172:173], 1, s[34:35]
	v_lshl_add_u64 v[172:173], v[144:145], 2, s[30:31]
	v_fmac_f32_e32 v37, v36, v36
	v_fmac_f32_e32 v37, v38, v38
	v_fmac_f32_e32 v37, v39, v39
	v_fmac_f32_e32 v37, v28, v28
	v_fmac_f32_e32 v37, v29, v29
	v_fmac_f32_e32 v37, v30, v30
	v_fmac_f32_e32 v37, v31, v31
	s_waitcnt vmcnt(15)
	s_nop 1
	v_mov_b32_e32 v112, v194
	v_mov_b32_e32 v113, v195
	v_mov_b32_e32 v114, v196
	v_mov_b32_e32 v115, v197
	v_mov_b32_e32 v166, v198
	v_mov_b32_e32 v167, v199
	v_mov_b32_e32 v168, v200
	v_mov_b32_e32 v169, v201
	v_pk_add_f32 v[34:35], v[34:35], v[114:115]
	v_pk_add_f32 v[32:33], v[32:33], v[112:113]
	v_pk_add_f32 v[26:27], v[26:27], v[168:169]
	v_pk_add_f32 v[24:25], v[24:25], v[166:167]
	v_cvt_pk_bf16_f32 v112, v32, v33
	v_cvt_pk_bf16_f32 v113, v34, v35
	v_cvt_pk_bf16_f32 v115, v26, v27
	v_mul_f32_e32 v29, v33, v33
	v_cvt_pk_bf16_f32 v114, v24, v25
	global_store_dwordx4 v[170:171], v[112:115], off
	s_nop 0
	s_nop 0
	s_nop 0
	v_fmac_f32_e32 v29, v32, v32
	v_fmac_f32_e32 v29, v34, v34
	v_fmac_f32_e32 v29, v35, v35
	v_fmac_f32_e32 v29, v24, v24
	v_fmac_f32_e32 v29, v25, v25
	v_fmac_f32_e32 v29, v26, v26
	v_fmac_f32_e32 v29, v27, v27
	s_waitcnt vmcnt(13)
	s_nop 1
	v_mov_b32_e32 v112, v202
	v_mov_b32_e32 v113, v203
	v_mov_b32_e32 v114, v204
	v_mov_b32_e32 v115, v205
	v_mov_b32_e32 v166, v206
	v_mov_b32_e32 v167, v207
	v_mov_b32_e32 v168, v208
	v_mov_b32_e32 v169, v209
	v_pk_add_f32 v[174:175], v[22:23], v[114:115]
	v_pk_add_f32 v[176:177], v[20:21], v[112:113]
	v_pk_add_f32 v[168:169], v[18:19], v[168:169]
	v_pk_add_f32 v[166:167], v[16:17], v[166:167]
	v_cvt_pk_bf16_f32 v16, v176, v177
	v_cvt_pk_bf16_f32 v17, v174, v175
	v_cvt_pk_bf16_f32 v19, v168, v169
	v_mul_f32_e32 v24, v177, v177
	v_cvt_pk_bf16_f32 v18, v166, v167
	global_store_dwordx4 v[170:171], v[16:19], off offset:256
	s_nop 0
	s_nop 0
	v_mul_f32_e32 v19, v101, v101
	v_fmac_f32_e32 v19, v100, v100
	v_fmac_f32_e32 v19, v102, v102
	v_fmac_f32_e32 v19, v103, v103
	v_fmac_f32_e32 v19, v92, v92
	v_fmac_f32_e32 v19, v93, v93
	v_lshl_add_u64 v[92:93], v[144:145], 1, s[34:35]
	v_fmac_f32_e32 v24, v176, v176
	v_fmac_f32_e32 v24, v174, v174
	v_fmac_f32_e32 v24, v175, v175
	v_fmac_f32_e32 v24, v166, v166
	v_fmac_f32_e32 v24, v167, v167
	v_fmac_f32_e32 v24, v168, v168
	v_fmac_f32_e32 v24, v169, v169
	v_add_f32_e32 v26, v29, v24
	v_mul_f32_e32 v16, v125, v125
	v_mul_f32_e32 v17, v149, v149
	v_mul_f32_e32 v18, v111, v111
	v_fmac_f32_e32 v19, v94, v94
	v_mul_f32_e32 v94, v97, v97
	v_fmac_f32_e32 v16, v124, v124
	v_fmac_f32_e32 v17, v148, v148
	v_fmac_f32_e32 v18, v110, v110
	v_fmac_f32_e32 v94, v96, v96
	v_fmac_f32_e32 v16, v126, v126
	v_fmac_f32_e32 v17, v118, v118
	v_fmac_f32_e32 v18, v108, v108
	v_fmac_f32_e32 v94, v98, v98
	v_fmac_f32_e32 v16, v127, v127
	v_fmac_f32_e32 v17, v119, v119
	v_fmac_f32_e32 v18, v109, v109
	v_fmac_f32_e32 v94, v99, v99
	v_fmac_f32_e32 v16, v120, v120
	v_fmac_f32_e32 v17, v146, v146
	v_fmac_f32_e32 v18, v104, v104
	v_fmac_f32_e32 v94, v88, v88
	v_fmac_f32_e32 v16, v121, v121
	v_fmac_f32_e32 v17, v147, v147
	v_fmac_f32_e32 v18, v105, v105
	v_fmac_f32_e32 v94, v89, v89
	v_fmac_f32_e32 v16, v122, v122
	v_fmac_f32_e32 v17, v116, v116
	v_fmac_f32_e32 v18, v106, v106
	v_fmac_f32_e32 v94, v90, v90
	v_fmac_f32_e32 v16, v123, v123
	v_fmac_f32_e32 v17, v117, v117
	v_fmac_f32_e32 v18, v107, v107
	v_fmac_f32_e32 v19, v95, v95
	v_fmac_f32_e32 v94, v91, v91
	v_add_f32_e32 v16, v16, v17
	v_add_f32_e32 v18, v18, v19
	v_add_f32_e32 v84, v94, v85
	ds_bpermute_b32 v17, v153, v16
	ds_bpermute_b32 v19, v153, v18
	ds_bpermute_b32 v85, v153, v84
	ds_bpermute_b32 v27, v153, v26
	s_waitcnt lgkmcnt(0)
	v_add_f32_e32 v16, v16, v17
	v_add_f32_e32 v18, v18, v19
	ds_bpermute_b32 v17, v154, v16
	ds_bpermute_b32 v19, v154, v18
	s_waitcnt vmcnt(11)
	s_nop 1
	v_mov_b32_e32 v20, v210
	v_mov_b32_e32 v21, v211
	v_mov_b32_e32 v22, v212
	v_mov_b32_e32 v23, v213
	v_mov_b32_e32 v112, v214
	v_mov_b32_e32 v113, v215
	v_mov_b32_e32 v114, v216
	v_mov_b32_e32 v115, v217
	v_pk_add_f32 v[14:15], v[14:15], v[22:23]
	v_pk_add_f32 v[72:73], v[12:13], v[20:21]
	s_waitcnt vmcnt(11)
	v_pk_add_f32 v[80:81], v[10:11], v[114:115]
	v_pk_add_f32 v[82:83], v[8:9], v[112:113]
	v_cvt_pk_bf16_f32 v8, v72, v73
	v_cvt_pk_bf16_f32 v9, v14, v15
	v_cvt_pk_bf16_f32 v11, v80, v81
	v_mul_f32_e32 v29, v73, v73
	v_cvt_pk_bf16_f32 v10, v82, v83
	global_store_dwordx4 v[92:93], v[8:11], off
	s_nop 0
	s_nop 0
	v_mul_f32_e32 v8, v69, v69
	v_fmac_f32_e32 v8, v68, v68
	v_fmac_f32_e32 v8, v70, v70
	v_fmac_f32_e32 v8, v71, v71
	v_fmac_f32_e32 v8, v64, v64
	v_fmac_f32_e32 v8, v65, v65
	v_fmac_f32_e32 v8, v66, v66
	v_fmac_f32_e32 v8, v67, v67
	v_add_f32_e32 v10, v86, v8
	v_mul_f32_e32 v8, v61, v61
	v_mul_f32_e32 v9, v53, v53
	v_fmac_f32_e32 v8, v60, v60
	v_fmac_f32_e32 v9, v52, v52
	v_fmac_f32_e32 v8, v62, v62
	v_fmac_f32_e32 v9, v54, v54
	v_fmac_f32_e32 v8, v63, v63
	v_fmac_f32_e32 v9, v55, v55
	v_fmac_f32_e32 v8, v56, v56
	v_fmac_f32_e32 v9, v44, v44
	v_fmac_f32_e32 v8, v57, v57
	v_fmac_f32_e32 v9, v45, v45
	v_fmac_f32_e32 v8, v58, v58
	v_fmac_f32_e32 v9, v46, v46
	v_fmac_f32_e32 v8, v59, v59
	v_fmac_f32_e32 v9, v47, v47
	v_add_f32_e32 v12, v8, v9
	ds_bpermute_b32 v13, v153, v12
	v_fmac_f32_e32 v29, v72, v72
	v_fmac_f32_e32 v29, v14, v14
	v_fmac_f32_e32 v29, v15, v15
	v_fmac_f32_e32 v29, v82, v82
	s_waitcnt lgkmcnt(0)
	v_add_f32_e32 v12, v12, v13
	v_mul_f32_e32 v13, v49, v49
	v_fmac_f32_e32 v13, v48, v48
	v_fmac_f32_e32 v13, v50, v50
	v_fmac_f32_e32 v13, v51, v51
	v_fmac_f32_e32 v13, v40, v40
	v_fmac_f32_e32 v13, v41, v41
	v_fmac_f32_e32 v29, v83, v83
	v_fmac_f32_e32 v13, v42, v42
	v_fmac_f32_e32 v29, v80, v80
	v_fmac_f32_e32 v13, v43, v43
	v_fmac_f32_e32 v29, v81, v81
	v_add_f32_e32 v13, v13, v37
	ds_bpermute_b32 v11, v153, v10
	ds_bpermute_b32 v28, v153, v13
	v_add_f32_e32 v8, v84, v85
	ds_bpermute_b32 v9, v154, v8
	s_waitcnt lgkmcnt(2)
	v_add_f32_e32 v10, v10, v11
	ds_bpermute_b32 v11, v154, v10
	s_waitcnt vmcnt(9)
	s_nop 1
	v_mov_b32_e32 v20, v218
	v_mov_b32_e32 v21, v219
	v_mov_b32_e32 v22, v220
	v_mov_b32_e32 v23, v221
	v_mov_b32_e32 v76, v222
	v_mov_b32_e32 v77, v223
	v_mov_b32_e32 v78, v224
	v_mov_b32_e32 v79, v225
	v_pk_add_f32 v[24:25], v[2:3], v[22:23]
	s_waitcnt vmcnt(9)
	v_pk_add_f32 v[4:5], v[4:5], v[76:77]
	v_pk_add_f32 v[22:23], v[0:1], v[20:21]
	v_mul_f32_e32 v0, v5, v5
	v_pk_add_f32 v[14:15], v[6:7], v[78:79]
	v_fmac_f32_e32 v0, v4, v4
	v_fmac_f32_e32 v0, v14, v14
	v_fmac_f32_e32 v0, v15, v15
	v_fmac_f32_e32 v0, v22, v22
	v_fmac_f32_e32 v0, v23, v23
	v_fmac_f32_e32 v0, v24, v24
	v_fmac_f32_e32 v0, v25, v25
	v_cvt_pk_bf16_f32 v20, v4, v5
	v_add_f32_e32 v5, v29, v0
	ds_bpermute_b32 v6, v153, v5
	s_waitcnt lgkmcnt(3)
	v_add_f32_e32 v1, v13, v28
	v_add_f32_e32 v3, v26, v27
	ds_bpermute_b32 v0, v154, v12
	ds_bpermute_b32 v2, v154, v1
	s_waitcnt lgkmcnt(2)
	v_add_f32_e32 v5, v5, v6
	ds_bpermute_b32 v4, v154, v3
	ds_bpermute_b32 v6, v154, v5
	v_cvt_pk_bf16_f32 v21, v14, v15
	v_cvt_pk_bf16_f32 v22, v22, v23
	v_cvt_pk_bf16_f32 v23, v24, v25
	global_store_dwordx4 v[92:93], v[20:23], off offset:256
	s_and_saveexec_b64 s[30:31], s[0:1]
	s_cbranch_execz .LBB0_335
	s_waitcnt lgkmcnt(0)
	v_add_f32_e32 v5, v5, v6
	v_add_f32_e32 v3, v3, v4
	v_add_f32_e32 v1, v1, v2
	v_add_f32_e32 v2, v10, v11
	v_add_f32_e32 v4, v8, v9
	v_add_f32_e32 v6, v18, v19
	v_add_f32_e32 v7, v16, v17
	v_add_u32_e32 v8, s53, v155
	v_add_f32_e32 v0, v12, v0
	ds_write2st64_b32 v8, v7, v6 offset1:1
	ds_write2st64_b32 v8, v4, v2 offset0:2 offset1:3
	v_add_u32_e32 v2, s53, v159
	ds_write2st64_b32 v2, v0, v1 offset1:1
	ds_write2st64_b32 v2, v3, v5 offset0:2 offset1:3

.LBB0_404:
	ds_read_b128 v[128:131], v181
	ds_read_b128 v[132:135], v181 offset:1024
	ds_read_b128 v[136:139], v181 offset:2048
	ds_read_b128 v[140:143], v181 offset:3072
	s_add_u32 s30, s28, 0xfffc0080
	s_addc_u32 s31, s29, -1
	s_cmp_eq_u32 s66, 12
	s_cselect_b32 s35, s25, s31
	s_cselect_b32 s34, s24, s30
	s_cselect_b32 s31, s27, s65
	s_cselect_b32 s30, s26, s64
	v_lshl_add_u64 v[166:167], s[28:29], 0, v[152:153]
	s_add_i32 m0, s41, 0xc000
	ds_read_b128 v[158:161], v182
	ds_read_b128 v[162:165], v182 offset:1024
	ds_read_b128 v[184:187], v182 offset:2048
	ds_read_b128 v[188:191], v182 offset:3072
	ds_read_b128 v[192:195], v182 offset:4096
	ds_read_b128 v[196:199], v182 offset:5120
	ds_read_b128 v[200:203], v182 offset:6144
	ds_read_b128 v[204:207], v182 offset:7168
	global_load_lds_dwordx4 v[166:167], off
	v_lshl_add_u64 v[166:167], s[28:29], 0, v[154:155]
	s_add_i32 m0, s41, 0xe000
	s_nop 0
	global_load_lds_dwordx4 v[166:167], off
	s_waitcnt lgkmcnt(8)
	s_barrier
	s_waitcnt lgkmcnt(0)
	s_setprio 1
	s_waitcnt lgkmcnt(0)
	v_mfma_f32_16x16x32_bf16 v[124:127], v[128:131], v[158:161], v[124:127]
	v_mfma_f32_16x16x32_bf16 v[120:123], v[136:139], v[158:161], v[120:123]
	v_mfma_f32_16x16x32_bf16 v[116:119], v[128:131], v[184:187], v[116:119]
	v_mfma_f32_16x16x32_bf16 v[108:111], v[136:139], v[184:187], v[108:111]
	v_mfma_f32_16x16x32_bf16 v[92:95], v[128:131], v[192:195], v[92:95]
	v_mfma_f32_16x16x32_bf16 v[88:91], v[136:139], v[192:195], v[88:91]
	v_mfma_f32_16x16x32_bf16 v[76:79], v[128:131], v[200:203], v[76:79]
	v_mfma_f32_16x16x32_bf16 v[72:75], v[136:139], v[200:203], v[72:75]
	v_mfma_f32_16x16x32_bf16 v[124:127], v[132:135], v[162:165], v[124:127]
	v_mfma_f32_16x16x32_bf16 v[120:123], v[140:143], v[162:165], v[120:123]
	v_mfma_f32_16x16x32_bf16 v[116:119], v[132:135], v[188:191], v[116:119]
	v_mfma_f32_16x16x32_bf16 v[108:111], v[140:143], v[188:191], v[108:111]
	v_mfma_f32_16x16x32_bf16 v[92:95], v[132:135], v[196:199], v[92:95]
	v_mfma_f32_16x16x32_bf16 v[88:91], v[140:143], v[196:199], v[88:91]
	v_mfma_f32_16x16x32_bf16 v[76:79], v[132:135], v[204:207], v[76:79]
	v_mfma_f32_16x16x32_bf16 v[72:75], v[140:143], v[204:207], v[72:75]
	s_setprio 0
	s_barrier
	s_add_i32 s67, s56, s40
	v_lshl_add_u64 v[166:167], s[30:31], 0, v[146:147]
	s_mov_b32 m0, s67
	ds_read_b128 v[208:211], v183
	ds_read_b128 v[212:215], v183 offset:1024
	ds_read_b128 v[216:219], v183 offset:2048
	ds_read_b128 v[220:223], v183 offset:3072
	global_load_lds_dwordx4 v[166:167], off
	v_lshl_add_u64 v[224:225], s[30:31], 0, v[150:151]
	s_add_i32 m0, s67, 0x2000
	s_nop 0
	global_load_lds_dwordx4 v[224:225], off
	s_barrier
	s_waitcnt lgkmcnt(0)
	s_setprio 1
	s_waitcnt lgkmcnt(0)
	v_mfma_f32_16x16x32_bf16 v[112:115], v[208:211], v[158:161], v[112:115]
	v_mfma_f32_16x16x32_bf16 v[104:107], v[216:219], v[158:161], v[104:107]
	v_mfma_f32_16x16x32_bf16 v[100:103], v[208:211], v[184:187], v[100:103]
	v_mfma_f32_16x16x32_bf16 v[96:99], v[216:219], v[184:187], v[96:99]
	v_mfma_f32_16x16x32_bf16 v[84:87], v[208:211], v[192:195], v[84:87]
	v_mfma_f32_16x16x32_bf16 v[80:83], v[216:219], v[192:195], v[80:83]
	v_mfma_f32_16x16x32_bf16 v[68:71], v[208:211], v[200:203], v[68:71]
	v_mfma_f32_16x16x32_bf16 v[64:67], v[216:219], v[200:203], v[64:67]
	v_mfma_f32_16x16x32_bf16 v[112:115], v[212:215], v[162:165], v[112:115]
	v_mfma_f32_16x16x32_bf16 v[104:107], v[220:223], v[162:165], v[104:107]
	v_mfma_f32_16x16x32_bf16 v[100:103], v[212:215], v[188:191], v[100:103]
	v_mfma_f32_16x16x32_bf16 v[96:99], v[220:223], v[188:191], v[96:99]
	v_mfma_f32_16x16x32_bf16 v[84:87], v[212:215], v[196:199], v[84:87]
	v_mfma_f32_16x16x32_bf16 v[80:83], v[220:223], v[196:199], v[80:83]
	v_mfma_f32_16x16x32_bf16 v[68:71], v[212:215], v[204:207], v[68:71]
	v_mfma_f32_16x16x32_bf16 v[64:67], v[220:223], v[204:207], v[64:67]
	s_setprio 0
	s_mov_b32 m0, s41
	v_lshl_add_u64 v[226:227], s[34:35], 0, v[144:145]
	s_barrier
	ds_read_b128 v[158:161], v182 offset:16384
	ds_read_b128 v[162:165], v182 offset:17408
	ds_read_b128 v[184:187], v182 offset:18432
	ds_read_b128 v[188:191], v182 offset:19456
	ds_read_b128 v[192:195], v182 offset:20480
	ds_read_b128 v[196:199], v182 offset:21504
	ds_read_b128 v[200:203], v182 offset:22528
	ds_read_b128 v[204:207], v182 offset:23552
	global_load_lds_dwordx4 v[226:227], off
	v_lshl_add_u64 v[228:229], s[34:35], 0, v[148:149]
	s_mov_b32 m0, s42
	s_nop 0
	global_load_lds_dwordx4 v[228:229], off
	s_barrier
	s_waitcnt lgkmcnt(0)
	s_setprio 1
	s_waitcnt lgkmcnt(0)
	v_mfma_f32_16x16x32_bf16 v[60:63], v[128:131], v[158:161], v[60:63]
	v_mfma_f32_16x16x32_bf16 v[56:59], v[136:139], v[158:161], v[56:59]
	v_mfma_f32_16x16x32_bf16 v[44:47], v[128:131], v[184:187], v[44:47]
	v_mfma_f32_16x16x32_bf16 v[40:43], v[136:139], v[184:187], v[40:43]
	v_mfma_f32_16x16x32_bf16 v[28:31], v[128:131], v[192:195], v[28:31]
	v_mfma_f32_16x16x32_bf16 v[24:27], v[136:139], v[192:195], v[24:27]
	v_mfma_f32_16x16x32_bf16 v[16:19], v[128:131], v[200:203], v[16:19]
	v_mfma_f32_16x16x32_bf16 v[8:11], v[136:139], v[200:203], v[8:11]
	v_mfma_f32_16x16x32_bf16 v[60:63], v[132:135], v[162:165], v[60:63]
	v_mfma_f32_16x16x32_bf16 v[56:59], v[140:143], v[162:165], v[56:59]
	v_mfma_f32_16x16x32_bf16 v[44:47], v[132:135], v[188:191], v[44:47]
	v_mfma_f32_16x16x32_bf16 v[40:43], v[140:143], v[188:191], v[40:43]
	v_mfma_f32_16x16x32_bf16 v[28:31], v[132:135], v[196:199], v[28:31]
	v_mfma_f32_16x16x32_bf16 v[24:27], v[140:143], v[196:199], v[24:27]
	v_mfma_f32_16x16x32_bf16 v[16:19], v[132:135], v[204:207], v[16:19]
	v_mfma_f32_16x16x32_bf16 v[8:11], v[140:143], v[204:207], v[8:11]
	s_setprio 0
	s_barrier
	s_add_u32 s68, s30, 0x40000
	s_addc_u32 s69, s31, 0
	s_add_i32 s67, s57, s40
	v_lshl_add_u64 v[128:129], s[68:69], 0, v[146:147]
	s_mov_b32 m0, s67
	s_nop 0
	global_load_lds_dwordx4 v[128:129], off
	v_lshl_add_u64 v[128:129], s[68:69], 0, v[150:151]
	s_add_i32 m0, s67, 0x2000
	s_nop 0
	global_load_lds_dwordx4 v[128:129], off
	s_waitcnt vmcnt(6)
	s_barrier
	s_setprio 1
	v_mfma_f32_16x16x32_bf16 v[52:55], v[208:211], v[158:161], v[52:55]
	v_mfma_f32_16x16x32_bf16 v[48:51], v[216:219], v[158:161], v[48:51]
	v_mfma_f32_16x16x32_bf16 v[36:39], v[208:211], v[184:187], v[36:39]
	v_mfma_f32_16x16x32_bf16 v[32:35], v[216:219], v[184:187], v[32:35]
	v_mfma_f32_16x16x32_bf16 v[20:23], v[208:211], v[192:195], v[20:23]
	v_mfma_f32_16x16x32_bf16 v[12:15], v[216:219], v[192:195], v[12:15]
	v_mfma_f32_16x16x32_bf16 v[4:7], v[208:211], v[200:203], v[4:7]
	v_mfma_f32_16x16x32_bf16 v[0:3], v[216:219], v[200:203], v[0:3]
	v_mfma_f32_16x16x32_bf16 v[52:55], v[212:215], v[162:165], v[52:55]
	v_mfma_f32_16x16x32_bf16 v[48:51], v[220:223], v[162:165], v[48:51]
	v_mfma_f32_16x16x32_bf16 v[36:39], v[212:215], v[188:191], v[36:39]
	v_mfma_f32_16x16x32_bf16 v[32:35], v[220:223], v[188:191], v[32:35]
	v_mfma_f32_16x16x32_bf16 v[20:23], v[212:215], v[196:199], v[20:23]
	v_mfma_f32_16x16x32_bf16 v[12:15], v[220:223], v[196:199], v[12:15]
	v_mfma_f32_16x16x32_bf16 v[4:7], v[212:215], v[204:207], v[4:7]
	v_mfma_f32_16x16x32_bf16 v[0:3], v[220:223], v[204:207], v[0:3]
	s_setprio 0
	s_add_i32 s67, 0, 0x18000
	v_add_u32_e32 v140, s67, v169
	s_barrier
	ds_read_b128 v[128:131], v140
	ds_read_b128 v[132:135], v140 offset:1024
	ds_read_b128 v[136:139], v140 offset:2048
	ds_read_b128 v[140:143], v140 offset:3072
	s_add_u32 s34, s34, 0x40000
	s_addc_u32 s35, s35, 0
	s_mov_b32 m0, s43
	v_lshl_add_u64 v[208:209], s[34:35], 0, v[144:145]
	ds_read_b128 v[158:161], v182 offset:32768
	ds_read_b128 v[162:165], v182 offset:33792
	ds_read_b128 v[184:187], v182 offset:34816
	ds_read_b128 v[188:191], v182 offset:35840
	ds_read_b128 v[192:195], v182 offset:36864
	ds_read_b128 v[196:199], v182 offset:37888
	ds_read_b128 v[200:203], v182 offset:38912
	ds_read_b128 v[204:207], v182 offset:39936
	global_load_lds_dwordx4 v[208:209], off
	v_lshl_add_u64 v[208:209], s[34:35], 0, v[148:149]
	s_mov_b32 m0, s44
	s_nop 0
	global_load_lds_dwordx4 v[208:209], off
	s_waitcnt lgkmcnt(8)
	s_barrier
	s_waitcnt lgkmcnt(0)
	s_setprio 1
	s_waitcnt lgkmcnt(0)
	v_mfma_f32_16x16x32_bf16 v[124:127], v[128:131], v[158:161], v[124:127]
	v_mfma_f32_16x16x32_bf16 v[120:123], v[136:139], v[158:161], v[120:123]
	v_mfma_f32_16x16x32_bf16 v[116:119], v[128:131], v[184:187], v[116:119]
	v_mfma_f32_16x16x32_bf16 v[108:111], v[136:139], v[184:187], v[108:111]
	v_mfma_f32_16x16x32_bf16 v[92:95], v[128:131], v[192:195], v[92:95]
	v_mfma_f32_16x16x32_bf16 v[88:91], v[136:139], v[192:195], v[88:91]
	v_mfma_f32_16x16x32_bf16 v[76:79], v[128:131], v[200:203], v[76:79]
	v_mfma_f32_16x16x32_bf16 v[72:75], v[136:139], v[200:203], v[72:75]
	v_mfma_f32_16x16x32_bf16 v[124:127], v[132:135], v[162:165], v[124:127]
	v_mfma_f32_16x16x32_bf16 v[120:123], v[140:143], v[162:165], v[120:123]
	v_mfma_f32_16x16x32_bf16 v[116:119], v[132:135], v[188:191], v[116:119]
	v_mfma_f32_16x16x32_bf16 v[108:111], v[140:143], v[188:191], v[108:111]
	v_mfma_f32_16x16x32_bf16 v[92:95], v[132:135], v[196:199], v[92:95]
	v_mfma_f32_16x16x32_bf16 v[88:91], v[140:143], v[196:199], v[88:91]
	v_mfma_f32_16x16x32_bf16 v[76:79], v[132:135], v[204:207], v[76:79]
	v_mfma_f32_16x16x32_bf16 v[72:75], v[140:143], v[204:207], v[72:75]
	s_setprio 0
	s_barrier
	s_add_i32 s34, 0, 0x1c000
	s_add_i32 s35, s67, s40
	v_add_u32_e32 v220, s34, v169
	v_lshl_add_u64 v[166:167], v[166:167], 0, s[10:11]
	s_mov_b32 m0, s35
	ds_read_b128 v[208:211], v220
	ds_read_b128 v[212:215], v220 offset:1024
	ds_read_b128 v[216:219], v220 offset:2048
	ds_read_b128 v[220:223], v220 offset:3072
	global_load_lds_dwordx4 v[166:167], off
	v_lshl_add_u64 v[166:167], v[224:225], 0, s[10:11]
	s_add_i32 m0, s35, 0x2000
	s_nop 0
	global_load_lds_dwordx4 v[166:167], off
	s_barrier
	s_waitcnt lgkmcnt(0)
	s_setprio 1
	s_waitcnt lgkmcnt(0)
	v_mfma_f32_16x16x32_bf16 v[112:115], v[208:211], v[158:161], v[112:115]
	v_mfma_f32_16x16x32_bf16 v[104:107], v[216:219], v[158:161], v[104:107]
	v_mfma_f32_16x16x32_bf16 v[100:103], v[208:211], v[184:187], v[100:103]
	v_mfma_f32_16x16x32_bf16 v[96:99], v[216:219], v[184:187], v[96:99]
	v_mfma_f32_16x16x32_bf16 v[84:87], v[208:211], v[192:195], v[84:87]
	v_mfma_f32_16x16x32_bf16 v[80:83], v[216:219], v[192:195], v[80:83]
	v_mfma_f32_16x16x32_bf16 v[68:71], v[208:211], v[200:203], v[68:71]
	v_mfma_f32_16x16x32_bf16 v[64:67], v[216:219], v[200:203], v[64:67]
	v_mfma_f32_16x16x32_bf16 v[112:115], v[212:215], v[162:165], v[112:115]
	v_mfma_f32_16x16x32_bf16 v[104:107], v[220:223], v[162:165], v[104:107]
	v_mfma_f32_16x16x32_bf16 v[100:103], v[212:215], v[188:191], v[100:103]
	v_mfma_f32_16x16x32_bf16 v[96:99], v[220:223], v[188:191], v[96:99]
	v_mfma_f32_16x16x32_bf16 v[84:87], v[212:215], v[196:199], v[84:87]
	v_mfma_f32_16x16x32_bf16 v[80:83], v[220:223], v[196:199], v[80:83]
	v_mfma_f32_16x16x32_bf16 v[68:71], v[212:215], v[204:207], v[68:71]
	v_mfma_f32_16x16x32_bf16 v[64:67], v[220:223], v[204:207], v[64:67]
	s_setprio 0
	s_mov_b32 m0, s50
	v_lshl_add_u64 v[166:167], v[226:227], 0, s[10:11]
	s_barrier
	ds_read_b128 v[158:161], v182 offset:49152
	ds_read_b128 v[162:165], v182 offset:50176
	ds_read_b128 v[184:187], v182 offset:51200
	ds_read_b128 v[188:191], v182 offset:52224
	ds_read_b128 v[192:195], v182 offset:53248
	ds_read_b128 v[196:199], v182 offset:54272
	ds_read_b128 v[200:203], v182 offset:55296
	ds_read_b128 v[204:207], v182 offset:56320
	global_load_lds_dwordx4 v[166:167], off
	v_lshl_add_u64 v[166:167], v[228:229], 0, s[10:11]
	s_mov_b32 m0, s51
	s_nop 0
	global_load_lds_dwordx4 v[166:167], off
	s_barrier
	s_waitcnt lgkmcnt(0)
	s_setprio 1
	s_waitcnt lgkmcnt(0)
	v_mfma_f32_16x16x32_bf16 v[60:63], v[128:131], v[158:161], v[60:63]
	v_mfma_f32_16x16x32_bf16 v[56:59], v[136:139], v[158:161], v[56:59]
	v_mfma_f32_16x16x32_bf16 v[44:47], v[128:131], v[184:187], v[44:47]
	v_mfma_f32_16x16x32_bf16 v[40:43], v[136:139], v[184:187], v[40:43]
	v_mfma_f32_16x16x32_bf16 v[28:31], v[128:131], v[192:195], v[28:31]
	v_mfma_f32_16x16x32_bf16 v[24:27], v[136:139], v[192:195], v[24:27]
	v_mfma_f32_16x16x32_bf16 v[16:19], v[128:131], v[200:203], v[16:19]
	v_mfma_f32_16x16x32_bf16 v[8:11], v[136:139], v[200:203], v[8:11]
	v_mfma_f32_16x16x32_bf16 v[60:63], v[132:135], v[162:165], v[60:63]
	v_mfma_f32_16x16x32_bf16 v[56:59], v[140:143], v[162:165], v[56:59]
	v_mfma_f32_16x16x32_bf16 v[44:47], v[132:135], v[188:191], v[44:47]
	v_mfma_f32_16x16x32_bf16 v[40:43], v[140:143], v[188:191], v[40:43]
	v_mfma_f32_16x16x32_bf16 v[28:31], v[132:135], v[196:199], v[28:31]
	v_mfma_f32_16x16x32_bf16 v[24:27], v[140:143], v[196:199], v[24:27]
	v_mfma_f32_16x16x32_bf16 v[16:19], v[132:135], v[204:207], v[16:19]
	v_mfma_f32_16x16x32_bf16 v[8:11], v[140:143], v[204:207], v[8:11]
	s_setprio 0
	s_barrier
	s_add_u32 s30, s30, 0x40080
	s_addc_u32 s31, s31, 0
	s_add_i32 s34, s34, s40
	v_lshl_add_u64 v[128:129], s[30:31], 0, v[146:147]
	s_mov_b32 m0, s34
	s_nop 0
	global_load_lds_dwordx4 v[128:129], off
	v_lshl_add_u64 v[128:129], s[30:31], 0, v[150:151]
	s_add_i32 m0, s34, 0x2000
	s_nop 0
	global_load_lds_dwordx4 v[128:129], off
	s_waitcnt vmcnt(6)
	s_barrier
	s_setprio 1
	v_mfma_f32_16x16x32_bf16 v[52:55], v[208:211], v[158:161], v[52:55]
	v_mfma_f32_16x16x32_bf16 v[48:51], v[216:219], v[158:161], v[48:51]
	v_mfma_f32_16x16x32_bf16 v[36:39], v[208:211], v[184:187], v[36:39]
	v_mfma_f32_16x16x32_bf16 v[32:35], v[216:219], v[184:187], v[32:35]
	v_mfma_f32_16x16x32_bf16 v[20:23], v[208:211], v[192:195], v[20:23]
	v_mfma_f32_16x16x32_bf16 v[12:15], v[216:219], v[192:195], v[12:15]
	v_mfma_f32_16x16x32_bf16 v[4:7], v[208:211], v[200:203], v[4:7]
	v_mfma_f32_16x16x32_bf16 v[0:3], v[216:219], v[200:203], v[0:3]
	v_mfma_f32_16x16x32_bf16 v[52:55], v[212:215], v[162:165], v[52:55]
	v_mfma_f32_16x16x32_bf16 v[48:51], v[220:223], v[162:165], v[48:51]
	v_mfma_f32_16x16x32_bf16 v[36:39], v[212:215], v[188:191], v[36:39]
	v_mfma_f32_16x16x32_bf16 v[32:35], v[220:223], v[188:191], v[32:35]
	v_mfma_f32_16x16x32_bf16 v[20:23], v[212:215], v[196:199], v[20:23]
	v_mfma_f32_16x16x32_bf16 v[12:15], v[220:223], v[196:199], v[12:15]
	v_mfma_f32_16x16x32_bf16 v[4:7], v[212:215], v[204:207], v[4:7]
	v_mfma_f32_16x16x32_bf16 v[0:3], v[220:223], v[204:207], v[0:3]
	s_setprio 0
	s_add_i32 s66, s66, 2
	s_add_u32 s28, s28, 0x100
	s_addc_u32 s29, s29, 0
	s_add_u32 s64, s64, 0x100
	s_addc_u32 s65, s65, 0
	s_cmp_gt_u32 s66, 13
	s_barrier
	s_cbranch_scc0 .LBB0_404
	v_add_u32_e32 v158, s33, v168
	v_ashrrev_i32_e32 v159, 31, v158
	v_readlane_b32 s28, v254, 56
	v_add_u32_e32 v128, s49, v170
	v_lshlrev_b64 v[130:131], 11, v[158:159]
	v_readlane_b32 s29, v254, 57
	v_ashrrev_i32_e32 v129, 31, v128
	s_nop 0
	v_lshl_add_u64 v[130:131], s[28:29], 0, v[130:131]
	v_lshl_add_u64 v[160:161], v[128:129], 1, v[130:131]
	v_add_co_u32_e32 v192, vcc, s53, v160
	global_load_dwordx4 v[132:135], v[160:161], off
	global_load_dwordx4 v[140:143], v[160:161], off offset:256
	v_addc_co_u32_e32 v193, vcc, 0, v161, vcc
	global_load_dwordx4 v[184:187], v[192:193], off
	v_lshl_add_u64 v[164:165], v[160:161], 0, s[12:13]
	global_load_dwordx4 v[188:191], v[164:165], off offset:256
	v_add_co_u32_e32 v166, vcc, s46, v160
	v_lshl_add_u64 v[162:163], v[160:161], 0, s[14:15]
	s_nop 0
	v_addc_co_u32_e32 v167, vcc, 0, v161, vcc
	global_load_dwordx4 v[136:139], v[166:167], off
	global_load_dwordx4 v[128:131], v[162:163], off offset:256
	s_mov_b32 s98, s52
	s_mov_b32 s99, 0
	v_lshl_add_u64 v[250:251], v[160:161], 0, s[98:99]
	global_load_dwordx4 v[202:205], v[250:251], off
	v_lshl_add_u64 v[250:251], v[160:161], 0, s[16:17]
	global_load_dwordx4 v[206:209], v[250:251], off offset:256
	s_mov_b32 s98, s58
	s_mov_b32 s99, 0
	v_lshl_add_u64 v[250:251], v[160:161], 0, s[98:99]
	global_load_dwordx4 v[210:213], v[250:251], off
	v_lshl_add_u64 v[250:251], v[160:161], 0, s[8:9]
	global_load_dwordx4 v[214:217], v[250:251], off offset:256
	s_mov_b32 s98, s59
	s_mov_b32 s99, 0
	v_lshl_add_u64 v[250:251], v[160:161], 0, s[98:99]
	global_load_dwordx4 v[218:221], v[250:251], off
	v_lshl_add_u64 v[250:251], v[160:161], 0, s[18:19]
	global_load_dwordx4 v[222:225], v[250:251], off offset:256
	s_mov_b32 s98, s60
	s_mov_b32 s99, 0
	v_lshl_add_u64 v[250:251], v[160:161], 0, s[98:99]
	global_load_dwordx4 v[226:229], v[250:251], off
	v_lshl_add_u64 v[250:251], v[160:161], 0, s[20:21]
	global_load_dwordx4 v[230:233], v[250:251], off offset:256
	s_mov_b32 s98, s61
	s_mov_b32 s99, 0
	v_lshl_add_u64 v[250:251], v[160:161], 0, s[98:99]
	global_load_dwordx4 v[234:237], v[250:251], off
	v_lshl_add_u64 v[250:251], v[160:161], 0, s[22:23]
	global_load_dwordx4 v[238:241], v[250:251], off offset:256
	s_waitcnt vmcnt(10)
	v_lshlrev_b32_e32 v194, 16, v132
	v_and_b32_e32 v195, 0xffff0000, v132
	v_lshlrev_b32_e32 v196, 16, v134
	v_and_b32_e32 v197, 0xffff0000, v134
	v_pk_add_f32 v[124:125], v[124:125], v[194:195]
	v_lshlrev_b32_e32 v194, 16, v184
	v_and_b32_e32 v195, 0xffff0000, v184
	v_pk_add_f32 v[120:121], v[120:121], v[196:197]
	v_lshlrev_b32_e32 v184, 16, v185
	v_and_b32_e32 v185, 0xffff0000, v185
	v_lshlrev_b32_e32 v196, 16, v186
	v_and_b32_e32 v197, 0xffff0000, v186
	v_lshlrev_b32_e32 v186, 16, v187
	v_and_b32_e32 v187, 0xffff0000, v187
	v_pk_add_f32 v[116:117], v[116:117], v[194:195]
	v_pk_add_f32 v[118:119], v[118:119], v[184:185]
	v_pk_add_f32 v[184:185], v[110:111], v[186:187]
	v_mul_f32_e32 v111, v117, v117
	v_fmac_f32_e32 v111, v116, v116
	v_lshlrev_b32_e32 v132, 16, v133
	v_and_b32_e32 v133, 0xffff0000, v133
	v_lshlrev_b32_e32 v198, 16, v140
	v_and_b32_e32 v199, 0xffff0000, v140
	v_lshlrev_b32_e32 v140, 16, v141
	v_and_b32_e32 v141, 0xffff0000, v141
	v_lshlrev_b32_e32 v200, 16, v142
	v_and_b32_e32 v201, 0xffff0000, v142
	v_lshlrev_b32_e32 v142, 16, v143
	v_and_b32_e32 v143, 0xffff0000, v143
	v_fmac_f32_e32 v111, v118, v118
	v_lshlrev_b32_e32 v134, 16, v135
	v_and_b32_e32 v135, 0xffff0000, v135
	v_pk_add_f32 v[126:127], v[126:127], v[132:133]
	v_pk_add_f32 v[132:133], v[114:115], v[140:141]
	v_pk_add_f32 v[140:141], v[106:107], v[142:143]
	v_cvt_pk_bf16_f32 v106, v120, v121
	v_pk_add_f32 v[108:109], v[108:109], v[196:197]
	v_fmac_f32_e32 v111, v119, v119
	v_pk_add_f32 v[122:123], v[122:123], v[134:135]
	v_pk_add_f32 v[134:135], v[112:113], v[198:199]
	v_pk_add_f32 v[142:143], v[104:105], v[200:201]
	v_cvt_pk_bf16_f32 v104, v124, v125
	v_cvt_pk_bf16_f32 v105, v126, v127
	v_cvt_pk_bf16_f32 v107, v122, v123
	v_cvt_pk_bf16_f32 v112, v134, v135
	v_cvt_pk_bf16_f32 v113, v132, v133
	s_nop 0
	v_cvt_pk_bf16_f32 v114, v142, v143
	v_cvt_pk_bf16_f32 v115, v140, v141
	global_store_dwordx4 v[160:161], v[104:107], off
	v_fmac_f32_e32 v111, v108, v108
	global_store_dwordx4 v[160:161], v[112:115], off offset:256
	v_cvt_pk_bf16_f32 v106, v108, v109
	v_add_co_u32_e32 v108, vcc, s52, v160
	v_cvt_pk_bf16_f32 v104, v116, v117
	v_cvt_pk_bf16_f32 v105, v118, v119
	v_cvt_pk_bf16_f32 v107, v184, v185
	v_fmac_f32_e32 v111, v109, v109
	v_lshlrev_b32_e32 v112, 16, v188
	v_and_b32_e32 v113, 0xffff0000, v188
	v_lshlrev_b32_e32 v114, 16, v189
	v_and_b32_e32 v115, 0xffff0000, v189
	v_lshlrev_b32_e32 v116, 16, v190
	v_addc_co_u32_e32 v109, vcc, 0, v161, vcc
	v_and_b32_e32 v117, 0xffff0000, v190
	global_store_dwordx4 v[192:193], v[104:107], off
	s_nop 0
	v_lshlrev_b32_e32 v118, 16, v191
	v_and_b32_e32 v119, 0xffff0000, v191
	v_pk_add_f32 v[102:103], v[102:103], v[114:115]
	v_pk_add_f32 v[100:101], v[100:101], v[112:113]
	v_pk_add_f32 v[114:115], v[96:97], v[116:117]
	v_cvt_pk_bf16_f32 v96, v100, v101
	v_pk_add_f32 v[112:113], v[98:99], v[118:119]
	v_cvt_pk_bf16_f32 v97, v102, v103
	v_cvt_pk_bf16_f32 v98, v114, v115
	v_fmac_f32_e32 v111, v184, v184
	v_cvt_pk_bf16_f32 v99, v112, v113
	global_store_dwordx4 v[164:165], v[96:99], off offset:256
	v_fmac_f32_e32 v111, v185, v185
	v_lshlrev_b32_e32 v116, 16, v138
	v_mul_f32_e32 v96, v101, v101
	v_fmac_f32_e32 v96, v100, v100
	v_fmac_f32_e32 v96, v102, v102
	v_fmac_f32_e32 v96, v103, v103
	v_fmac_f32_e32 v96, v114, v114
	v_fmac_f32_e32 v96, v115, v115
	v_fmac_f32_e32 v96, v112, v112
	v_fmac_f32_e32 v96, v113, v113
	v_lshl_add_u64 v[100:101], v[160:161], 0, s[16:17]
	v_add_f32_e32 v102, v111, v96
	s_nop 0
	v_lshlrev_b32_e32 v112, 16, v136
	v_and_b32_e32 v113, 0xffff0000, v136
	v_lshlrev_b32_e32 v114, 16, v137
	v_and_b32_e32 v115, 0xffff0000, v137
	v_and_b32_e32 v117, 0xffff0000, v138
	v_lshlrev_b32_e32 v118, 16, v139
	v_and_b32_e32 v119, 0xffff0000, v139
	v_pk_add_f32 v[94:95], v[94:95], v[114:115]
	v_pk_add_f32 v[92:93], v[92:93], v[112:113]
	v_pk_add_f32 v[114:115], v[88:89], v[116:117]
	v_cvt_pk_bf16_f32 v88, v92, v93
	v_pk_add_f32 v[112:113], v[90:91], v[118:119]
	v_cvt_pk_bf16_f32 v89, v94, v95
	v_cvt_pk_bf16_f32 v90, v114, v115
	v_mul_f32_e32 v103, v93, v93
	v_cvt_pk_bf16_f32 v91, v112, v113
	global_store_dwordx4 v[166:167], v[88:91], off
	v_fmac_f32_e32 v103, v92, v92
	v_fmac_f32_e32 v103, v94, v94
	v_add_co_u32_e32 v88, vcc, s58, v160
	v_fmac_f32_e32 v103, v95, v95
	s_nop 0
	v_addc_co_u32_e32 v89, vcc, 0, v161, vcc
	s_nop 0
	v_fmac_f32_e32 v103, v114, v114
	v_fmac_f32_e32 v103, v115, v115
	v_fmac_f32_e32 v103, v112, v112
	v_fmac_f32_e32 v103, v113, v113
	v_lshlrev_b32_e32 v94, 16, v128
	v_and_b32_e32 v95, 0xffff0000, v128
	v_lshlrev_b32_e32 v112, 16, v129
	v_and_b32_e32 v113, 0xffff0000, v129
	v_lshlrev_b32_e32 v114, 16, v130
	v_and_b32_e32 v115, 0xffff0000, v130
	v_lshlrev_b32_e32 v116, 16, v131
	v_and_b32_e32 v117, 0xffff0000, v131
	v_pk_add_f32 v[86:87], v[86:87], v[112:113]
	v_pk_add_f32 v[84:85], v[84:85], v[94:95]
	v_pk_add_f32 v[112:113], v[80:81], v[114:115]
	v_cvt_pk_bf16_f32 v80, v84, v85
	v_pk_add_f32 v[94:95], v[82:83], v[116:117]
	v_cvt_pk_bf16_f32 v81, v86, v87
	v_cvt_pk_bf16_f32 v82, v112, v113
	v_mul_f32_e32 v125, v125, v125
	v_cvt_pk_bf16_f32 v83, v94, v95
	global_store_dwordx4 v[162:163], v[80:83], off offset:256
	v_mul_f32_e32 v135, v135, v135
	v_fmac_f32_e32 v125, v124, v124
	v_mul_f32_e32 v80, v85, v85
	v_fmac_f32_e32 v80, v84, v84
	v_fmac_f32_e32 v80, v86, v86
	v_fmac_f32_e32 v80, v87, v87
	v_fmac_f32_e32 v80, v112, v112
	v_fmac_f32_e32 v80, v113, v113
	v_fmac_f32_e32 v80, v94, v94
	v_fmac_f32_e32 v80, v95, v95
	v_lshl_add_u64 v[84:85], v[160:161], 0, s[8:9]
	v_add_f32_e32 v86, v103, v80
	s_nop 0
	s_waitcnt vmcnt(12)
	s_nop 1
	v_mov_b32_e32 v104, v202
	v_mov_b32_e32 v105, v203
	v_mov_b32_e32 v106, v204
	v_mov_b32_e32 v107, v205
	v_mov_b32_e32 v96, v206
	v_mov_b32_e32 v97, v207
	v_mov_b32_e32 v98, v208
	v_mov_b32_e32 v99, v209
	v_mov_b32_e32 v90, v210
	v_mov_b32_e32 v91, v211
	v_mov_b32_e32 v92, v212
	v_mov_b32_e32 v93, v213
	v_mov_b32_e32 v80, v214
	v_mov_b32_e32 v81, v215
	v_mov_b32_e32 v82, v216
	v_mov_b32_e32 v83, v217
	v_lshlrev_b32_e32 v94, 16, v104
	v_and_b32_e32 v95, 0xffff0000, v104
	v_pk_add_f32 v[76:77], v[76:77], v[94:95]
	v_lshlrev_b32_e32 v104, 16, v105
	v_and_b32_e32 v105, 0xffff0000, v105
	v_mul_f32_e32 v87, v77, v77
	v_pk_add_f32 v[78:79], v[78:79], v[104:105]
	v_fmac_f32_e32 v87, v76, v76
	v_lshlrev_b32_e32 v112, 16, v106
	v_and_b32_e32 v113, 0xffff0000, v106
	v_fmac_f32_e32 v87, v78, v78
	v_pk_add_f32 v[104:105], v[72:73], v[112:113]
	v_fmac_f32_e32 v87, v79, v79
	v_lshlrev_b32_e32 v106, 16, v107
	v_and_b32_e32 v107, 0xffff0000, v107
	v_fmac_f32_e32 v87, v104, v104
	v_pk_add_f32 v[94:95], v[74:75], v[106:107]
	v_fmac_f32_e32 v87, v105, v105
	v_fmac_f32_e32 v87, v94, v94
	v_cvt_pk_bf16_f32 v73, v78, v79
	v_cvt_pk_bf16_f32 v75, v94, v95
	v_fmac_f32_e32 v87, v95, v95
	v_lshlrev_b32_e32 v78, 16, v96
	v_and_b32_e32 v79, 0xffff0000, v96
	v_lshlrev_b32_e32 v94, 16, v97
	v_and_b32_e32 v95, 0xffff0000, v97
	v_lshlrev_b32_e32 v96, 16, v98
	v_and_b32_e32 v97, 0xffff0000, v98
	v_cvt_pk_bf16_f32 v72, v76, v77
	v_add_co_u32_e32 v76, vcc, s59, v160
	v_lshlrev_b32_e32 v98, 16, v99
	v_and_b32_e32 v99, 0xffff0000, v99
	v_pk_add_f32 v[70:71], v[70:71], v[94:95]
	v_pk_add_f32 v[68:69], v[68:69], v[78:79]
	v_pk_add_f32 v[94:95], v[64:65], v[96:97]
	v_cvt_pk_bf16_f32 v64, v68, v69
	v_cvt_pk_bf16_f32 v74, v104, v105
	v_addc_co_u32_e32 v77, vcc, 0, v161, vcc
	v_pk_add_f32 v[78:79], v[66:67], v[98:99]
	v_cvt_pk_bf16_f32 v65, v70, v71
	v_cvt_pk_bf16_f32 v66, v94, v95
	global_store_dwordx4 v[108:109], v[72:75], off
	v_cvt_pk_bf16_f32 v67, v78, v79
	global_store_dwordx4 v[100:101], v[64:67], off offset:256
	s_nop 0
	v_fmac_f32_e32 v135, v134, v134
	v_mul_f32_e32 v64, v69, v69
	v_fmac_f32_e32 v64, v68, v68
	v_fmac_f32_e32 v64, v70, v70
	v_fmac_f32_e32 v64, v71, v71
	v_fmac_f32_e32 v64, v94, v94
	v_fmac_f32_e32 v64, v95, v95
	v_fmac_f32_e32 v64, v78, v78
	v_fmac_f32_e32 v64, v79, v79
	v_add_f32_e32 v68, v87, v64
	v_lshlrev_b32_e32 v64, 16, v91
	v_and_b32_e32 v65, 0xffff0000, v91
	v_lshl_add_u64 v[66:67], v[160:161], 0, s[18:19]
	v_lshlrev_b32_e32 v70, 16, v90
	v_and_b32_e32 v71, 0xffff0000, v90
	v_lshlrev_b32_e32 v78, 16, v92
	v_and_b32_e32 v79, 0xffff0000, v92
	v_lshlrev_b32_e32 v90, 16, v93
	v_and_b32_e32 v91, 0xffff0000, v93
	v_pk_add_f32 v[92:93], v[62:63], v[64:65]
	s_nop 0
	v_pk_add_f32 v[60:61], v[60:61], v[70:71]
	v_pk_add_f32 v[78:79], v[56:57], v[78:79]
	v_mul_f32_e32 v69, v61, v61
	v_fmac_f32_e32 v69, v60, v60
	v_fmac_f32_e32 v69, v92, v92
	v_fmac_f32_e32 v69, v93, v93
	v_fmac_f32_e32 v69, v78, v78
	v_pk_add_f32 v[70:71], v[58:59], v[90:91]
	v_fmac_f32_e32 v69, v79, v79
	v_fmac_f32_e32 v69, v70, v70
	v_cvt_pk_bf16_f32 v58, v78, v79
	v_cvt_pk_bf16_f32 v59, v70, v71
	v_fmac_f32_e32 v69, v71, v71
	v_lshlrev_b32_e32 v70, 16, v80
	v_and_b32_e32 v71, 0xffff0000, v80
	v_lshlrev_b32_e32 v78, 16, v81
	v_and_b32_e32 v79, 0xffff0000, v81
	v_lshlrev_b32_e32 v80, 16, v82
	v_and_b32_e32 v81, 0xffff0000, v82
	v_lshlrev_b32_e32 v82, 16, v83
	v_and_b32_e32 v83, 0xffff0000, v83
	v_pk_add_f32 v[54:55], v[54:55], v[78:79]
	v_pk_add_f32 v[52:53], v[52:53], v[70:71]
	v_pk_add_f32 v[78:79], v[48:49], v[80:81]
	v_cvt_pk_bf16_f32 v48, v52, v53
	v_pk_add_f32 v[70:71], v[50:51], v[82:83]
	v_cvt_pk_bf16_f32 v49, v54, v55
	v_cvt_pk_bf16_f32 v50, v78, v79
	v_cvt_pk_bf16_f32 v56, v60, v61
	v_add_co_u32_e32 v60, vcc, s60, v160
	v_cvt_pk_bf16_f32 v51, v70, v71
	global_store_dwordx4 v[84:85], v[48:51], off offset:256
	v_cvt_pk_bf16_f32 v57, v92, v93
	s_nop 0
	v_addc_co_u32_e32 v61, vcc, 0, v161, vcc
	v_mul_f32_e32 v48, v53, v53
	v_fmac_f32_e32 v48, v52, v52
	v_fmac_f32_e32 v48, v54, v54
	v_fmac_f32_e32 v48, v55, v55
	v_fmac_f32_e32 v48, v78, v78
	global_store_dwordx4 v[88:89], v[56:59], off
	s_nop 0
	v_fmac_f32_e32 v48, v79, v79
	v_fmac_f32_e32 v48, v70, v70
	v_fmac_f32_e32 v48, v71, v71
	v_add_f32_e32 v69, v69, v48
	v_lshl_add_u64 v[48:49], v[160:161], 0, s[20:21]
	s_nop 0
	v_fmac_f32_e32 v125, v126, v126
	v_fmac_f32_e32 v135, v132, v132
	v_fmac_f32_e32 v125, v127, v127
	v_fmac_f32_e32 v135, v133, v133
	v_fmac_f32_e32 v125, v120, v120
	v_fmac_f32_e32 v135, v142, v142
	v_fmac_f32_e32 v125, v121, v121
	v_fmac_f32_e32 v135, v143, v143
	v_fmac_f32_e32 v125, v122, v122
	s_waitcnt vmcnt(12)
	s_nop 1
	v_mov_b32_e32 v72, v218
	v_mov_b32_e32 v73, v219
	v_mov_b32_e32 v74, v220
	v_mov_b32_e32 v75, v221
	v_mov_b32_e32 v62, v222
	v_mov_b32_e32 v63, v223
	v_mov_b32_e32 v64, v224
	v_mov_b32_e32 v65, v225
	v_mov_b32_e32 v56, v226
	v_mov_b32_e32 v57, v227
	v_mov_b32_e32 v58, v228
	v_mov_b32_e32 v59, v229
	v_mov_b32_e32 v50, v230
	v_mov_b32_e32 v51, v231
	v_mov_b32_e32 v52, v232
	v_mov_b32_e32 v53, v233
	v_lshlrev_b32_e32 v54, 16, v72
	v_and_b32_e32 v55, 0xffff0000, v72
	v_lshlrev_b32_e32 v70, 16, v73
	v_and_b32_e32 v71, 0xffff0000, v73
	v_lshlrev_b32_e32 v72, 16, v74
	v_and_b32_e32 v73, 0xffff0000, v74
	v_pk_add_f32 v[44:45], v[44:45], v[54:55]
	v_pk_add_f32 v[46:47], v[46:47], v[70:71]
	v_pk_add_f32 v[70:71], v[40:41], v[72:73]
	v_mul_f32_e32 v72, v45, v45
	v_fmac_f32_e32 v72, v44, v44
	v_fmac_f32_e32 v72, v46, v46
	v_fmac_f32_e32 v72, v47, v47
	v_lshlrev_b32_e32 v74, 16, v75
	v_and_b32_e32 v75, 0xffff0000, v75
	v_cvt_pk_bf16_f32 v40, v44, v45
	v_fmac_f32_e32 v72, v70, v70
	v_add_co_u32_e32 v44, vcc, s61, v160
	v_pk_add_f32 v[54:55], v[42:43], v[74:75]
	v_cvt_pk_bf16_f32 v41, v46, v47
	v_cvt_pk_bf16_f32 v42, v70, v71
	v_fmac_f32_e32 v72, v71, v71
	v_cvt_pk_bf16_f32 v43, v54, v55
	v_addc_co_u32_e32 v45, vcc, 0, v161, vcc
	global_store_dwordx4 v[76:77], v[40:43], off
	v_fmac_f32_e32 v72, v54, v54
	s_nop 0
	v_lshlrev_b32_e32 v46, 16, v62
	v_and_b32_e32 v47, 0xffff0000, v62
	v_fmac_f32_e32 v72, v55, v55
	v_lshlrev_b32_e32 v54, 16, v63
	v_and_b32_e32 v55, 0xffff0000, v63
	v_lshlrev_b32_e32 v62, 16, v64
	v_and_b32_e32 v63, 0xffff0000, v64
	v_pk_add_f32 v[36:37], v[36:37], v[46:47]
	v_lshlrev_b32_e32 v64, 16, v65
	v_and_b32_e32 v65, 0xffff0000, v65
	v_pk_add_f32 v[38:39], v[38:39], v[54:55]
	v_pk_add_f32 v[54:55], v[32:33], v[62:63]
	v_mul_f32_e32 v62, v37, v37
	v_pk_add_f32 v[46:47], v[34:35], v[64:65]
	v_cvt_pk_bf16_f32 v32, v36, v37
	v_cvt_pk_bf16_f32 v33, v38, v39
	v_cvt_pk_bf16_f32 v34, v54, v55
	v_fmac_f32_e32 v62, v36, v36
	v_cvt_pk_bf16_f32 v35, v46, v47
	v_lshl_add_u64 v[36:37], v[160:161], 0, s[22:23]
	global_store_dwordx4 v[66:67], v[32:35], off offset:256
	s_nop 0
	v_fmac_f32_e32 v62, v38, v38
	v_fmac_f32_e32 v62, v39, v39
	v_fmac_f32_e32 v62, v54, v54
	v_fmac_f32_e32 v62, v55, v55
	v_fmac_f32_e32 v62, v46, v46
	v_fmac_f32_e32 v62, v47, v47
	v_fmac_f32_e32 v135, v140, v140
	v_fmac_f32_e32 v125, v123, v123
	v_fmac_f32_e32 v135, v141, v141
	v_add_f32_e32 v110, v125, v135
	v_add_f32_e32 v62, v72, v62
	v_lshlrev_b32_e32 v38, 16, v56
	v_and_b32_e32 v39, 0xffff0000, v56
	v_lshlrev_b32_e32 v46, 16, v57
	v_and_b32_e32 v47, 0xffff0000, v57
	v_lshlrev_b32_e32 v54, 16, v58
	v_and_b32_e32 v55, 0xffff0000, v58
	v_pk_add_f32 v[28:29], v[28:29], v[38:39]
	v_lshlrev_b32_e32 v56, 16, v59
	v_and_b32_e32 v57, 0xffff0000, v59
	v_pk_add_f32 v[30:31], v[30:31], v[46:47]
	v_pk_add_f32 v[46:47], v[24:25], v[54:55]
	v_mul_f32_e32 v54, v29, v29
	v_pk_add_f32 v[38:39], v[26:27], v[56:57]
	v_cvt_pk_bf16_f32 v24, v28, v29
	v_cvt_pk_bf16_f32 v25, v30, v31
	v_cvt_pk_bf16_f32 v26, v46, v47
	v_fmac_f32_e32 v54, v28, v28
	v_cvt_pk_bf16_f32 v27, v38, v39
	global_store_dwordx4 v[60:61], v[24:27], off
	v_fmac_f32_e32 v54, v30, v30
	v_lshlrev_b32_e32 v28, 16, v52
	v_lshlrev_b32_e32 v24, 16, v50
	v_and_b32_e32 v25, 0xffff0000, v50
	v_lshlrev_b32_e32 v26, 16, v51
	v_and_b32_e32 v27, 0xffff0000, v51
	v_and_b32_e32 v29, 0xffff0000, v52
	v_fmac_f32_e32 v54, v31, v31
	v_lshlrev_b32_e32 v30, 16, v53
	v_and_b32_e32 v31, 0xffff0000, v53
	v_pk_add_f32 v[22:23], v[22:23], v[26:27]
	v_pk_add_f32 v[20:21], v[20:21], v[24:25]
	v_pk_add_f32 v[26:27], v[12:13], v[28:29]
	v_cvt_pk_bf16_f32 v12, v20, v21
	v_pk_add_f32 v[24:25], v[14:15], v[30:31]
	v_cvt_pk_bf16_f32 v13, v22, v23
	v_cvt_pk_bf16_f32 v14, v26, v27
	v_fmac_f32_e32 v54, v46, v46
	v_cvt_pk_bf16_f32 v15, v24, v25
	global_store_dwordx4 v[48:49], v[12:15], off offset:256
	v_fmac_f32_e32 v54, v47, v47
	v_fmac_f32_e32 v54, v38, v38
	v_mul_f32_e32 v12, v21, v21
	v_fmac_f32_e32 v12, v20, v20
	v_fmac_f32_e32 v12, v22, v22
	v_fmac_f32_e32 v12, v23, v23
	v_fmac_f32_e32 v12, v26, v26
	v_fmac_f32_e32 v12, v27, v27
	v_fmac_f32_e32 v12, v24, v24
	v_fmac_f32_e32 v54, v39, v39
	v_fmac_f32_e32 v12, v25, v25
	v_add_f32_e32 v24, v54, v12
	s_waitcnt vmcnt(14)
	s_nop 1
	v_mov_b32_e32 v40, v234
	v_mov_b32_e32 v41, v235
	v_mov_b32_e32 v42, v236
	v_mov_b32_e32 v43, v237
	v_mov_b32_e32 v32, v238
	v_mov_b32_e32 v33, v239
	v_mov_b32_e32 v34, v240
	v_mov_b32_e32 v35, v241
	v_lshlrev_b32_e32 v12, 16, v40
	v_and_b32_e32 v13, 0xffff0000, v40
	v_pk_add_f32 v[12:13], v[16:17], v[12:13]
	v_lshlrev_b32_e32 v14, 16, v41
	v_and_b32_e32 v15, 0xffff0000, v41
	v_lshlrev_b32_e32 v20, 16, v42
	v_and_b32_e32 v21, 0xffff0000, v42
	v_mul_f32_e32 v25, v13, v13
	v_lshlrev_b32_e32 v22, 16, v43
	v_and_b32_e32 v23, 0xffff0000, v43
	v_pk_add_f32 v[14:15], v[18:19], v[14:15]
	v_pk_add_f32 v[18:19], v[8:9], v[20:21]
	v_cvt_pk_bf16_f32 v8, v12, v13
	v_cvt_pk_bf16_f32 v9, v14, v15
	v_fmac_f32_e32 v25, v12, v12
	v_pk_add_f32 v[16:17], v[10:11], v[22:23]
	v_cvt_pk_bf16_f32 v10, v18, v19
	v_fmac_f32_e32 v25, v14, v14
	v_cvt_pk_bf16_f32 v11, v16, v17
	global_store_dwordx4 v[44:45], v[8:11], off
	v_fmac_f32_e32 v25, v15, v15
	v_lshlrev_b32_e32 v12, 16, v34
	v_lshlrev_b32_e32 v8, 16, v32
	v_and_b32_e32 v9, 0xffff0000, v32
	v_and_b32_e32 v13, 0xffff0000, v34
	v_pk_add_f32 v[4:5], v[4:5], v[8:9]
	v_fmac_f32_e32 v25, v18, v18
	v_lshlrev_b32_e32 v10, 16, v33
	v_and_b32_e32 v11, 0xffff0000, v33
	v_pk_add_f32 v[22:23], v[0:1], v[12:13]
	v_mul_f32_e32 v0, v5, v5
	v_fmac_f32_e32 v25, v19, v19
	v_pk_add_f32 v[18:19], v[6:7], v[10:11]
	v_fmac_f32_e32 v0, v4, v4
	v_fmac_f32_e32 v0, v18, v18
	v_fmac_f32_e32 v0, v19, v19
	v_lshlrev_b32_e32 v14, 16, v35
	v_and_b32_e32 v15, 0xffff0000, v35
	v_fmac_f32_e32 v0, v22, v22
	v_pk_add_f32 v[20:21], v[2:3], v[14:15]
	v_fmac_f32_e32 v0, v23, v23
	v_fmac_f32_e32 v25, v16, v16
	v_fmac_f32_e32 v0, v20, v20
	v_fmac_f32_e32 v25, v17, v17
	v_fmac_f32_e32 v0, v21, v21
	v_add_f32_e32 v14, v25, v0
	v_cvt_pk_bf16_f32 v16, v4, v5
	ds_bpermute_b32 v1, v171, v110
	ds_bpermute_b32 v2, v171, v102
	ds_bpermute_b32 v4, v171, v86
	ds_bpermute_b32 v6, v171, v68
	ds_bpermute_b32 v8, v171, v69
	ds_bpermute_b32 v10, v171, v62
	ds_bpermute_b32 v12, v171, v24
	ds_bpermute_b32 v15, v171, v14
	s_waitcnt lgkmcnt(0)
	v_add_f32_e32 v0, v110, v1
	v_add_f32_e32 v2, v102, v2
	v_add_f32_e32 v4, v86, v4
	v_add_f32_e32 v6, v68, v6
	v_add_f32_e32 v8, v69, v8
	v_add_f32_e32 v10, v62, v10
	v_add_f32_e32 v12, v24, v12
	v_add_f32_e32 v14, v14, v15
	ds_bpermute_b32 v1, v172, v0
	ds_bpermute_b32 v3, v172, v2
	ds_bpermute_b32 v5, v172, v4
	ds_bpermute_b32 v7, v172, v6
	ds_bpermute_b32 v9, v172, v8
	ds_bpermute_b32 v11, v172, v10
	ds_bpermute_b32 v13, v172, v12
	ds_bpermute_b32 v15, v172, v14
	v_cvt_pk_bf16_f32 v17, v18, v19
	v_cvt_pk_bf16_f32 v18, v22, v23
	v_cvt_pk_bf16_f32 v19, v20, v21
	global_store_dwordx4 v[36:37], v[16:19], off offset:256
	s_and_saveexec_b64 s[28:29], s[0:1]
	s_cbranch_execz .LBB0_407
	s_waitcnt lgkmcnt(6)
	v_add_f32_e32 v2, v2, v3
	v_add_f32_e32 v0, v0, v1
	v_add_u32_e32 v1, s54, v173
	s_waitcnt lgkmcnt(2)
	v_add_f32_e32 v10, v10, v11
	v_add_f32_e32 v8, v8, v9
	v_add_f32_e32 v6, v6, v7
	v_add_f32_e32 v4, v4, v5
	ds_write2st64_b32 v1, v0, v2 offset1:1
	ds_write2st64_b32 v1, v4, v6 offset0:2 offset1:3
	v_add_u32_e32 v0, s54, v177
	s_waitcnt lgkmcnt(2)
	v_add_f32_e32 v14, v14, v15
	v_add_f32_e32 v12, v12, v13
	ds_write2st64_b32 v0, v8, v10 offset1:1
	ds_write2st64_b32 v0, v12, v14 offset0:2 offset1:3

.LBB0_470:
	s_add_u32 s22, s48, 0xfff00080
	s_addc_u32 s23, s49, -1
	s_add_i32 s86, 0, 0x10000
	v_add_u32_e32 v172, s86, v149
	ds_read_b128 v[144:147], v172
	ds_read_b128 v[164:167], v172 offset:1024
	ds_read_b128 v[168:171], v172 offset:2048
	ds_read_b128 v[172:175], v172 offset:3072
	s_cmp_eq_u32 s60, 60
	s_cselect_b32 s53, s45, s23
	s_cselect_b32 s52, s44, s22
	s_cselect_b32 s51, s47, s19
	s_cselect_b32 s50, s46, s18
	v_lshl_add_u64 v[212:213], s[48:49], 0, v[140:141]
	s_add_i32 m0, s75, 0xc000
	ds_read_b128 v[176:179], v163
	ds_read_b128 v[180:183], v163 offset:1024
	ds_read_b128 v[184:187], v163 offset:2048
	ds_read_b128 v[188:191], v163 offset:3072
	ds_read_b128 v[192:195], v163 offset:4096
	ds_read_b128 v[200:203], v163 offset:5120
	ds_read_b128 v[204:207], v163 offset:6144
	ds_read_b128 v[208:211], v163 offset:7168
	global_load_lds_dwordx4 v[212:213], off
	v_lshl_add_u64 v[212:213], s[48:49], 0, v[142:143]
	s_add_i32 m0, s75, 0xe000
	s_nop 0
	global_load_lds_dwordx4 v[212:213], off
	s_waitcnt lgkmcnt(8)
	s_barrier
	s_waitcnt lgkmcnt(0)
	s_setprio 1
	s_waitcnt lgkmcnt(0)
	v_mfma_f32_16x16x32_bf16 v[124:127], v[144:147], v[176:179], v[124:127]
	v_mfma_f32_16x16x32_bf16 v[120:123], v[168:171], v[176:179], v[120:123]
	v_mfma_f32_16x16x32_bf16 v[108:111], v[144:147], v[184:187], v[108:111]
	v_mfma_f32_16x16x32_bf16 v[104:107], v[168:171], v[184:187], v[104:107]
	v_mfma_f32_16x16x32_bf16 v[92:95], v[144:147], v[192:195], v[92:95]
	v_mfma_f32_16x16x32_bf16 v[88:91], v[168:171], v[192:195], v[88:91]
	v_mfma_f32_16x16x32_bf16 v[76:79], v[144:147], v[204:207], v[76:79]
	v_mfma_f32_16x16x32_bf16 v[72:75], v[168:171], v[204:207], v[72:75]
	v_mfma_f32_16x16x32_bf16 v[124:127], v[164:167], v[180:183], v[124:127]
	v_mfma_f32_16x16x32_bf16 v[120:123], v[172:175], v[180:183], v[120:123]
	v_mfma_f32_16x16x32_bf16 v[108:111], v[164:167], v[188:191], v[108:111]
	v_mfma_f32_16x16x32_bf16 v[104:107], v[172:175], v[188:191], v[104:107]
	v_mfma_f32_16x16x32_bf16 v[92:95], v[164:167], v[200:203], v[92:95]
	v_mfma_f32_16x16x32_bf16 v[88:91], v[172:175], v[200:203], v[88:91]
	v_mfma_f32_16x16x32_bf16 v[76:79], v[164:167], v[208:211], v[76:79]
	v_mfma_f32_16x16x32_bf16 v[72:75], v[172:175], v[208:211], v[72:75]
	s_setprio 0
	s_barrier
	s_add_i32 s87, 0, 0x14000
	s_add_i32 s22, s86, s74
	v_add_u32_e32 v224, s87, v149
	v_lshl_add_u64 v[228:229], s[50:51], 0, v[138:139]
	s_mov_b32 m0, s22
	ds_read_b128 v[212:215], v224
	ds_read_b128 v[216:219], v224 offset:1024
	ds_read_b128 v[220:223], v224 offset:2048
	ds_read_b128 v[224:227], v224 offset:3072
	global_load_lds_dwordx4 v[228:229], off
	v_lshl_add_u64 v[230:231], s[50:51], 0, v[134:135]
	s_add_i32 m0, s22, 0x2000
	s_nop 0
	global_load_lds_dwordx4 v[230:231], off
	s_barrier
	s_waitcnt lgkmcnt(0)
	s_setprio 1
	s_waitcnt lgkmcnt(0)
	v_mfma_f32_16x16x32_bf16 v[116:119], v[212:215], v[176:179], v[116:119]
	v_mfma_f32_16x16x32_bf16 v[112:115], v[220:223], v[176:179], v[112:115]
	v_mfma_f32_16x16x32_bf16 v[100:103], v[212:215], v[184:187], v[100:103]
	v_mfma_f32_16x16x32_bf16 v[96:99], v[220:223], v[184:187], v[96:99]
	v_mfma_f32_16x16x32_bf16 v[84:87], v[212:215], v[192:195], v[84:87]
	v_mfma_f32_16x16x32_bf16 v[80:83], v[220:223], v[192:195], v[80:83]
	v_mfma_f32_16x16x32_bf16 v[68:71], v[212:215], v[204:207], v[68:71]
	v_mfma_f32_16x16x32_bf16 v[64:67], v[220:223], v[204:207], v[64:67]
	v_mfma_f32_16x16x32_bf16 v[116:119], v[216:219], v[180:183], v[116:119]
	v_mfma_f32_16x16x32_bf16 v[112:115], v[224:227], v[180:183], v[112:115]
	v_mfma_f32_16x16x32_bf16 v[100:103], v[216:219], v[188:191], v[100:103]
	v_mfma_f32_16x16x32_bf16 v[96:99], v[224:227], v[188:191], v[96:99]
	v_mfma_f32_16x16x32_bf16 v[84:87], v[216:219], v[200:203], v[84:87]
	v_mfma_f32_16x16x32_bf16 v[80:83], v[224:227], v[200:203], v[80:83]
	v_mfma_f32_16x16x32_bf16 v[68:71], v[216:219], v[208:211], v[68:71]
	v_mfma_f32_16x16x32_bf16 v[64:67], v[224:227], v[208:211], v[64:67]
	s_setprio 0
	s_mov_b32 m0, s75
	v_lshl_add_u64 v[232:233], s[52:53], 0, v[128:129]
	s_barrier
	ds_read_b128 v[176:179], v163 offset:16384
	ds_read_b128 v[180:183], v163 offset:17408
	ds_read_b128 v[184:187], v163 offset:18432
	ds_read_b128 v[188:191], v163 offset:19456
	ds_read_b128 v[192:195], v163 offset:20480
	ds_read_b128 v[200:203], v163 offset:21504
	ds_read_b128 v[204:207], v163 offset:22528
	ds_read_b128 v[208:211], v163 offset:23552
	global_load_lds_dwordx4 v[232:233], off
	v_lshl_add_u64 v[234:235], s[52:53], 0, v[136:137]
	s_mov_b32 m0, s76
	s_nop 0
	global_load_lds_dwordx4 v[234:235], off
	s_barrier
	s_waitcnt lgkmcnt(0)
	s_setprio 1
	s_waitcnt lgkmcnt(0)
	v_mfma_f32_16x16x32_bf16 v[60:63], v[144:147], v[176:179], v[60:63]
	v_mfma_f32_16x16x32_bf16 v[56:59], v[168:171], v[176:179], v[56:59]
	v_mfma_f32_16x16x32_bf16 v[44:47], v[144:147], v[184:187], v[44:47]
	v_mfma_f32_16x16x32_bf16 v[40:43], v[168:171], v[184:187], v[40:43]
	v_mfma_f32_16x16x32_bf16 v[28:31], v[144:147], v[192:195], v[28:31]
	v_mfma_f32_16x16x32_bf16 v[24:27], v[168:171], v[192:195], v[24:27]
	v_mfma_f32_16x16x32_bf16 v[12:15], v[144:147], v[204:207], v[12:15]
	v_mfma_f32_16x16x32_bf16 v[8:11], v[168:171], v[204:207], v[8:11]
	v_mfma_f32_16x16x32_bf16 v[60:63], v[164:167], v[180:183], v[60:63]
	v_mfma_f32_16x16x32_bf16 v[56:59], v[172:175], v[180:183], v[56:59]
	v_mfma_f32_16x16x32_bf16 v[44:47], v[164:167], v[188:191], v[44:47]
	v_mfma_f32_16x16x32_bf16 v[40:43], v[172:175], v[188:191], v[40:43]
	v_mfma_f32_16x16x32_bf16 v[28:31], v[164:167], v[200:203], v[28:31]
	v_mfma_f32_16x16x32_bf16 v[24:27], v[172:175], v[200:203], v[24:27]
	v_mfma_f32_16x16x32_bf16 v[12:15], v[164:167], v[208:211], v[12:15]
	v_mfma_f32_16x16x32_bf16 v[8:11], v[172:175], v[208:211], v[8:11]
	s_setprio 0
	s_barrier
	s_add_u32 s22, s50, 0x100000
	s_addc_u32 s23, s51, 0
	s_add_i32 s86, s87, s74
	v_lshl_add_u64 v[144:145], s[22:23], 0, v[138:139]
	s_mov_b32 m0, s86
	s_nop 0
	global_load_lds_dwordx4 v[144:145], off
	v_lshl_add_u64 v[144:145], s[22:23], 0, v[134:135]
	s_add_i32 m0, s86, 0x2000
	s_nop 0
	global_load_lds_dwordx4 v[144:145], off
	s_waitcnt vmcnt(6)
	s_barrier
	s_setprio 1
	v_mfma_f32_16x16x32_bf16 v[52:55], v[212:215], v[176:179], v[52:55]
	v_mfma_f32_16x16x32_bf16 v[48:51], v[220:223], v[176:179], v[48:51]
	v_mfma_f32_16x16x32_bf16 v[36:39], v[212:215], v[184:187], v[36:39]
	v_mfma_f32_16x16x32_bf16 v[32:35], v[220:223], v[184:187], v[32:35]
	v_mfma_f32_16x16x32_bf16 v[20:23], v[212:215], v[192:195], v[20:23]
	v_mfma_f32_16x16x32_bf16 v[16:19], v[220:223], v[192:195], v[16:19]
	v_mfma_f32_16x16x32_bf16 v[4:7], v[212:215], v[204:207], v[4:7]
	v_mfma_f32_16x16x32_bf16 v[0:3], v[220:223], v[204:207], v[0:3]
	v_mfma_f32_16x16x32_bf16 v[52:55], v[216:219], v[180:183], v[52:55]
	v_mfma_f32_16x16x32_bf16 v[48:51], v[224:227], v[180:183], v[48:51]
	v_mfma_f32_16x16x32_bf16 v[36:39], v[216:219], v[188:191], v[36:39]
	v_mfma_f32_16x16x32_bf16 v[32:35], v[224:227], v[188:191], v[32:35]
	v_mfma_f32_16x16x32_bf16 v[20:23], v[216:219], v[200:203], v[20:23]
	v_mfma_f32_16x16x32_bf16 v[16:19], v[224:227], v[200:203], v[16:19]
	v_mfma_f32_16x16x32_bf16 v[4:7], v[216:219], v[208:211], v[4:7]
	v_mfma_f32_16x16x32_bf16 v[0:3], v[224:227], v[208:211], v[0:3]
	s_setprio 0
	s_add_i32 s86, 0, 0x18000
	v_add_u32_e32 v172, s86, v149
	s_barrier
	ds_read_b128 v[144:147], v172
	ds_read_b128 v[164:167], v172 offset:1024
	ds_read_b128 v[168:171], v172 offset:2048
	ds_read_b128 v[172:175], v172 offset:3072
	s_add_u32 s22, s52, 0x100000
	s_addc_u32 s23, s53, 0
	s_mov_b32 m0, s77
	v_lshl_add_u64 v[212:213], s[22:23], 0, v[128:129]
	ds_read_b128 v[176:179], v163 offset:32768
	ds_read_b128 v[180:183], v163 offset:33792
	ds_read_b128 v[184:187], v163 offset:34816
	ds_read_b128 v[188:191], v163 offset:35840
	ds_read_b128 v[192:195], v163 offset:36864
	ds_read_b128 v[200:203], v163 offset:37888
	ds_read_b128 v[204:207], v163 offset:38912
	ds_read_b128 v[208:211], v163 offset:39936
	global_load_lds_dwordx4 v[212:213], off
	v_lshl_add_u64 v[212:213], s[22:23], 0, v[136:137]
	s_mov_b32 m0, s78
	s_nop 0
	global_load_lds_dwordx4 v[212:213], off
	s_waitcnt lgkmcnt(8)
	s_barrier
	s_waitcnt lgkmcnt(0)
	s_setprio 1
	s_waitcnt lgkmcnt(0)
	v_mfma_f32_16x16x32_bf16 v[124:127], v[144:147], v[176:179], v[124:127]
	v_mfma_f32_16x16x32_bf16 v[120:123], v[168:171], v[176:179], v[120:123]
	v_mfma_f32_16x16x32_bf16 v[108:111], v[144:147], v[184:187], v[108:111]
	v_mfma_f32_16x16x32_bf16 v[104:107], v[168:171], v[184:187], v[104:107]
	v_mfma_f32_16x16x32_bf16 v[92:95], v[144:147], v[192:195], v[92:95]
	v_mfma_f32_16x16x32_bf16 v[88:91], v[168:171], v[192:195], v[88:91]
	v_mfma_f32_16x16x32_bf16 v[76:79], v[144:147], v[204:207], v[76:79]
	v_mfma_f32_16x16x32_bf16 v[72:75], v[168:171], v[204:207], v[72:75]
	v_mfma_f32_16x16x32_bf16 v[124:127], v[164:167], v[180:183], v[124:127]
	v_mfma_f32_16x16x32_bf16 v[120:123], v[172:175], v[180:183], v[120:123]
	v_mfma_f32_16x16x32_bf16 v[108:111], v[164:167], v[188:191], v[108:111]
	v_mfma_f32_16x16x32_bf16 v[104:107], v[172:175], v[188:191], v[104:107]
	v_mfma_f32_16x16x32_bf16 v[92:95], v[164:167], v[200:203], v[92:95]
	v_mfma_f32_16x16x32_bf16 v[88:91], v[172:175], v[200:203], v[88:91]
	v_mfma_f32_16x16x32_bf16 v[76:79], v[164:167], v[208:211], v[76:79]
	v_mfma_f32_16x16x32_bf16 v[72:75], v[172:175], v[208:211], v[72:75]
	s_setprio 0
	s_barrier
	s_add_i32 s52, 0, 0x1c000
	s_add_i32 s22, s86, s74
	v_add_u32_e32 v224, s52, v149
	v_lshl_add_u64 v[228:229], v[228:229], 0, s[40:41]
	s_mov_b32 m0, s22
	ds_read_b128 v[212:215], v224
	ds_read_b128 v[216:219], v224 offset:1024
	ds_read_b128 v[220:223], v224 offset:2048
	ds_read_b128 v[224:227], v224 offset:3072
	global_load_lds_dwordx4 v[228:229], off
	v_lshl_add_u64 v[228:229], v[230:231], 0, s[40:41]
	s_add_i32 m0, s22, 0x2000
	s_nop 0
	global_load_lds_dwordx4 v[228:229], off
	s_barrier
	s_waitcnt lgkmcnt(0)
	s_setprio 1
	s_waitcnt lgkmcnt(0)
	v_mfma_f32_16x16x32_bf16 v[116:119], v[212:215], v[176:179], v[116:119]
	v_mfma_f32_16x16x32_bf16 v[112:115], v[220:223], v[176:179], v[112:115]
	v_mfma_f32_16x16x32_bf16 v[100:103], v[212:215], v[184:187], v[100:103]
	v_mfma_f32_16x16x32_bf16 v[96:99], v[220:223], v[184:187], v[96:99]
	v_mfma_f32_16x16x32_bf16 v[84:87], v[212:215], v[192:195], v[84:87]
	v_mfma_f32_16x16x32_bf16 v[80:83], v[220:223], v[192:195], v[80:83]
	v_mfma_f32_16x16x32_bf16 v[68:71], v[212:215], v[204:207], v[68:71]
	v_mfma_f32_16x16x32_bf16 v[64:67], v[220:223], v[204:207], v[64:67]
	v_mfma_f32_16x16x32_bf16 v[116:119], v[216:219], v[180:183], v[116:119]
	v_mfma_f32_16x16x32_bf16 v[112:115], v[224:227], v[180:183], v[112:115]
	v_mfma_f32_16x16x32_bf16 v[100:103], v[216:219], v[188:191], v[100:103]
	v_mfma_f32_16x16x32_bf16 v[96:99], v[224:227], v[188:191], v[96:99]
	v_mfma_f32_16x16x32_bf16 v[84:87], v[216:219], v[200:203], v[84:87]
	v_mfma_f32_16x16x32_bf16 v[80:83], v[224:227], v[200:203], v[80:83]
	v_mfma_f32_16x16x32_bf16 v[68:71], v[216:219], v[208:211], v[68:71]
	v_mfma_f32_16x16x32_bf16 v[64:67], v[224:227], v[208:211], v[64:67]
	s_setprio 0
	s_mov_b32 m0, s79
	v_lshl_add_u64 v[228:229], v[232:233], 0, s[40:41]
	s_barrier
	ds_read_b128 v[176:179], v163 offset:49152
	ds_read_b128 v[180:183], v163 offset:50176
	ds_read_b128 v[184:187], v163 offset:51200
	ds_read_b128 v[188:191], v163 offset:52224
	ds_read_b128 v[192:195], v163 offset:53248
	ds_read_b128 v[200:203], v163 offset:54272
	ds_read_b128 v[204:207], v163 offset:55296
	ds_read_b128 v[208:211], v163 offset:56320
	global_load_lds_dwordx4 v[228:229], off
	v_lshl_add_u64 v[228:229], v[234:235], 0, s[40:41]
	s_mov_b32 m0, s80
	s_nop 0
	global_load_lds_dwordx4 v[228:229], off
	s_barrier
	s_waitcnt lgkmcnt(0)
	s_setprio 1
	s_waitcnt lgkmcnt(0)
	v_mfma_f32_16x16x32_bf16 v[60:63], v[144:147], v[176:179], v[60:63]
	v_mfma_f32_16x16x32_bf16 v[56:59], v[168:171], v[176:179], v[56:59]
	v_mfma_f32_16x16x32_bf16 v[44:47], v[144:147], v[184:187], v[44:47]
	v_mfma_f32_16x16x32_bf16 v[40:43], v[168:171], v[184:187], v[40:43]
	v_mfma_f32_16x16x32_bf16 v[28:31], v[144:147], v[192:195], v[28:31]
	v_mfma_f32_16x16x32_bf16 v[24:27], v[168:171], v[192:195], v[24:27]
	v_mfma_f32_16x16x32_bf16 v[12:15], v[144:147], v[204:207], v[12:15]
	v_mfma_f32_16x16x32_bf16 v[8:11], v[168:171], v[204:207], v[8:11]
	v_mfma_f32_16x16x32_bf16 v[60:63], v[164:167], v[180:183], v[60:63]
	v_mfma_f32_16x16x32_bf16 v[56:59], v[172:175], v[180:183], v[56:59]
	v_mfma_f32_16x16x32_bf16 v[44:47], v[164:167], v[188:191], v[44:47]
	v_mfma_f32_16x16x32_bf16 v[40:43], v[172:175], v[188:191], v[40:43]
	v_mfma_f32_16x16x32_bf16 v[28:31], v[164:167], v[200:203], v[28:31]
	v_mfma_f32_16x16x32_bf16 v[24:27], v[172:175], v[200:203], v[24:27]
	v_mfma_f32_16x16x32_bf16 v[12:15], v[164:167], v[208:211], v[12:15]
	v_mfma_f32_16x16x32_bf16 v[8:11], v[172:175], v[208:211], v[8:11]
	s_setprio 0
	s_barrier
	s_add_u32 s22, s50, 0x100080
	s_addc_u32 s23, s51, 0
	s_add_i32 s50, s52, s74
	v_lshl_add_u64 v[144:145], s[22:23], 0, v[138:139]
	s_mov_b32 m0, s50
	s_nop 0
	global_load_lds_dwordx4 v[144:145], off
	v_lshl_add_u64 v[144:145], s[22:23], 0, v[134:135]
	s_add_i32 m0, s50, 0x2000
	s_nop 0
	global_load_lds_dwordx4 v[144:145], off
	s_waitcnt vmcnt(6)
	s_barrier
	s_setprio 1
	v_mfma_f32_16x16x32_bf16 v[52:55], v[212:215], v[176:179], v[52:55]
	v_mfma_f32_16x16x32_bf16 v[48:51], v[220:223], v[176:179], v[48:51]
	v_mfma_f32_16x16x32_bf16 v[36:39], v[212:215], v[184:187], v[36:39]
	v_mfma_f32_16x16x32_bf16 v[32:35], v[220:223], v[184:187], v[32:35]
	v_mfma_f32_16x16x32_bf16 v[20:23], v[212:215], v[192:195], v[20:23]
	v_mfma_f32_16x16x32_bf16 v[16:19], v[220:223], v[192:195], v[16:19]
	v_mfma_f32_16x16x32_bf16 v[4:7], v[212:215], v[204:207], v[4:7]
	v_mfma_f32_16x16x32_bf16 v[0:3], v[220:223], v[204:207], v[0:3]
	v_mfma_f32_16x16x32_bf16 v[52:55], v[216:219], v[180:183], v[52:55]
	v_mfma_f32_16x16x32_bf16 v[48:51], v[224:227], v[180:183], v[48:51]
	v_mfma_f32_16x16x32_bf16 v[36:39], v[216:219], v[188:191], v[36:39]
	v_mfma_f32_16x16x32_bf16 v[32:35], v[224:227], v[188:191], v[32:35]
	v_mfma_f32_16x16x32_bf16 v[20:23], v[216:219], v[200:203], v[20:23]
	v_mfma_f32_16x16x32_bf16 v[16:19], v[224:227], v[200:203], v[16:19]
	v_mfma_f32_16x16x32_bf16 v[4:7], v[216:219], v[208:211], v[4:7]
	v_mfma_f32_16x16x32_bf16 v[0:3], v[224:227], v[208:211], v[0:3]
	s_setprio 0
	s_add_i32 s60, s60, 2
	s_add_u32 s48, s48, 0x100
	s_addc_u32 s49, s49, 0
	s_add_u32 s18, s18, 0x100
	s_addc_u32 s19, s19, 0
	s_cmp_gt_u32 s60, 61
	s_barrier
	s_cbranch_scc0 .LBB0_470
	v_add_u32_e32 v144, s33, v148
	v_ashrrev_i32_e32 v145, 31, v144
	v_readlane_b32 s18, v254, 56
	v_add_u32_e32 v146, s83, v150
	v_lshlrev_b64 v[164:165], 11, v[144:145]
	v_readlane_b32 s19, v254, 57
	v_ashrrev_i32_e32 v147, 31, v146
	s_nop 0
	v_lshl_add_u64 v[164:165], s[18:19], 0, v[164:165]
	v_lshl_add_u64 v[146:147], v[146:147], 1, v[164:165]
	global_load_dwordx4 v[164:167], v[146:147], off
	global_load_dwordx4 v[172:175], v[146:147], off offset:256
	s_mov_b32 s98, 0x8000
	s_mov_b32 s99, 0
	v_lshl_add_u64 v[236:237], v[146:147], 0, s[98:99]
	global_load_dwordx4 v[176:179], v[236:237], off
	s_mov_b64 s[98:99], 0x8000
	v_lshl_add_u64 v[236:237], v[146:147], 0, s[98:99]
	global_load_dwordx4 v[180:183], v[236:237], off offset:256
	s_mov_b32 s98, 0x10000
	s_mov_b32 s99, 0
	v_lshl_add_u64 v[236:237], v[146:147], 0, s[98:99]
	global_load_dwordx4 v[184:187], v[236:237], off
	s_mov_b64 s[98:99], 0x10000
	v_lshl_add_u64 v[236:237], v[146:147], 0, s[98:99]
	global_load_dwordx4 v[188:191], v[236:237], off offset:256
	s_mov_b32 s98, 0x18000
	s_mov_b32 s99, 0
	v_lshl_add_u64 v[236:237], v[146:147], 0, s[98:99]
	global_load_dwordx4 v[192:195], v[236:237], off
	s_mov_b64 s[98:99], 0x18000
	v_lshl_add_u64 v[236:237], v[146:147], 0, s[98:99]
	global_load_dwordx4 v[200:203], v[236:237], off offset:256
	s_mov_b32 s98, 0x40000
	s_mov_b32 s99, 0
	v_lshl_add_u64 v[236:237], v[146:147], 0, s[98:99]
	global_load_dwordx4 v[204:207], v[236:237], off
	s_mov_b64 s[98:99], 0x40000
	v_lshl_add_u64 v[236:237], v[146:147], 0, s[98:99]
	global_load_dwordx4 v[208:211], v[236:237], off offset:256
	s_mov_b32 s98, 0x48000
	s_mov_b32 s99, 0
	v_lshl_add_u64 v[236:237], v[146:147], 0, s[98:99]
	global_load_dwordx4 v[212:215], v[236:237], off
	s_mov_b64 s[98:99], 0x48000
	v_lshl_add_u64 v[236:237], v[146:147], 0, s[98:99]
	global_load_dwordx4 v[216:219], v[236:237], off offset:256
	s_mov_b32 s98, 0x50000
	s_mov_b32 s99, 0
	v_lshl_add_u64 v[236:237], v[146:147], 0, s[98:99]
	global_load_dwordx4 v[220:223], v[236:237], off
	s_mov_b64 s[98:99], 0x50000
	v_lshl_add_u64 v[236:237], v[146:147], 0, s[98:99]
	global_load_dwordx4 v[224:227], v[236:237], off offset:256
	s_mov_b32 s98, 0x58000
	s_mov_b32 s99, 0
	v_lshl_add_u64 v[236:237], v[146:147], 0, s[98:99]
	global_load_dwordx4 v[228:231], v[236:237], off
	s_mov_b64 s[98:99], 0x58000
	v_lshl_add_u64 v[236:237], v[146:147], 0, s[98:99]
	global_load_dwordx4 v[232:235], v[236:237], off offset:256
	s_mov_b64 s[18:19], 0x8000
	s_waitcnt vmcnt(15)
	v_lshlrev_b32_e32 v168, 16, v164
	v_and_b32_e32 v169, 0xffff0000, v164
	v_lshlrev_b32_e32 v164, 16, v165
	v_and_b32_e32 v165, 0xffff0000, v165
	v_lshlrev_b32_e32 v170, 16, v166
	v_and_b32_e32 v171, 0xffff0000, v166
	v_lshlrev_b32_e32 v166, 16, v167
	v_and_b32_e32 v167, 0xffff0000, v167
	v_pk_add_f32 v[126:127], v[126:127], v[164:165]
	v_pk_add_f32 v[124:125], v[124:125], v[168:169]
	v_pk_add_f32 v[164:165], v[122:123], v[166:167]
	v_pk_add_f32 v[166:167], v[120:121], v[170:171]
	v_cvt_pk_bf16_f32 v120, v124, v125
	v_cvt_pk_bf16_f32 v121, v126, v127
	v_cvt_pk_bf16_f32 v123, v164, v165
	v_mul_f32_e32 v168, v125, v125
	v_cvt_pk_bf16_f32 v122, v166, v167
	global_store_dwordx4 v[146:147], v[120:123], off
	s_nop 0
	v_fmac_f32_e32 v168, v124, v124
	v_fmac_f32_e32 v168, v126, v126
	v_fmac_f32_e32 v168, v127, v127
	v_fmac_f32_e32 v168, v166, v166
	v_fmac_f32_e32 v168, v167, v167
	v_fmac_f32_e32 v168, v164, v164
	v_fmac_f32_e32 v168, v165, v165
	s_waitcnt vmcnt(15)
	s_nop 1
	v_mov_b32_e32 v120, v172
	v_mov_b32_e32 v121, v173
	v_mov_b32_e32 v122, v174
	v_mov_b32_e32 v123, v175
	v_lshlrev_b32_e32 v124, 16, v120
	v_and_b32_e32 v125, 0xffff0000, v120
	v_lshlrev_b32_e32 v120, 16, v121
	v_and_b32_e32 v121, 0xffff0000, v121
	v_lshlrev_b32_e32 v126, 16, v122
	v_and_b32_e32 v127, 0xffff0000, v122
	v_lshlrev_b32_e32 v122, 16, v123
	v_and_b32_e32 v123, 0xffff0000, v123
	v_pk_add_f32 v[118:119], v[118:119], v[120:121]
	v_pk_add_f32 v[116:117], v[116:117], v[124:125]
	v_pk_add_f32 v[120:121], v[114:115], v[122:123]
	v_pk_add_f32 v[122:123], v[112:113], v[126:127]
	v_cvt_pk_bf16_f32 v112, v116, v117
	v_cvt_pk_bf16_f32 v113, v118, v119
	v_cvt_pk_bf16_f32 v115, v120, v121
	s_nop 0
	v_cvt_pk_bf16_f32 v114, v122, v123
	global_store_dwordx4 v[146:147], v[112:115], off offset:256
	s_nop 1
	v_mul_f32_e32 v112, v117, v117
	v_fmac_f32_e32 v112, v116, v116
	v_fmac_f32_e32 v112, v118, v118
	v_fmac_f32_e32 v112, v119, v119
	v_fmac_f32_e32 v112, v122, v122
	v_fmac_f32_e32 v112, v123, v123
	v_lshl_add_u64 v[118:119], v[146:147], 0, s[18:19]
	s_mov_b32 s18, 0x8000
	v_fmac_f32_e32 v112, v120, v120
	v_add_co_u32_e32 v120, vcc, s18, v146
	v_fmac_f32_e32 v112, v121, v121
	s_nop 0
	v_addc_co_u32_e32 v121, vcc, 0, v147, vcc
	s_nop 0
	s_mov_b64 s[18:19], 0x10000
	v_add_f32_e32 v112, v168, v112
	s_waitcnt vmcnt(15)
	s_nop 1
	v_mov_b32_e32 v114, v176
	v_mov_b32_e32 v115, v177
	v_mov_b32_e32 v116, v178
	v_mov_b32_e32 v117, v179
	v_lshlrev_b32_e32 v122, 16, v114
	v_and_b32_e32 v123, 0xffff0000, v114
	v_lshlrev_b32_e32 v114, 16, v115
	v_and_b32_e32 v115, 0xffff0000, v115
	v_lshlrev_b32_e32 v124, 16, v116
	v_and_b32_e32 v125, 0xffff0000, v116
	v_lshlrev_b32_e32 v116, 16, v117
	v_and_b32_e32 v117, 0xffff0000, v117
	v_pk_add_f32 v[110:111], v[110:111], v[114:115]
	v_pk_add_f32 v[108:109], v[108:109], v[122:123]
	v_pk_add_f32 v[114:115], v[106:107], v[116:117]
	v_pk_add_f32 v[116:117], v[104:105], v[124:125]
	v_cvt_pk_bf16_f32 v104, v108, v109
	v_cvt_pk_bf16_f32 v105, v110, v111
	v_cvt_pk_bf16_f32 v107, v114, v115
	v_mul_f32_e32 v113, v109, v109
	v_cvt_pk_bf16_f32 v106, v116, v117
	global_store_dwordx4 v[120:121], v[104:107], off
	s_nop 0
	v_fmac_f32_e32 v113, v108, v108
	v_fmac_f32_e32 v113, v110, v110
	v_fmac_f32_e32 v113, v111, v111
	v_fmac_f32_e32 v113, v116, v116
	v_fmac_f32_e32 v113, v117, v117
	v_fmac_f32_e32 v113, v114, v114
	v_fmac_f32_e32 v113, v115, v115
	s_waitcnt vmcnt(15)
	s_nop 1
	v_mov_b32_e32 v104, v180
	v_mov_b32_e32 v105, v181
	v_mov_b32_e32 v106, v182
	v_mov_b32_e32 v107, v183
	v_lshlrev_b32_e32 v108, 16, v104
	v_and_b32_e32 v109, 0xffff0000, v104
	v_lshlrev_b32_e32 v104, 16, v105
	v_and_b32_e32 v105, 0xffff0000, v105
	v_lshlrev_b32_e32 v110, 16, v106
	v_and_b32_e32 v111, 0xffff0000, v106
	v_lshlrev_b32_e32 v106, 16, v107
	v_and_b32_e32 v107, 0xffff0000, v107
	v_pk_add_f32 v[102:103], v[102:103], v[104:105]
	v_pk_add_f32 v[100:101], v[100:101], v[108:109]
	v_pk_add_f32 v[104:105], v[98:99], v[106:107]
	v_pk_add_f32 v[106:107], v[96:97], v[110:111]
	v_cvt_pk_bf16_f32 v96, v100, v101
	v_cvt_pk_bf16_f32 v97, v102, v103
	v_cvt_pk_bf16_f32 v99, v104, v105
	s_nop 0
	v_cvt_pk_bf16_f32 v98, v106, v107
	global_store_dwordx4 v[118:119], v[96:99], off offset:256
	s_nop 1
	v_mul_f32_e32 v96, v101, v101
	v_fmac_f32_e32 v96, v100, v100
	v_fmac_f32_e32 v96, v102, v102
	v_fmac_f32_e32 v96, v103, v103
	v_fmac_f32_e32 v96, v106, v106
	v_fmac_f32_e32 v96, v107, v107
	v_fmac_f32_e32 v96, v104, v104
	v_fmac_f32_e32 v96, v105, v105
	v_add_f32_e32 v98, v113, v96
	v_lshl_add_u64 v[96:97], v[146:147], 0, s[18:19]
	s_mov_b32 s18, 0x10000
	v_add_co_u32_e32 v104, vcc, s18, v146
	s_mov_b64 s[18:19], 0x18000
	s_nop 0
	v_addc_co_u32_e32 v105, vcc, 0, v147, vcc
	s_nop 0
	s_waitcnt vmcnt(15)
	s_nop 1
	v_mov_b32_e32 v100, v184
	v_mov_b32_e32 v101, v185
	v_mov_b32_e32 v102, v186
	v_mov_b32_e32 v103, v187
	v_lshlrev_b32_e32 v106, 16, v100
	v_and_b32_e32 v107, 0xffff0000, v100
	v_lshlrev_b32_e32 v100, 16, v101
	v_and_b32_e32 v101, 0xffff0000, v101
	v_lshlrev_b32_e32 v108, 16, v102
	v_and_b32_e32 v109, 0xffff0000, v102
	v_lshlrev_b32_e32 v102, 16, v103
	v_and_b32_e32 v103, 0xffff0000, v103
	v_pk_add_f32 v[94:95], v[94:95], v[100:101]
	v_pk_add_f32 v[92:93], v[92:93], v[106:107]
	v_pk_add_f32 v[100:101], v[90:91], v[102:103]
	v_pk_add_f32 v[102:103], v[88:89], v[108:109]
	v_cvt_pk_bf16_f32 v88, v92, v93
	v_cvt_pk_bf16_f32 v89, v94, v95
	v_cvt_pk_bf16_f32 v91, v100, v101
	v_mul_f32_e32 v99, v93, v93
	v_cvt_pk_bf16_f32 v90, v102, v103
	global_store_dwordx4 v[104:105], v[88:91], off
	s_nop 0
	v_fmac_f32_e32 v99, v92, v92
	v_fmac_f32_e32 v99, v94, v94
	v_fmac_f32_e32 v99, v95, v95
	v_fmac_f32_e32 v99, v102, v102
	v_fmac_f32_e32 v99, v103, v103
	v_fmac_f32_e32 v99, v100, v100
	v_fmac_f32_e32 v99, v101, v101
	s_waitcnt vmcnt(15)
	s_nop 1
	v_mov_b32_e32 v88, v188
	v_mov_b32_e32 v89, v189
	v_mov_b32_e32 v90, v190
	v_mov_b32_e32 v91, v191
	v_lshlrev_b32_e32 v92, 16, v88
	v_and_b32_e32 v93, 0xffff0000, v88
	v_lshlrev_b32_e32 v88, 16, v89
	v_and_b32_e32 v89, 0xffff0000, v89
	v_lshlrev_b32_e32 v94, 16, v90
	v_and_b32_e32 v95, 0xffff0000, v90
	v_lshlrev_b32_e32 v90, 16, v91
	v_and_b32_e32 v91, 0xffff0000, v91
	v_pk_add_f32 v[86:87], v[86:87], v[88:89]
	v_pk_add_f32 v[84:85], v[84:85], v[92:93]
	v_pk_add_f32 v[88:89], v[82:83], v[90:91]
	v_pk_add_f32 v[90:91], v[80:81], v[94:95]
	v_cvt_pk_bf16_f32 v80, v84, v85
	v_cvt_pk_bf16_f32 v81, v86, v87
	v_cvt_pk_bf16_f32 v83, v88, v89
	s_nop 0
	v_cvt_pk_bf16_f32 v82, v90, v91
	global_store_dwordx4 v[96:97], v[80:83], off offset:256
	s_nop 1
	v_mul_f32_e32 v80, v85, v85
	v_fmac_f32_e32 v80, v84, v84
	v_fmac_f32_e32 v80, v86, v86
	v_fmac_f32_e32 v80, v87, v87
	v_fmac_f32_e32 v80, v90, v90
	v_fmac_f32_e32 v80, v91, v91
	v_fmac_f32_e32 v80, v88, v88
	v_fmac_f32_e32 v80, v89, v89
	v_add_f32_e32 v82, v99, v80
	v_lshl_add_u64 v[80:81], v[146:147], 0, s[18:19]
	s_mov_b32 s18, 0x18000
	v_add_co_u32_e32 v88, vcc, s18, v146
	s_mov_b64 s[18:19], 0x40000
	s_nop 0
	v_addc_co_u32_e32 v89, vcc, 0, v147, vcc
	s_nop 0
	s_waitcnt vmcnt(15)
	s_nop 1
	v_mov_b32_e32 v84, v192
	v_mov_b32_e32 v85, v193
	v_mov_b32_e32 v86, v194
	v_mov_b32_e32 v87, v195
	v_lshlrev_b32_e32 v90, 16, v84
	v_and_b32_e32 v91, 0xffff0000, v84
	v_lshlrev_b32_e32 v84, 16, v85
	v_and_b32_e32 v85, 0xffff0000, v85
	v_lshlrev_b32_e32 v92, 16, v86
	v_and_b32_e32 v93, 0xffff0000, v86
	v_lshlrev_b32_e32 v86, 16, v87
	v_and_b32_e32 v87, 0xffff0000, v87
	v_pk_add_f32 v[78:79], v[78:79], v[84:85]
	v_pk_add_f32 v[76:77], v[76:77], v[90:91]
	v_pk_add_f32 v[84:85], v[74:75], v[86:87]
	v_pk_add_f32 v[86:87], v[72:73], v[92:93]
	v_cvt_pk_bf16_f32 v72, v76, v77
	v_cvt_pk_bf16_f32 v73, v78, v79
	v_cvt_pk_bf16_f32 v75, v84, v85
	v_mul_f32_e32 v83, v77, v77
	v_cvt_pk_bf16_f32 v74, v86, v87
	global_store_dwordx4 v[88:89], v[72:75], off
	s_nop 0
	v_fmac_f32_e32 v83, v76, v76
	v_fmac_f32_e32 v83, v78, v78
	v_fmac_f32_e32 v83, v79, v79
	v_fmac_f32_e32 v83, v86, v86
	v_fmac_f32_e32 v83, v87, v87
	v_fmac_f32_e32 v83, v84, v84
	v_fmac_f32_e32 v83, v85, v85
	s_waitcnt vmcnt(15)
	s_nop 1
	v_mov_b32_e32 v72, v200
	v_mov_b32_e32 v73, v201
	v_mov_b32_e32 v74, v202
	v_mov_b32_e32 v75, v203
	v_lshlrev_b32_e32 v76, 16, v72
	v_and_b32_e32 v77, 0xffff0000, v72
	v_lshlrev_b32_e32 v72, 16, v73
	v_and_b32_e32 v73, 0xffff0000, v73
	v_lshlrev_b32_e32 v78, 16, v74
	v_and_b32_e32 v79, 0xffff0000, v74
	v_lshlrev_b32_e32 v74, 16, v75
	v_and_b32_e32 v75, 0xffff0000, v75
	v_pk_add_f32 v[70:71], v[70:71], v[72:73]
	v_pk_add_f32 v[68:69], v[68:69], v[76:77]
	v_pk_add_f32 v[72:73], v[66:67], v[74:75]
	v_pk_add_f32 v[74:75], v[64:65], v[78:79]
	v_cvt_pk_bf16_f32 v64, v68, v69
	v_cvt_pk_bf16_f32 v65, v70, v71
	v_cvt_pk_bf16_f32 v67, v72, v73
	s_nop 0
	v_cvt_pk_bf16_f32 v66, v74, v75
	global_store_dwordx4 v[80:81], v[64:67], off offset:256
	s_nop 1
	v_mul_f32_e32 v64, v69, v69
	v_fmac_f32_e32 v64, v68, v68
	v_fmac_f32_e32 v64, v70, v70
	v_fmac_f32_e32 v64, v71, v71
	v_fmac_f32_e32 v64, v74, v74
	v_fmac_f32_e32 v64, v75, v75
	v_fmac_f32_e32 v64, v72, v72
	v_fmac_f32_e32 v64, v73, v73
	v_add_f32_e32 v66, v83, v64
	v_lshl_add_u64 v[64:65], v[146:147], 0, s[18:19]
	s_mov_b32 s18, 0x40000
	v_add_co_u32_e32 v72, vcc, s18, v146
	s_mov_b64 s[18:19], 0x48000
	s_nop 0
	v_addc_co_u32_e32 v73, vcc, 0, v147, vcc
	s_nop 0
	s_waitcnt vmcnt(15)
	s_nop 1
	v_mov_b32_e32 v68, v204
	v_mov_b32_e32 v69, v205
	v_mov_b32_e32 v70, v206
	v_mov_b32_e32 v71, v207
	v_lshlrev_b32_e32 v74, 16, v68
	v_and_b32_e32 v75, 0xffff0000, v68
	v_lshlrev_b32_e32 v68, 16, v69
	v_and_b32_e32 v69, 0xffff0000, v69
	v_lshlrev_b32_e32 v76, 16, v70
	v_and_b32_e32 v77, 0xffff0000, v70
	v_lshlrev_b32_e32 v70, 16, v71
	v_and_b32_e32 v71, 0xffff0000, v71
	v_pk_add_f32 v[62:63], v[62:63], v[68:69]
	v_pk_add_f32 v[60:61], v[60:61], v[74:75]
	v_pk_add_f32 v[68:69], v[58:59], v[70:71]
	v_pk_add_f32 v[70:71], v[56:57], v[76:77]
	v_cvt_pk_bf16_f32 v56, v60, v61
	v_cvt_pk_bf16_f32 v57, v62, v63
	v_cvt_pk_bf16_f32 v59, v68, v69
	v_mul_f32_e32 v67, v61, v61
	v_cvt_pk_bf16_f32 v58, v70, v71
	global_store_dwordx4 v[72:73], v[56:59], off
	s_nop 0
	v_fmac_f32_e32 v67, v60, v60
	v_fmac_f32_e32 v67, v62, v62
	v_fmac_f32_e32 v67, v63, v63
	v_fmac_f32_e32 v67, v70, v70
	v_fmac_f32_e32 v67, v71, v71
	v_fmac_f32_e32 v67, v68, v68
	v_fmac_f32_e32 v67, v69, v69
	s_waitcnt vmcnt(15)
	s_nop 1
	v_mov_b32_e32 v56, v208
	v_mov_b32_e32 v57, v209
	v_mov_b32_e32 v58, v210
	v_mov_b32_e32 v59, v211
	v_lshlrev_b32_e32 v60, 16, v56
	v_and_b32_e32 v61, 0xffff0000, v56
	v_lshlrev_b32_e32 v56, 16, v57
	v_and_b32_e32 v57, 0xffff0000, v57
	v_lshlrev_b32_e32 v62, 16, v58
	v_and_b32_e32 v63, 0xffff0000, v58
	v_lshlrev_b32_e32 v58, 16, v59
	v_and_b32_e32 v59, 0xffff0000, v59
	v_pk_add_f32 v[54:55], v[54:55], v[56:57]
	v_pk_add_f32 v[52:53], v[52:53], v[60:61]
	v_pk_add_f32 v[56:57], v[50:51], v[58:59]
	v_pk_add_f32 v[58:59], v[48:49], v[62:63]
	v_cvt_pk_bf16_f32 v48, v52, v53
	v_cvt_pk_bf16_f32 v49, v54, v55
	v_cvt_pk_bf16_f32 v51, v56, v57
	s_nop 0
	v_cvt_pk_bf16_f32 v50, v58, v59
	global_store_dwordx4 v[64:65], v[48:51], off offset:256
	s_nop 1
	v_mul_f32_e32 v48, v53, v53
	v_fmac_f32_e32 v48, v52, v52
	v_fmac_f32_e32 v48, v54, v54
	v_fmac_f32_e32 v48, v55, v55
	v_fmac_f32_e32 v48, v58, v58
	v_fmac_f32_e32 v48, v59, v59
	v_fmac_f32_e32 v48, v56, v56
	v_fmac_f32_e32 v48, v57, v57
	v_add_f32_e32 v50, v67, v48
	v_lshl_add_u64 v[48:49], v[146:147], 0, s[18:19]
	s_mov_b32 s18, 0x48000
	v_add_co_u32_e32 v56, vcc, s18, v146
	s_mov_b64 s[18:19], 0x50000
	s_nop 0
	v_addc_co_u32_e32 v57, vcc, 0, v147, vcc
	s_nop 0
	s_waitcnt vmcnt(15)
	s_nop 1
	v_mov_b32_e32 v52, v212
	v_mov_b32_e32 v53, v213
	v_mov_b32_e32 v54, v214
	v_mov_b32_e32 v55, v215
	v_lshlrev_b32_e32 v58, 16, v52
	v_and_b32_e32 v59, 0xffff0000, v52
	v_lshlrev_b32_e32 v52, 16, v53
	v_and_b32_e32 v53, 0xffff0000, v53
	v_lshlrev_b32_e32 v60, 16, v54
	v_and_b32_e32 v61, 0xffff0000, v54
	v_lshlrev_b32_e32 v54, 16, v55
	v_and_b32_e32 v55, 0xffff0000, v55
	v_pk_add_f32 v[46:47], v[46:47], v[52:53]
	v_pk_add_f32 v[44:45], v[44:45], v[58:59]
	v_pk_add_f32 v[52:53], v[42:43], v[54:55]
	v_pk_add_f32 v[54:55], v[40:41], v[60:61]
	v_cvt_pk_bf16_f32 v40, v44, v45
	v_cvt_pk_bf16_f32 v41, v46, v47
	v_cvt_pk_bf16_f32 v43, v52, v53
	v_mul_f32_e32 v51, v45, v45
	v_cvt_pk_bf16_f32 v42, v54, v55
	global_store_dwordx4 v[56:57], v[40:43], off
	s_nop 0
	v_fmac_f32_e32 v51, v44, v44
	v_fmac_f32_e32 v51, v46, v46
	v_fmac_f32_e32 v51, v47, v47
	v_fmac_f32_e32 v51, v54, v54
	v_fmac_f32_e32 v51, v55, v55
	v_fmac_f32_e32 v51, v52, v52
	v_fmac_f32_e32 v51, v53, v53
	s_waitcnt vmcnt(15)
	s_nop 1
	v_mov_b32_e32 v40, v216
	v_mov_b32_e32 v41, v217
	v_mov_b32_e32 v42, v218
	v_mov_b32_e32 v43, v219
	v_lshlrev_b32_e32 v44, 16, v40
	v_and_b32_e32 v45, 0xffff0000, v40
	v_lshlrev_b32_e32 v40, 16, v41
	v_and_b32_e32 v41, 0xffff0000, v41
	v_lshlrev_b32_e32 v46, 16, v42
	v_and_b32_e32 v47, 0xffff0000, v42
	v_lshlrev_b32_e32 v42, 16, v43
	v_and_b32_e32 v43, 0xffff0000, v43
	v_pk_add_f32 v[38:39], v[38:39], v[40:41]
	v_pk_add_f32 v[36:37], v[36:37], v[44:45]
	v_pk_add_f32 v[40:41], v[34:35], v[42:43]
	v_pk_add_f32 v[42:43], v[32:33], v[46:47]
	v_cvt_pk_bf16_f32 v32, v36, v37
	v_cvt_pk_bf16_f32 v33, v38, v39
	v_cvt_pk_bf16_f32 v35, v40, v41
	s_nop 0
	v_cvt_pk_bf16_f32 v34, v42, v43
	global_store_dwordx4 v[48:49], v[32:35], off offset:256
	s_nop 1
	v_mul_f32_e32 v32, v37, v37
	v_fmac_f32_e32 v32, v36, v36
	v_fmac_f32_e32 v32, v38, v38
	v_fmac_f32_e32 v32, v39, v39
	v_fmac_f32_e32 v32, v42, v42
	v_fmac_f32_e32 v32, v43, v43
	v_fmac_f32_e32 v32, v40, v40
	v_fmac_f32_e32 v32, v41, v41
	v_add_f32_e32 v34, v51, v32
	v_lshl_add_u64 v[32:33], v[146:147], 0, s[18:19]
	s_mov_b32 s18, 0x50000
	v_add_co_u32_e32 v40, vcc, s18, v146
	s_mov_b64 s[18:19], 0x58000
	s_nop 0
	v_addc_co_u32_e32 v41, vcc, 0, v147, vcc
	s_nop 0
	s_waitcnt vmcnt(15)
	s_nop 1
	v_mov_b32_e32 v36, v220
	v_mov_b32_e32 v37, v221
	v_mov_b32_e32 v38, v222
	v_mov_b32_e32 v39, v223
	v_lshlrev_b32_e32 v42, 16, v36
	v_and_b32_e32 v43, 0xffff0000, v36
	v_lshlrev_b32_e32 v36, 16, v37
	v_and_b32_e32 v37, 0xffff0000, v37
	v_lshlrev_b32_e32 v44, 16, v38
	v_and_b32_e32 v45, 0xffff0000, v38
	v_lshlrev_b32_e32 v38, 16, v39
	v_and_b32_e32 v39, 0xffff0000, v39
	v_pk_add_f32 v[30:31], v[30:31], v[36:37]
	v_pk_add_f32 v[28:29], v[28:29], v[42:43]
	v_pk_add_f32 v[36:37], v[26:27], v[38:39]
	v_pk_add_f32 v[38:39], v[24:25], v[44:45]
	v_cvt_pk_bf16_f32 v24, v28, v29
	v_cvt_pk_bf16_f32 v25, v30, v31
	v_cvt_pk_bf16_f32 v27, v36, v37
	v_mul_f32_e32 v35, v29, v29
	v_cvt_pk_bf16_f32 v26, v38, v39
	global_store_dwordx4 v[40:41], v[24:27], off
	s_nop 0
	v_fmac_f32_e32 v35, v28, v28
	v_fmac_f32_e32 v35, v30, v30
	v_fmac_f32_e32 v35, v31, v31
	v_fmac_f32_e32 v35, v38, v38
	v_fmac_f32_e32 v35, v39, v39
	v_fmac_f32_e32 v35, v36, v36
	v_fmac_f32_e32 v35, v37, v37
	s_waitcnt vmcnt(15)
	s_nop 1
	v_mov_b32_e32 v24, v224
	v_mov_b32_e32 v25, v225
	v_mov_b32_e32 v26, v226
	v_mov_b32_e32 v27, v227
	v_lshlrev_b32_e32 v28, 16, v24
	v_and_b32_e32 v29, 0xffff0000, v24
	v_lshlrev_b32_e32 v24, 16, v25
	v_and_b32_e32 v25, 0xffff0000, v25
	v_lshlrev_b32_e32 v30, 16, v26
	v_and_b32_e32 v31, 0xffff0000, v26
	v_lshlrev_b32_e32 v26, 16, v27
	v_and_b32_e32 v27, 0xffff0000, v27
	v_pk_add_f32 v[22:23], v[22:23], v[24:25]
	v_pk_add_f32 v[20:21], v[20:21], v[28:29]
	v_pk_add_f32 v[24:25], v[18:19], v[26:27]
	v_pk_add_f32 v[26:27], v[16:17], v[30:31]
	v_cvt_pk_bf16_f32 v16, v20, v21
	v_cvt_pk_bf16_f32 v17, v22, v23
	v_cvt_pk_bf16_f32 v19, v24, v25
	s_nop 0
	v_cvt_pk_bf16_f32 v18, v26, v27
	global_store_dwordx4 v[32:33], v[16:19], off offset:256
	s_nop 1
	v_mul_f32_e32 v16, v21, v21
	v_fmac_f32_e32 v16, v20, v20
	v_fmac_f32_e32 v16, v22, v22
	v_fmac_f32_e32 v16, v23, v23
	v_fmac_f32_e32 v16, v26, v26
	v_fmac_f32_e32 v16, v27, v27
	v_fmac_f32_e32 v16, v24, v24
	v_fmac_f32_e32 v16, v25, v25
	v_add_f32_e32 v18, v35, v16
	v_lshl_add_u64 v[16:17], v[146:147], 0, s[18:19]
	s_mov_b32 s18, 0x58000
	v_add_co_u32_e32 v24, vcc, s18, v146
	s_nop 1
	v_addc_co_u32_e32 v25, vcc, 0, v147, vcc
	s_nop 0
	s_waitcnt vmcnt(15)
	s_nop 1
	v_mov_b32_e32 v20, v228
	v_mov_b32_e32 v21, v229
	v_mov_b32_e32 v22, v230
	v_mov_b32_e32 v23, v231
	v_lshlrev_b32_e32 v26, 16, v20
	v_and_b32_e32 v27, 0xffff0000, v20
	v_lshlrev_b32_e32 v20, 16, v21
	v_and_b32_e32 v21, 0xffff0000, v21
	v_lshlrev_b32_e32 v28, 16, v22
	v_and_b32_e32 v29, 0xffff0000, v22
	v_lshlrev_b32_e32 v22, 16, v23
	v_and_b32_e32 v23, 0xffff0000, v23
	v_pk_add_f32 v[14:15], v[14:15], v[20:21]
	v_pk_add_f32 v[20:21], v[12:13], v[26:27]
	v_pk_add_f32 v[22:23], v[10:11], v[22:23]
	v_pk_add_f32 v[26:27], v[8:9], v[28:29]
	v_cvt_pk_bf16_f32 v8, v20, v21
	v_cvt_pk_bf16_f32 v9, v14, v15
	v_cvt_pk_bf16_f32 v11, v22, v23
	v_mul_f32_e32 v12, v21, v21
	v_cvt_pk_bf16_f32 v10, v26, v27
	global_store_dwordx4 v[24:25], v[8:11], off
	s_nop 0
	v_fmac_f32_e32 v12, v20, v20
	v_fmac_f32_e32 v12, v14, v14
	v_fmac_f32_e32 v12, v15, v15
	v_fmac_f32_e32 v12, v26, v26
	v_fmac_f32_e32 v12, v27, v27
	v_fmac_f32_e32 v12, v22, v22
	v_fmac_f32_e32 v12, v23, v23
	s_waitcnt vmcnt(15)
	s_nop 1
	v_mov_b32_e32 v8, v232
	v_mov_b32_e32 v9, v233
	v_mov_b32_e32 v10, v234
	v_mov_b32_e32 v11, v235
	v_lshlrev_b32_e32 v14, 16, v8
	v_and_b32_e32 v15, 0xffff0000, v8
	v_lshlrev_b32_e32 v8, 16, v9
	v_and_b32_e32 v9, 0xffff0000, v9
	v_lshlrev_b32_e32 v20, 16, v10
	v_and_b32_e32 v21, 0xffff0000, v10
	v_lshlrev_b32_e32 v10, 16, v11
	v_and_b32_e32 v11, 0xffff0000, v11
	v_pk_add_f32 v[6:7], v[6:7], v[8:9]
	v_pk_add_f32 v[4:5], v[4:5], v[14:15]
	v_pk_add_f32 v[8:9], v[2:3], v[10:11]
	v_pk_add_f32 v[10:11], v[0:1], v[20:21]
	v_cvt_pk_bf16_f32 v0, v4, v5
	v_cvt_pk_bf16_f32 v1, v6, v7
	v_cvt_pk_bf16_f32 v3, v8, v9
	s_nop 0
	v_cvt_pk_bf16_f32 v2, v10, v11
	global_store_dwordx4 v[16:17], v[0:3], off offset:256
	ds_bpermute_b32 v2, v151, v98
	s_nop 0
	v_mul_f32_e32 v0, v5, v5
	v_fmac_f32_e32 v0, v4, v4
	v_fmac_f32_e32 v0, v6, v6
	v_fmac_f32_e32 v0, v7, v7
	v_fmac_f32_e32 v0, v10, v10
	v_fmac_f32_e32 v0, v11, v11
	v_fmac_f32_e32 v0, v8, v8
	v_fmac_f32_e32 v0, v9, v9
	v_add_f32_e32 v14, v12, v0
	ds_bpermute_b32 v0, v151, v112
	ds_bpermute_b32 v4, v151, v82
	ds_bpermute_b32 v6, v151, v66
	ds_bpermute_b32 v8, v151, v50
	ds_bpermute_b32 v10, v151, v34
	ds_bpermute_b32 v12, v151, v18
	ds_bpermute_b32 v15, v151, v14
	s_waitcnt lgkmcnt(0)
	v_add_f32_e32 v0, v112, v0
	v_add_f32_e32 v2, v98, v2
	v_add_f32_e32 v4, v82, v4
	v_add_f32_e32 v6, v66, v6
	v_add_f32_e32 v8, v50, v8
	v_add_f32_e32 v10, v34, v10
	v_add_f32_e32 v12, v18, v12
	v_add_f32_e32 v14, v14, v15
	ds_bpermute_b32 v1, v152, v0
	ds_bpermute_b32 v3, v152, v2
	ds_bpermute_b32 v5, v152, v4
	ds_bpermute_b32 v7, v152, v6
	ds_bpermute_b32 v9, v152, v8
	ds_bpermute_b32 v11, v152, v10
	ds_bpermute_b32 v13, v152, v12
	ds_bpermute_b32 v15, v152, v14
	s_and_saveexec_b64 s[48:49], s[2:3]
	s_cbranch_execz .LBB0_473
	s_waitcnt lgkmcnt(6)
	v_add_f32_e32 v2, v2, v3
	v_add_f32_e32 v0, v0, v1
	v_add_u32_e32 v1, s82, v153
	s_waitcnt lgkmcnt(2)
	v_add_f32_e32 v10, v10, v11
	v_add_f32_e32 v8, v8, v9
	v_add_f32_e32 v6, v6, v7
	v_add_f32_e32 v4, v4, v5
	ds_write2st64_b32 v1, v0, v2 offset1:1
	ds_write2st64_b32 v1, v4, v6 offset0:2 offset1:3
	v_add_u32_e32 v0, s82, v157
	s_waitcnt lgkmcnt(2)
	v_add_f32_e32 v14, v14, v15
	v_add_f32_e32 v12, v12, v13
	ds_write2st64_b32 v0, v8, v10 offset1:1
	ds_write2st64_b32 v0, v12, v14 offset0:2 offset1:3

.LBB0_817:
	ds_read_b128 v[128:131], v179
	ds_read_b128 v[132:135], v179 offset:1024
	ds_read_b128 v[136:139], v179 offset:2048
	ds_read_b128 v[140:143], v179 offset:3072
	s_add_u32 s44, s42, 0xfffc0080
	s_addc_u32 s45, s43, -1
	s_cmp_eq_u32 s60, 12
	s_cselect_b32 s47, s39, s45
	s_cselect_b32 s46, s38, s44
	s_cselect_b32 s45, s41, s19
	s_cselect_b32 s44, s40, s18
	v_lshl_add_u64 v[194:195], s[42:43], 0, v[152:153]
	s_add_i32 m0, s52, 0xc000
	ds_read_b128 v[158:161], v180
	ds_read_b128 v[162:165], v180 offset:1024
	ds_read_b128 v[182:185], v180 offset:2048
	ds_read_b128 v[186:189], v180 offset:3072
	ds_read_b128 v[190:193], v180 offset:4096
	ds_read_b128 v[200:203], v180 offset:5120
	ds_read_b128 v[204:207], v180 offset:6144
	ds_read_b128 v[208:211], v180 offset:7168
	global_load_lds_dwordx4 v[194:195], off
	v_lshl_add_u64 v[194:195], s[42:43], 0, v[154:155]
	s_add_i32 m0, s52, 0xe000
	s_nop 0
	global_load_lds_dwordx4 v[194:195], off
	s_waitcnt lgkmcnt(8)
	s_barrier
	s_waitcnt lgkmcnt(0)
	s_setprio 1
	s_waitcnt lgkmcnt(0)
	v_mfma_f32_16x16x32_bf16 v[124:127], v[128:131], v[158:161], v[124:127]
	v_mfma_f32_16x16x32_bf16 v[120:123], v[136:139], v[158:161], v[120:123]
	v_mfma_f32_16x16x32_bf16 v[116:119], v[128:131], v[182:185], v[116:119]
	v_mfma_f32_16x16x32_bf16 v[108:111], v[136:139], v[182:185], v[108:111]
	v_mfma_f32_16x16x32_bf16 v[92:95], v[128:131], v[190:193], v[92:95]
	v_mfma_f32_16x16x32_bf16 v[88:91], v[136:139], v[190:193], v[88:91]
	v_mfma_f32_16x16x32_bf16 v[76:79], v[128:131], v[204:207], v[76:79]
	v_mfma_f32_16x16x32_bf16 v[72:75], v[136:139], v[204:207], v[72:75]
	v_mfma_f32_16x16x32_bf16 v[124:127], v[132:135], v[162:165], v[124:127]
	v_mfma_f32_16x16x32_bf16 v[120:123], v[140:143], v[162:165], v[120:123]
	v_mfma_f32_16x16x32_bf16 v[116:119], v[132:135], v[186:189], v[116:119]
	v_mfma_f32_16x16x32_bf16 v[108:111], v[140:143], v[186:189], v[108:111]
	v_mfma_f32_16x16x32_bf16 v[92:95], v[132:135], v[200:203], v[92:95]
	v_mfma_f32_16x16x32_bf16 v[88:91], v[140:143], v[200:203], v[88:91]
	v_mfma_f32_16x16x32_bf16 v[76:79], v[132:135], v[208:211], v[76:79]
	v_mfma_f32_16x16x32_bf16 v[72:75], v[140:143], v[208:211], v[72:75]
	s_setprio 0
	s_barrier
	s_add_i32 s81, s73, s51
	v_lshl_add_u64 v[194:195], s[44:45], 0, v[146:147]
	s_mov_b32 m0, s81
	ds_read_b128 v[212:215], v181
	ds_read_b128 v[216:219], v181 offset:1024
	ds_read_b128 v[220:223], v181 offset:2048
	ds_read_b128 v[224:227], v181 offset:3072
	global_load_lds_dwordx4 v[194:195], off
	v_lshl_add_u64 v[228:229], s[44:45], 0, v[150:151]
	s_add_i32 m0, s81, 0x2000
	s_nop 0
	global_load_lds_dwordx4 v[228:229], off
	s_barrier
	s_waitcnt lgkmcnt(0)
	s_setprio 1
	s_waitcnt lgkmcnt(0)
	v_mfma_f32_16x16x32_bf16 v[112:115], v[212:215], v[158:161], v[112:115]
	v_mfma_f32_16x16x32_bf16 v[104:107], v[220:223], v[158:161], v[104:107]
	v_mfma_f32_16x16x32_bf16 v[100:103], v[212:215], v[182:185], v[100:103]
	v_mfma_f32_16x16x32_bf16 v[96:99], v[220:223], v[182:185], v[96:99]
	v_mfma_f32_16x16x32_bf16 v[84:87], v[212:215], v[190:193], v[84:87]
	v_mfma_f32_16x16x32_bf16 v[80:83], v[220:223], v[190:193], v[80:83]
	v_mfma_f32_16x16x32_bf16 v[68:71], v[212:215], v[204:207], v[68:71]
	v_mfma_f32_16x16x32_bf16 v[64:67], v[220:223], v[204:207], v[64:67]
	v_mfma_f32_16x16x32_bf16 v[112:115], v[216:219], v[162:165], v[112:115]
	v_mfma_f32_16x16x32_bf16 v[104:107], v[224:227], v[162:165], v[104:107]
	v_mfma_f32_16x16x32_bf16 v[100:103], v[216:219], v[186:189], v[100:103]
	v_mfma_f32_16x16x32_bf16 v[96:99], v[224:227], v[186:189], v[96:99]
	v_mfma_f32_16x16x32_bf16 v[84:87], v[216:219], v[200:203], v[84:87]
	v_mfma_f32_16x16x32_bf16 v[80:83], v[224:227], v[200:203], v[80:83]
	v_mfma_f32_16x16x32_bf16 v[68:71], v[216:219], v[208:211], v[68:71]
	v_mfma_f32_16x16x32_bf16 v[64:67], v[224:227], v[208:211], v[64:67]
	s_setprio 0
	s_mov_b32 m0, s52
	v_lshl_add_u64 v[230:231], s[46:47], 0, v[144:145]
	s_barrier
	ds_read_b128 v[158:161], v180 offset:16384
	ds_read_b128 v[162:165], v180 offset:17408
	ds_read_b128 v[182:185], v180 offset:18432
	ds_read_b128 v[186:189], v180 offset:19456
	ds_read_b128 v[190:193], v180 offset:20480
	ds_read_b128 v[200:203], v180 offset:21504
	ds_read_b128 v[204:207], v180 offset:22528
	ds_read_b128 v[208:211], v180 offset:23552
	global_load_lds_dwordx4 v[230:231], off
	v_lshl_add_u64 v[232:233], s[46:47], 0, v[148:149]
	s_mov_b32 m0, s53
	s_nop 0
	global_load_lds_dwordx4 v[232:233], off
	s_barrier
	s_waitcnt lgkmcnt(0)
	s_setprio 1
	s_waitcnt lgkmcnt(0)
	v_mfma_f32_16x16x32_bf16 v[60:63], v[128:131], v[158:161], v[60:63]
	v_mfma_f32_16x16x32_bf16 v[56:59], v[136:139], v[158:161], v[56:59]
	v_mfma_f32_16x16x32_bf16 v[44:47], v[128:131], v[182:185], v[44:47]
	v_mfma_f32_16x16x32_bf16 v[40:43], v[136:139], v[182:185], v[40:43]
	v_mfma_f32_16x16x32_bf16 v[28:31], v[128:131], v[190:193], v[28:31]
	v_mfma_f32_16x16x32_bf16 v[24:27], v[136:139], v[190:193], v[24:27]
	v_mfma_f32_16x16x32_bf16 v[16:19], v[128:131], v[204:207], v[16:19]
	v_mfma_f32_16x16x32_bf16 v[8:11], v[136:139], v[204:207], v[8:11]
	v_mfma_f32_16x16x32_bf16 v[60:63], v[132:135], v[162:165], v[60:63]
	v_mfma_f32_16x16x32_bf16 v[56:59], v[140:143], v[162:165], v[56:59]
	v_mfma_f32_16x16x32_bf16 v[44:47], v[132:135], v[186:189], v[44:47]
	v_mfma_f32_16x16x32_bf16 v[40:43], v[140:143], v[186:189], v[40:43]
	v_mfma_f32_16x16x32_bf16 v[28:31], v[132:135], v[200:203], v[28:31]
	v_mfma_f32_16x16x32_bf16 v[24:27], v[140:143], v[200:203], v[24:27]
	v_mfma_f32_16x16x32_bf16 v[16:19], v[132:135], v[208:211], v[16:19]
	v_mfma_f32_16x16x32_bf16 v[8:11], v[140:143], v[208:211], v[8:11]
	s_setprio 0
	s_barrier
	s_add_u32 s82, s44, 0x40000
	s_addc_u32 s83, s45, 0
	s_add_i32 s81, s74, s51
	v_lshl_add_u64 v[128:129], s[82:83], 0, v[146:147]
	s_mov_b32 m0, s81
	s_nop 0
	global_load_lds_dwordx4 v[128:129], off
	v_lshl_add_u64 v[128:129], s[82:83], 0, v[150:151]
	s_add_i32 m0, s81, 0x2000
	s_nop 0
	global_load_lds_dwordx4 v[128:129], off
	s_waitcnt vmcnt(6)
	s_barrier
	s_setprio 1
	v_mfma_f32_16x16x32_bf16 v[52:55], v[212:215], v[158:161], v[52:55]
	v_mfma_f32_16x16x32_bf16 v[48:51], v[220:223], v[158:161], v[48:51]
	v_mfma_f32_16x16x32_bf16 v[36:39], v[212:215], v[182:185], v[36:39]
	v_mfma_f32_16x16x32_bf16 v[32:35], v[220:223], v[182:185], v[32:35]
	v_mfma_f32_16x16x32_bf16 v[20:23], v[212:215], v[190:193], v[20:23]
	v_mfma_f32_16x16x32_bf16 v[12:15], v[220:223], v[190:193], v[12:15]
	v_mfma_f32_16x16x32_bf16 v[4:7], v[212:215], v[204:207], v[4:7]
	v_mfma_f32_16x16x32_bf16 v[0:3], v[220:223], v[204:207], v[0:3]
	v_mfma_f32_16x16x32_bf16 v[52:55], v[216:219], v[162:165], v[52:55]
	v_mfma_f32_16x16x32_bf16 v[48:51], v[224:227], v[162:165], v[48:51]
	v_mfma_f32_16x16x32_bf16 v[36:39], v[216:219], v[186:189], v[36:39]
	v_mfma_f32_16x16x32_bf16 v[32:35], v[224:227], v[186:189], v[32:35]
	v_mfma_f32_16x16x32_bf16 v[20:23], v[216:219], v[200:203], v[20:23]
	v_mfma_f32_16x16x32_bf16 v[12:15], v[224:227], v[200:203], v[12:15]
	v_mfma_f32_16x16x32_bf16 v[4:7], v[216:219], v[208:211], v[4:7]
	v_mfma_f32_16x16x32_bf16 v[0:3], v[224:227], v[208:211], v[0:3]
	s_setprio 0
	s_add_i32 s81, 0, 0x18000
	v_add_u32_e32 v140, s81, v167
	s_barrier
	ds_read_b128 v[128:131], v140
	ds_read_b128 v[132:135], v140 offset:1024
	ds_read_b128 v[136:139], v140 offset:2048
	ds_read_b128 v[140:143], v140 offset:3072
	s_add_u32 s46, s46, 0x40000
	s_addc_u32 s47, s47, 0
	s_mov_b32 m0, s62
	v_lshl_add_u64 v[212:213], s[46:47], 0, v[144:145]
	ds_read_b128 v[158:161], v180 offset:32768
	ds_read_b128 v[162:165], v180 offset:33792
	ds_read_b128 v[182:185], v180 offset:34816
	ds_read_b128 v[186:189], v180 offset:35840
	ds_read_b128 v[190:193], v180 offset:36864
	ds_read_b128 v[200:203], v180 offset:37888
	ds_read_b128 v[204:207], v180 offset:38912
	ds_read_b128 v[208:211], v180 offset:39936
	global_load_lds_dwordx4 v[212:213], off
	v_lshl_add_u64 v[212:213], s[46:47], 0, v[148:149]
	s_mov_b32 m0, s63
	s_nop 0
	global_load_lds_dwordx4 v[212:213], off
	s_waitcnt lgkmcnt(8)
	s_barrier
	s_waitcnt lgkmcnt(0)
	s_setprio 1
	s_waitcnt lgkmcnt(0)
	v_mfma_f32_16x16x32_bf16 v[124:127], v[128:131], v[158:161], v[124:127]
	v_mfma_f32_16x16x32_bf16 v[120:123], v[136:139], v[158:161], v[120:123]
	v_mfma_f32_16x16x32_bf16 v[116:119], v[128:131], v[182:185], v[116:119]
	v_mfma_f32_16x16x32_bf16 v[108:111], v[136:139], v[182:185], v[108:111]
	v_mfma_f32_16x16x32_bf16 v[92:95], v[128:131], v[190:193], v[92:95]
	v_mfma_f32_16x16x32_bf16 v[88:91], v[136:139], v[190:193], v[88:91]
	v_mfma_f32_16x16x32_bf16 v[76:79], v[128:131], v[204:207], v[76:79]
	v_mfma_f32_16x16x32_bf16 v[72:75], v[136:139], v[204:207], v[72:75]
	v_mfma_f32_16x16x32_bf16 v[124:127], v[132:135], v[162:165], v[124:127]
	v_mfma_f32_16x16x32_bf16 v[120:123], v[140:143], v[162:165], v[120:123]
	v_mfma_f32_16x16x32_bf16 v[116:119], v[132:135], v[186:189], v[116:119]
	v_mfma_f32_16x16x32_bf16 v[108:111], v[140:143], v[186:189], v[108:111]
	v_mfma_f32_16x16x32_bf16 v[92:95], v[132:135], v[200:203], v[92:95]
	v_mfma_f32_16x16x32_bf16 v[88:91], v[140:143], v[200:203], v[88:91]
	v_mfma_f32_16x16x32_bf16 v[76:79], v[132:135], v[208:211], v[76:79]
	v_mfma_f32_16x16x32_bf16 v[72:75], v[140:143], v[208:211], v[72:75]
	s_setprio 0
	s_barrier
	s_add_i32 s46, 0, 0x1c000
	s_add_i32 s47, s81, s51
	v_add_u32_e32 v224, s46, v167
	v_lshl_add_u64 v[194:195], v[194:195], 0, s[22:23]
	s_mov_b32 m0, s47
	ds_read_b128 v[212:215], v224
	ds_read_b128 v[216:219], v224 offset:1024
	ds_read_b128 v[220:223], v224 offset:2048
	ds_read_b128 v[224:227], v224 offset:3072
	global_load_lds_dwordx4 v[194:195], off
	v_lshl_add_u64 v[194:195], v[228:229], 0, s[22:23]
	s_add_i32 m0, s47, 0x2000
	s_nop 0
	global_load_lds_dwordx4 v[194:195], off
	s_barrier
	s_waitcnt lgkmcnt(0)
	s_setprio 1
	s_waitcnt lgkmcnt(0)
	v_mfma_f32_16x16x32_bf16 v[112:115], v[212:215], v[158:161], v[112:115]
	v_mfma_f32_16x16x32_bf16 v[104:107], v[220:223], v[158:161], v[104:107]
	v_mfma_f32_16x16x32_bf16 v[100:103], v[212:215], v[182:185], v[100:103]
	v_mfma_f32_16x16x32_bf16 v[96:99], v[220:223], v[182:185], v[96:99]
	v_mfma_f32_16x16x32_bf16 v[84:87], v[212:215], v[190:193], v[84:87]
	v_mfma_f32_16x16x32_bf16 v[80:83], v[220:223], v[190:193], v[80:83]
	v_mfma_f32_16x16x32_bf16 v[68:71], v[212:215], v[204:207], v[68:71]
	v_mfma_f32_16x16x32_bf16 v[64:67], v[220:223], v[204:207], v[64:67]
	v_mfma_f32_16x16x32_bf16 v[112:115], v[216:219], v[162:165], v[112:115]
	v_mfma_f32_16x16x32_bf16 v[104:107], v[224:227], v[162:165], v[104:107]
	v_mfma_f32_16x16x32_bf16 v[100:103], v[216:219], v[186:189], v[100:103]
	v_mfma_f32_16x16x32_bf16 v[96:99], v[224:227], v[186:189], v[96:99]
	v_mfma_f32_16x16x32_bf16 v[84:87], v[216:219], v[200:203], v[84:87]
	v_mfma_f32_16x16x32_bf16 v[80:83], v[224:227], v[200:203], v[80:83]
	v_mfma_f32_16x16x32_bf16 v[68:71], v[216:219], v[208:211], v[68:71]
	v_mfma_f32_16x16x32_bf16 v[64:67], v[224:227], v[208:211], v[64:67]
	s_setprio 0
	s_mov_b32 m0, s68
	v_lshl_add_u64 v[194:195], v[230:231], 0, s[22:23]
	s_barrier
	ds_read_b128 v[158:161], v180 offset:49152
	ds_read_b128 v[162:165], v180 offset:50176
	ds_read_b128 v[182:185], v180 offset:51200
	ds_read_b128 v[186:189], v180 offset:52224
	ds_read_b128 v[190:193], v180 offset:53248
	ds_read_b128 v[200:203], v180 offset:54272
	ds_read_b128 v[204:207], v180 offset:55296
	ds_read_b128 v[208:211], v180 offset:56320
	global_load_lds_dwordx4 v[194:195], off
	v_lshl_add_u64 v[194:195], v[232:233], 0, s[22:23]
	s_mov_b32 m0, s69
	s_nop 0
	global_load_lds_dwordx4 v[194:195], off
	s_barrier
	s_waitcnt lgkmcnt(0)
	s_setprio 1
	s_waitcnt lgkmcnt(0)
	v_mfma_f32_16x16x32_bf16 v[60:63], v[128:131], v[158:161], v[60:63]
	v_mfma_f32_16x16x32_bf16 v[56:59], v[136:139], v[158:161], v[56:59]
	v_mfma_f32_16x16x32_bf16 v[44:47], v[128:131], v[182:185], v[44:47]
	v_mfma_f32_16x16x32_bf16 v[40:43], v[136:139], v[182:185], v[40:43]
	v_mfma_f32_16x16x32_bf16 v[28:31], v[128:131], v[190:193], v[28:31]
	v_mfma_f32_16x16x32_bf16 v[24:27], v[136:139], v[190:193], v[24:27]
	v_mfma_f32_16x16x32_bf16 v[16:19], v[128:131], v[204:207], v[16:19]
	v_mfma_f32_16x16x32_bf16 v[8:11], v[136:139], v[204:207], v[8:11]
	v_mfma_f32_16x16x32_bf16 v[60:63], v[132:135], v[162:165], v[60:63]
	v_mfma_f32_16x16x32_bf16 v[56:59], v[140:143], v[162:165], v[56:59]
	v_mfma_f32_16x16x32_bf16 v[44:47], v[132:135], v[186:189], v[44:47]
	v_mfma_f32_16x16x32_bf16 v[40:43], v[140:143], v[186:189], v[40:43]
	v_mfma_f32_16x16x32_bf16 v[28:31], v[132:135], v[200:203], v[28:31]
	v_mfma_f32_16x16x32_bf16 v[24:27], v[140:143], v[200:203], v[24:27]
	v_mfma_f32_16x16x32_bf16 v[16:19], v[132:135], v[208:211], v[16:19]
	v_mfma_f32_16x16x32_bf16 v[8:11], v[140:143], v[208:211], v[8:11]
	s_setprio 0
	s_barrier
	s_add_u32 s44, s44, 0x40080
	s_addc_u32 s45, s45, 0
	s_add_i32 s46, s46, s51
	v_lshl_add_u64 v[128:129], s[44:45], 0, v[146:147]
	s_mov_b32 m0, s46
	s_nop 0
	global_load_lds_dwordx4 v[128:129], off
	v_lshl_add_u64 v[128:129], s[44:45], 0, v[150:151]
	s_add_i32 m0, s46, 0x2000
	s_nop 0
	global_load_lds_dwordx4 v[128:129], off
	s_waitcnt vmcnt(6)
	s_barrier
	s_setprio 1
	v_mfma_f32_16x16x32_bf16 v[52:55], v[212:215], v[158:161], v[52:55]
	v_mfma_f32_16x16x32_bf16 v[48:51], v[220:223], v[158:161], v[48:51]
	v_mfma_f32_16x16x32_bf16 v[36:39], v[212:215], v[182:185], v[36:39]
	v_mfma_f32_16x16x32_bf16 v[32:35], v[220:223], v[182:185], v[32:35]
	v_mfma_f32_16x16x32_bf16 v[20:23], v[212:215], v[190:193], v[20:23]
	v_mfma_f32_16x16x32_bf16 v[12:15], v[220:223], v[190:193], v[12:15]
	v_mfma_f32_16x16x32_bf16 v[4:7], v[212:215], v[204:207], v[4:7]
	v_mfma_f32_16x16x32_bf16 v[0:3], v[220:223], v[204:207], v[0:3]
	v_mfma_f32_16x16x32_bf16 v[52:55], v[216:219], v[162:165], v[52:55]
	v_mfma_f32_16x16x32_bf16 v[48:51], v[224:227], v[162:165], v[48:51]
	v_mfma_f32_16x16x32_bf16 v[36:39], v[216:219], v[186:189], v[36:39]
	v_mfma_f32_16x16x32_bf16 v[32:35], v[224:227], v[186:189], v[32:35]
	v_mfma_f32_16x16x32_bf16 v[20:23], v[216:219], v[200:203], v[20:23]
	v_mfma_f32_16x16x32_bf16 v[12:15], v[224:227], v[200:203], v[12:15]
	v_mfma_f32_16x16x32_bf16 v[4:7], v[216:219], v[208:211], v[4:7]
	v_mfma_f32_16x16x32_bf16 v[0:3], v[224:227], v[208:211], v[0:3]
	s_setprio 0
	s_add_i32 s60, s60, 2
	s_add_u32 s42, s42, 0x100
	s_addc_u32 s43, s43, 0
	s_add_u32 s18, s18, 0x100
	s_addc_u32 s19, s19, 0
	s_cmp_gt_u32 s60, 13
	s_barrier
	s_cbranch_scc0 .LBB0_817
	v_add_u32_e32 v158, s33, v166
	v_ashrrev_i32_e32 v159, 31, v158
	v_readlane_b32 s18, v254, 56
	v_add_u32_e32 v128, s67, v168
	v_lshlrev_b64 v[130:131], 11, v[158:159]
	v_readlane_b32 s19, v254, 57
	v_ashrrev_i32_e32 v129, 31, v128
	s_nop 0
	v_lshl_add_u64 v[130:131], s[18:19], 0, v[130:131]
	v_lshl_add_u64 v[160:161], v[128:129], 1, v[130:131]
	v_add_co_u32_e32 v190, vcc, s71, v160
	global_load_dwordx4 v[132:135], v[160:161], off
	global_load_dwordx4 v[140:143], v[160:161], off offset:256
	v_addc_co_u32_e32 v191, vcc, 0, v161, vcc
	global_load_dwordx4 v[182:185], v[190:191], off
	v_lshl_add_u64 v[192:193], v[160:161], 0, s[24:25]
	global_load_dwordx4 v[186:189], v[192:193], off offset:256
	s_mov_b32 s18, 0x10000
	v_add_co_u32_e32 v164, vcc, s18, v160
	v_lshl_add_u64 v[162:163], v[160:161], 0, s[26:27]
	s_nop 0
	v_addc_co_u32_e32 v165, vcc, 0, v161, vcc
	global_load_dwordx4 v[136:139], v[164:165], off
	global_load_dwordx4 v[128:131], v[162:163], off offset:256
	s_mov_b32 s98, s70
	s_mov_b32 s99, 0
	v_lshl_add_u64 v[246:247], v[160:161], 0, s[98:99]
	global_load_dwordx4 v[206:209], v[246:247], off
	v_lshl_add_u64 v[246:247], v[160:161], 0, s[28:29]
	global_load_dwordx4 v[210:213], v[246:247], off offset:256
	s_mov_b32 s98, s75
	s_mov_b32 s99, 0
	v_lshl_add_u64 v[246:247], v[160:161], 0, s[98:99]
	global_load_dwordx4 v[214:217], v[246:247], off
	v_lshl_add_u64 v[246:247], v[160:161], 0, s[20:21]
	global_load_dwordx4 v[218:221], v[246:247], off offset:256
	s_mov_b32 s98, s76
	s_mov_b32 s99, 0
	v_lshl_add_u64 v[246:247], v[160:161], 0, s[98:99]
	global_load_dwordx4 v[222:225], v[246:247], off
	v_lshl_add_u64 v[246:247], v[160:161], 0, s[30:31]
	global_load_dwordx4 v[226:229], v[246:247], off offset:256
	s_mov_b32 s98, s77
	s_mov_b32 s99, 0
	v_lshl_add_u64 v[246:247], v[160:161], 0, s[98:99]
	global_load_dwordx4 v[230:233], v[246:247], off
	v_lshl_add_u64 v[246:247], v[160:161], 0, s[34:35]
	global_load_dwordx4 v[234:237], v[246:247], off offset:256
	s_mov_b32 s98, s78
	s_mov_b32 s99, 0
	v_lshl_add_u64 v[246:247], v[160:161], 0, s[98:99]
	global_load_dwordx4 v[238:241], v[246:247], off
	v_lshl_add_u64 v[246:247], v[160:161], 0, s[36:37]
	global_load_dwordx4 v[242:245], v[246:247], off offset:256
	s_waitcnt vmcnt(10)
	v_lshlrev_b32_e32 v194, 16, v132
	v_and_b32_e32 v195, 0xffff0000, v132
	v_lshlrev_b32_e32 v200, 16, v134
	v_and_b32_e32 v201, 0xffff0000, v134
	v_pk_add_f32 v[124:125], v[124:125], v[194:195]
	v_lshlrev_b32_e32 v194, 16, v182
	v_and_b32_e32 v195, 0xffff0000, v182
	v_pk_add_f32 v[120:121], v[120:121], v[200:201]
	v_lshlrev_b32_e32 v182, 16, v183
	v_and_b32_e32 v183, 0xffff0000, v183
	v_lshlrev_b32_e32 v200, 16, v184
	v_and_b32_e32 v201, 0xffff0000, v184
	v_lshlrev_b32_e32 v184, 16, v185
	v_and_b32_e32 v185, 0xffff0000, v185
	v_pk_add_f32 v[116:117], v[116:117], v[194:195]
	v_pk_add_f32 v[118:119], v[118:119], v[182:183]
	v_pk_add_f32 v[182:183], v[110:111], v[184:185]
	v_mul_f32_e32 v111, v117, v117
	v_fmac_f32_e32 v111, v116, v116
	v_lshlrev_b32_e32 v132, 16, v133
	v_and_b32_e32 v133, 0xffff0000, v133
	v_lshlrev_b32_e32 v202, 16, v140
	v_and_b32_e32 v203, 0xffff0000, v140
	v_lshlrev_b32_e32 v140, 16, v141
	v_and_b32_e32 v141, 0xffff0000, v141
	v_lshlrev_b32_e32 v204, 16, v142
	v_and_b32_e32 v205, 0xffff0000, v142
	v_lshlrev_b32_e32 v142, 16, v143
	v_and_b32_e32 v143, 0xffff0000, v143
	v_fmac_f32_e32 v111, v118, v118
	v_lshlrev_b32_e32 v134, 16, v135
	v_and_b32_e32 v135, 0xffff0000, v135
	v_pk_add_f32 v[126:127], v[126:127], v[132:133]
	v_pk_add_f32 v[132:133], v[114:115], v[140:141]
	v_pk_add_f32 v[140:141], v[106:107], v[142:143]
	v_cvt_pk_bf16_f32 v106, v120, v121
	v_pk_add_f32 v[108:109], v[108:109], v[200:201]
	v_fmac_f32_e32 v111, v119, v119
	v_pk_add_f32 v[122:123], v[122:123], v[134:135]
	v_pk_add_f32 v[134:135], v[112:113], v[202:203]
	v_pk_add_f32 v[142:143], v[104:105], v[204:205]
	v_cvt_pk_bf16_f32 v104, v124, v125
	v_cvt_pk_bf16_f32 v105, v126, v127
	v_cvt_pk_bf16_f32 v107, v122, v123
	v_cvt_pk_bf16_f32 v112, v134, v135
	v_cvt_pk_bf16_f32 v113, v132, v133
	s_nop 0
	v_cvt_pk_bf16_f32 v114, v142, v143
	v_cvt_pk_bf16_f32 v115, v140, v141
	global_store_dwordx4 v[160:161], v[104:107], off
	v_fmac_f32_e32 v111, v108, v108
	global_store_dwordx4 v[160:161], v[112:115], off offset:256
	v_cvt_pk_bf16_f32 v106, v108, v109
	v_add_co_u32_e32 v108, vcc, s70, v160
	v_cvt_pk_bf16_f32 v104, v116, v117
	v_cvt_pk_bf16_f32 v105, v118, v119
	v_cvt_pk_bf16_f32 v107, v182, v183
	v_fmac_f32_e32 v111, v109, v109
	v_lshlrev_b32_e32 v112, 16, v186
	v_and_b32_e32 v113, 0xffff0000, v186
	v_lshlrev_b32_e32 v114, 16, v187
	v_and_b32_e32 v115, 0xffff0000, v187
	v_lshlrev_b32_e32 v116, 16, v188
	v_addc_co_u32_e32 v109, vcc, 0, v161, vcc
	v_and_b32_e32 v117, 0xffff0000, v188
	global_store_dwordx4 v[190:191], v[104:107], off
	s_nop 0
	v_lshlrev_b32_e32 v118, 16, v189
	v_and_b32_e32 v119, 0xffff0000, v189
	v_pk_add_f32 v[102:103], v[102:103], v[114:115]
	v_pk_add_f32 v[100:101], v[100:101], v[112:113]
	v_pk_add_f32 v[114:115], v[96:97], v[116:117]
	v_cvt_pk_bf16_f32 v96, v100, v101
	v_pk_add_f32 v[112:113], v[98:99], v[118:119]
	v_cvt_pk_bf16_f32 v97, v102, v103
	v_cvt_pk_bf16_f32 v98, v114, v115
	v_fmac_f32_e32 v111, v182, v182
	v_cvt_pk_bf16_f32 v99, v112, v113
	global_store_dwordx4 v[192:193], v[96:99], off offset:256
	v_fmac_f32_e32 v111, v183, v183
	v_lshlrev_b32_e32 v116, 16, v138
	v_mul_f32_e32 v96, v101, v101
	v_fmac_f32_e32 v96, v100, v100
	v_fmac_f32_e32 v96, v102, v102
	v_fmac_f32_e32 v96, v103, v103
	v_fmac_f32_e32 v96, v114, v114
	v_fmac_f32_e32 v96, v115, v115
	v_fmac_f32_e32 v96, v112, v112
	v_fmac_f32_e32 v96, v113, v113
	v_lshl_add_u64 v[100:101], v[160:161], 0, s[28:29]
	v_add_f32_e32 v102, v111, v96
	s_nop 0
	v_lshlrev_b32_e32 v112, 16, v136
	v_and_b32_e32 v113, 0xffff0000, v136
	v_lshlrev_b32_e32 v114, 16, v137
	v_and_b32_e32 v115, 0xffff0000, v137
	v_and_b32_e32 v117, 0xffff0000, v138
	v_lshlrev_b32_e32 v118, 16, v139
	v_and_b32_e32 v119, 0xffff0000, v139
	v_pk_add_f32 v[94:95], v[94:95], v[114:115]
	v_pk_add_f32 v[92:93], v[92:93], v[112:113]
	v_pk_add_f32 v[114:115], v[88:89], v[116:117]
	v_cvt_pk_bf16_f32 v88, v92, v93
	v_pk_add_f32 v[112:113], v[90:91], v[118:119]
	v_cvt_pk_bf16_f32 v89, v94, v95
	v_cvt_pk_bf16_f32 v90, v114, v115
	v_mul_f32_e32 v103, v93, v93
	v_cvt_pk_bf16_f32 v91, v112, v113
	global_store_dwordx4 v[164:165], v[88:91], off
	v_fmac_f32_e32 v103, v92, v92
	v_fmac_f32_e32 v103, v94, v94
	v_add_co_u32_e32 v88, vcc, s75, v160
	v_fmac_f32_e32 v103, v95, v95
	s_nop 0
	v_addc_co_u32_e32 v89, vcc, 0, v161, vcc
	s_nop 0
	v_fmac_f32_e32 v103, v114, v114
	v_fmac_f32_e32 v103, v115, v115
	v_fmac_f32_e32 v103, v112, v112
	v_fmac_f32_e32 v103, v113, v113
	v_lshlrev_b32_e32 v94, 16, v128
	v_and_b32_e32 v95, 0xffff0000, v128
	v_lshlrev_b32_e32 v112, 16, v129
	v_and_b32_e32 v113, 0xffff0000, v129
	v_lshlrev_b32_e32 v114, 16, v130
	v_and_b32_e32 v115, 0xffff0000, v130
	v_lshlrev_b32_e32 v116, 16, v131
	v_and_b32_e32 v117, 0xffff0000, v131
	v_pk_add_f32 v[86:87], v[86:87], v[112:113]
	v_pk_add_f32 v[84:85], v[84:85], v[94:95]
	v_pk_add_f32 v[112:113], v[80:81], v[114:115]
	v_cvt_pk_bf16_f32 v80, v84, v85
	v_pk_add_f32 v[94:95], v[82:83], v[116:117]
	v_cvt_pk_bf16_f32 v81, v86, v87
	v_cvt_pk_bf16_f32 v82, v112, v113
	v_mul_f32_e32 v125, v125, v125
	v_cvt_pk_bf16_f32 v83, v94, v95
	global_store_dwordx4 v[162:163], v[80:83], off offset:256
	v_mul_f32_e32 v135, v135, v135
	v_fmac_f32_e32 v125, v124, v124
	v_mul_f32_e32 v80, v85, v85
	v_fmac_f32_e32 v80, v84, v84
	v_fmac_f32_e32 v80, v86, v86
	v_fmac_f32_e32 v80, v87, v87
	v_fmac_f32_e32 v80, v112, v112
	v_fmac_f32_e32 v80, v113, v113
	v_fmac_f32_e32 v80, v94, v94
	v_fmac_f32_e32 v80, v95, v95
	v_lshl_add_u64 v[84:85], v[160:161], 0, s[20:21]
	v_add_f32_e32 v86, v103, v80
	s_nop 0
	s_waitcnt vmcnt(12)
	s_nop 1
	v_mov_b32_e32 v104, v206
	v_mov_b32_e32 v105, v207
	v_mov_b32_e32 v106, v208
	v_mov_b32_e32 v107, v209
	v_mov_b32_e32 v96, v210
	v_mov_b32_e32 v97, v211
	v_mov_b32_e32 v98, v212
	v_mov_b32_e32 v99, v213
	v_mov_b32_e32 v90, v214
	v_mov_b32_e32 v91, v215
	v_mov_b32_e32 v92, v216
	v_mov_b32_e32 v93, v217
	v_mov_b32_e32 v80, v218
	v_mov_b32_e32 v81, v219
	v_mov_b32_e32 v82, v220
	v_mov_b32_e32 v83, v221
	v_lshlrev_b32_e32 v94, 16, v104
	v_and_b32_e32 v95, 0xffff0000, v104
	v_pk_add_f32 v[76:77], v[76:77], v[94:95]
	v_lshlrev_b32_e32 v104, 16, v105
	v_and_b32_e32 v105, 0xffff0000, v105
	v_mul_f32_e32 v87, v77, v77
	v_pk_add_f32 v[78:79], v[78:79], v[104:105]
	v_fmac_f32_e32 v87, v76, v76
	v_lshlrev_b32_e32 v112, 16, v106
	v_and_b32_e32 v113, 0xffff0000, v106
	v_fmac_f32_e32 v87, v78, v78
	v_pk_add_f32 v[104:105], v[72:73], v[112:113]
	v_fmac_f32_e32 v87, v79, v79
	v_lshlrev_b32_e32 v106, 16, v107
	v_and_b32_e32 v107, 0xffff0000, v107
	v_fmac_f32_e32 v87, v104, v104
	v_pk_add_f32 v[94:95], v[74:75], v[106:107]
	v_fmac_f32_e32 v87, v105, v105
	v_fmac_f32_e32 v87, v94, v94
	v_cvt_pk_bf16_f32 v73, v78, v79
	v_cvt_pk_bf16_f32 v75, v94, v95
	v_fmac_f32_e32 v87, v95, v95
	v_lshlrev_b32_e32 v78, 16, v96
	v_and_b32_e32 v79, 0xffff0000, v96
	v_lshlrev_b32_e32 v94, 16, v97
	v_and_b32_e32 v95, 0xffff0000, v97
	v_lshlrev_b32_e32 v96, 16, v98
	v_and_b32_e32 v97, 0xffff0000, v98
	v_cvt_pk_bf16_f32 v72, v76, v77
	v_add_co_u32_e32 v76, vcc, s76, v160
	v_lshlrev_b32_e32 v98, 16, v99
	v_and_b32_e32 v99, 0xffff0000, v99
	v_pk_add_f32 v[70:71], v[70:71], v[94:95]
	v_pk_add_f32 v[68:69], v[68:69], v[78:79]
	v_pk_add_f32 v[94:95], v[64:65], v[96:97]
	v_cvt_pk_bf16_f32 v64, v68, v69
	v_cvt_pk_bf16_f32 v74, v104, v105
	v_addc_co_u32_e32 v77, vcc, 0, v161, vcc
	v_pk_add_f32 v[78:79], v[66:67], v[98:99]
	v_cvt_pk_bf16_f32 v65, v70, v71
	v_cvt_pk_bf16_f32 v66, v94, v95
	global_store_dwordx4 v[108:109], v[72:75], off
	v_cvt_pk_bf16_f32 v67, v78, v79
	global_store_dwordx4 v[100:101], v[64:67], off offset:256
	s_nop 0
	v_fmac_f32_e32 v135, v134, v134
	v_mul_f32_e32 v64, v69, v69
	v_fmac_f32_e32 v64, v68, v68
	v_fmac_f32_e32 v64, v70, v70
	v_fmac_f32_e32 v64, v71, v71
	v_fmac_f32_e32 v64, v94, v94
	v_fmac_f32_e32 v64, v95, v95
	v_fmac_f32_e32 v64, v78, v78
	v_fmac_f32_e32 v64, v79, v79
	v_add_f32_e32 v68, v87, v64
	v_lshlrev_b32_e32 v64, 16, v91
	v_and_b32_e32 v65, 0xffff0000, v91
	v_lshl_add_u64 v[66:67], v[160:161], 0, s[30:31]
	v_lshlrev_b32_e32 v70, 16, v90
	v_and_b32_e32 v71, 0xffff0000, v90
	v_lshlrev_b32_e32 v78, 16, v92
	v_and_b32_e32 v79, 0xffff0000, v92
	v_lshlrev_b32_e32 v90, 16, v93
	v_and_b32_e32 v91, 0xffff0000, v93
	v_pk_add_f32 v[92:93], v[62:63], v[64:65]
	s_nop 0
	v_pk_add_f32 v[60:61], v[60:61], v[70:71]
	v_pk_add_f32 v[78:79], v[56:57], v[78:79]
	v_mul_f32_e32 v69, v61, v61
	v_fmac_f32_e32 v69, v60, v60
	v_fmac_f32_e32 v69, v92, v92
	v_fmac_f32_e32 v69, v93, v93
	v_fmac_f32_e32 v69, v78, v78
	v_pk_add_f32 v[70:71], v[58:59], v[90:91]
	v_fmac_f32_e32 v69, v79, v79
	v_fmac_f32_e32 v69, v70, v70
	v_cvt_pk_bf16_f32 v58, v78, v79
	v_cvt_pk_bf16_f32 v59, v70, v71
	v_fmac_f32_e32 v69, v71, v71
	v_lshlrev_b32_e32 v70, 16, v80
	v_and_b32_e32 v71, 0xffff0000, v80
	v_lshlrev_b32_e32 v78, 16, v81
	v_and_b32_e32 v79, 0xffff0000, v81
	v_lshlrev_b32_e32 v80, 16, v82
	v_and_b32_e32 v81, 0xffff0000, v82
	v_lshlrev_b32_e32 v82, 16, v83
	v_and_b32_e32 v83, 0xffff0000, v83
	v_pk_add_f32 v[54:55], v[54:55], v[78:79]
	v_pk_add_f32 v[52:53], v[52:53], v[70:71]
	v_pk_add_f32 v[78:79], v[48:49], v[80:81]
	v_cvt_pk_bf16_f32 v48, v52, v53
	v_pk_add_f32 v[70:71], v[50:51], v[82:83]
	v_cvt_pk_bf16_f32 v49, v54, v55
	v_cvt_pk_bf16_f32 v50, v78, v79
	v_cvt_pk_bf16_f32 v56, v60, v61
	v_add_co_u32_e32 v60, vcc, s77, v160
	v_cvt_pk_bf16_f32 v51, v70, v71
	global_store_dwordx4 v[84:85], v[48:51], off offset:256
	v_cvt_pk_bf16_f32 v57, v92, v93
	s_nop 0
	v_addc_co_u32_e32 v61, vcc, 0, v161, vcc
	v_mul_f32_e32 v48, v53, v53
	v_fmac_f32_e32 v48, v52, v52
	v_fmac_f32_e32 v48, v54, v54
	v_fmac_f32_e32 v48, v55, v55
	v_fmac_f32_e32 v48, v78, v78
	global_store_dwordx4 v[88:89], v[56:59], off
	s_nop 0
	v_fmac_f32_e32 v48, v79, v79
	v_fmac_f32_e32 v48, v70, v70
	v_fmac_f32_e32 v48, v71, v71
	v_add_f32_e32 v69, v69, v48
	v_lshl_add_u64 v[48:49], v[160:161], 0, s[34:35]
	s_nop 0
	v_fmac_f32_e32 v125, v126, v126
	v_fmac_f32_e32 v135, v132, v132
	v_fmac_f32_e32 v125, v127, v127
	v_fmac_f32_e32 v135, v133, v133
	v_fmac_f32_e32 v125, v120, v120
	v_fmac_f32_e32 v135, v142, v142
	v_fmac_f32_e32 v125, v121, v121
	v_fmac_f32_e32 v135, v143, v143
	v_fmac_f32_e32 v125, v122, v122
	s_waitcnt vmcnt(12)
	s_nop 1
	v_mov_b32_e32 v72, v222
	v_mov_b32_e32 v73, v223
	v_mov_b32_e32 v74, v224
	v_mov_b32_e32 v75, v225
	v_mov_b32_e32 v62, v226
	v_mov_b32_e32 v63, v227
	v_mov_b32_e32 v64, v228
	v_mov_b32_e32 v65, v229
	v_mov_b32_e32 v56, v230
	v_mov_b32_e32 v57, v231
	v_mov_b32_e32 v58, v232
	v_mov_b32_e32 v59, v233
	v_mov_b32_e32 v50, v234
	v_mov_b32_e32 v51, v235
	v_mov_b32_e32 v52, v236
	v_mov_b32_e32 v53, v237
	v_lshlrev_b32_e32 v54, 16, v72
	v_and_b32_e32 v55, 0xffff0000, v72
	v_lshlrev_b32_e32 v70, 16, v73
	v_and_b32_e32 v71, 0xffff0000, v73
	v_lshlrev_b32_e32 v72, 16, v74
	v_and_b32_e32 v73, 0xffff0000, v74
	v_pk_add_f32 v[44:45], v[44:45], v[54:55]
	v_pk_add_f32 v[46:47], v[46:47], v[70:71]
	v_pk_add_f32 v[70:71], v[40:41], v[72:73]
	v_mul_f32_e32 v72, v45, v45
	v_fmac_f32_e32 v72, v44, v44
	v_fmac_f32_e32 v72, v46, v46
	v_fmac_f32_e32 v72, v47, v47
	v_lshlrev_b32_e32 v74, 16, v75
	v_and_b32_e32 v75, 0xffff0000, v75
	v_cvt_pk_bf16_f32 v40, v44, v45
	v_fmac_f32_e32 v72, v70, v70
	v_add_co_u32_e32 v44, vcc, s78, v160
	v_pk_add_f32 v[54:55], v[42:43], v[74:75]
	v_cvt_pk_bf16_f32 v41, v46, v47
	v_cvt_pk_bf16_f32 v42, v70, v71
	v_fmac_f32_e32 v72, v71, v71
	v_cvt_pk_bf16_f32 v43, v54, v55
	v_addc_co_u32_e32 v45, vcc, 0, v161, vcc
	global_store_dwordx4 v[76:77], v[40:43], off
	v_fmac_f32_e32 v72, v54, v54
	s_nop 0
	v_lshlrev_b32_e32 v46, 16, v62
	v_and_b32_e32 v47, 0xffff0000, v62
	v_fmac_f32_e32 v72, v55, v55
	v_lshlrev_b32_e32 v54, 16, v63
	v_and_b32_e32 v55, 0xffff0000, v63
	v_lshlrev_b32_e32 v62, 16, v64
	v_and_b32_e32 v63, 0xffff0000, v64
	v_pk_add_f32 v[36:37], v[36:37], v[46:47]
	v_lshlrev_b32_e32 v64, 16, v65
	v_and_b32_e32 v65, 0xffff0000, v65
	v_pk_add_f32 v[38:39], v[38:39], v[54:55]
	v_pk_add_f32 v[54:55], v[32:33], v[62:63]
	v_mul_f32_e32 v62, v37, v37
	v_pk_add_f32 v[46:47], v[34:35], v[64:65]
	v_cvt_pk_bf16_f32 v32, v36, v37
	v_cvt_pk_bf16_f32 v33, v38, v39
	v_cvt_pk_bf16_f32 v34, v54, v55
	v_fmac_f32_e32 v62, v36, v36
	v_cvt_pk_bf16_f32 v35, v46, v47
	v_lshl_add_u64 v[36:37], v[160:161], 0, s[36:37]
	global_store_dwordx4 v[66:67], v[32:35], off offset:256
	s_nop 0
	v_fmac_f32_e32 v62, v38, v38
	v_fmac_f32_e32 v62, v39, v39
	v_fmac_f32_e32 v62, v54, v54
	v_fmac_f32_e32 v62, v55, v55
	v_fmac_f32_e32 v62, v46, v46
	v_fmac_f32_e32 v62, v47, v47
	v_fmac_f32_e32 v135, v140, v140
	v_fmac_f32_e32 v125, v123, v123
	v_fmac_f32_e32 v135, v141, v141
	v_add_f32_e32 v110, v125, v135
	v_add_f32_e32 v62, v72, v62
	v_lshlrev_b32_e32 v38, 16, v56
	v_and_b32_e32 v39, 0xffff0000, v56
	v_lshlrev_b32_e32 v46, 16, v57
	v_and_b32_e32 v47, 0xffff0000, v57
	v_lshlrev_b32_e32 v54, 16, v58
	v_and_b32_e32 v55, 0xffff0000, v58
	v_pk_add_f32 v[28:29], v[28:29], v[38:39]
	v_lshlrev_b32_e32 v56, 16, v59
	v_and_b32_e32 v57, 0xffff0000, v59
	v_pk_add_f32 v[30:31], v[30:31], v[46:47]
	v_pk_add_f32 v[46:47], v[24:25], v[54:55]
	v_mul_f32_e32 v54, v29, v29
	v_pk_add_f32 v[38:39], v[26:27], v[56:57]
	v_cvt_pk_bf16_f32 v24, v28, v29
	v_cvt_pk_bf16_f32 v25, v30, v31
	v_cvt_pk_bf16_f32 v26, v46, v47
	v_fmac_f32_e32 v54, v28, v28
	v_cvt_pk_bf16_f32 v27, v38, v39
	global_store_dwordx4 v[60:61], v[24:27], off
	v_fmac_f32_e32 v54, v30, v30
	v_lshlrev_b32_e32 v28, 16, v52
	v_lshlrev_b32_e32 v24, 16, v50
	v_and_b32_e32 v25, 0xffff0000, v50
	v_lshlrev_b32_e32 v26, 16, v51
	v_and_b32_e32 v27, 0xffff0000, v51
	v_and_b32_e32 v29, 0xffff0000, v52
	v_fmac_f32_e32 v54, v31, v31
	v_lshlrev_b32_e32 v30, 16, v53
	v_and_b32_e32 v31, 0xffff0000, v53
	v_pk_add_f32 v[22:23], v[22:23], v[26:27]
	v_pk_add_f32 v[20:21], v[20:21], v[24:25]
	v_pk_add_f32 v[26:27], v[12:13], v[28:29]
	v_cvt_pk_bf16_f32 v12, v20, v21
	v_pk_add_f32 v[24:25], v[14:15], v[30:31]
	v_cvt_pk_bf16_f32 v13, v22, v23
	v_cvt_pk_bf16_f32 v14, v26, v27
	v_fmac_f32_e32 v54, v46, v46
	v_cvt_pk_bf16_f32 v15, v24, v25
	global_store_dwordx4 v[48:49], v[12:15], off offset:256
	v_fmac_f32_e32 v54, v47, v47
	v_fmac_f32_e32 v54, v38, v38
	v_mul_f32_e32 v12, v21, v21
	v_fmac_f32_e32 v12, v20, v20
	v_fmac_f32_e32 v12, v22, v22
	v_fmac_f32_e32 v12, v23, v23
	v_fmac_f32_e32 v12, v26, v26
	v_fmac_f32_e32 v12, v27, v27
	v_fmac_f32_e32 v12, v24, v24
	v_fmac_f32_e32 v54, v39, v39
	v_fmac_f32_e32 v12, v25, v25
	v_add_f32_e32 v24, v54, v12
	s_waitcnt vmcnt(14)
	s_nop 1
	v_mov_b32_e32 v40, v238
	v_mov_b32_e32 v41, v239
	v_mov_b32_e32 v42, v240
	v_mov_b32_e32 v43, v241
	v_mov_b32_e32 v32, v242
	v_mov_b32_e32 v33, v243
	v_mov_b32_e32 v34, v244
	v_mov_b32_e32 v35, v245
	v_lshlrev_b32_e32 v12, 16, v40
	v_and_b32_e32 v13, 0xffff0000, v40
	v_pk_add_f32 v[12:13], v[16:17], v[12:13]
	v_lshlrev_b32_e32 v14, 16, v41
	v_and_b32_e32 v15, 0xffff0000, v41
	v_lshlrev_b32_e32 v20, 16, v42
	v_and_b32_e32 v21, 0xffff0000, v42
	v_mul_f32_e32 v25, v13, v13
	v_lshlrev_b32_e32 v22, 16, v43
	v_and_b32_e32 v23, 0xffff0000, v43
	v_pk_add_f32 v[14:15], v[18:19], v[14:15]
	v_pk_add_f32 v[18:19], v[8:9], v[20:21]
	v_cvt_pk_bf16_f32 v8, v12, v13
	v_cvt_pk_bf16_f32 v9, v14, v15
	v_fmac_f32_e32 v25, v12, v12
	v_pk_add_f32 v[16:17], v[10:11], v[22:23]
	v_cvt_pk_bf16_f32 v10, v18, v19
	v_fmac_f32_e32 v25, v14, v14
	v_cvt_pk_bf16_f32 v11, v16, v17
	global_store_dwordx4 v[44:45], v[8:11], off
	v_fmac_f32_e32 v25, v15, v15
	v_lshlrev_b32_e32 v12, 16, v34
	v_lshlrev_b32_e32 v8, 16, v32
	v_and_b32_e32 v9, 0xffff0000, v32
	v_and_b32_e32 v13, 0xffff0000, v34
	v_pk_add_f32 v[4:5], v[4:5], v[8:9]
	v_fmac_f32_e32 v25, v18, v18
	v_lshlrev_b32_e32 v10, 16, v33
	v_and_b32_e32 v11, 0xffff0000, v33
	v_pk_add_f32 v[22:23], v[0:1], v[12:13]
	v_mul_f32_e32 v0, v5, v5
	v_fmac_f32_e32 v25, v19, v19
	v_pk_add_f32 v[18:19], v[6:7], v[10:11]
	v_fmac_f32_e32 v0, v4, v4
	v_fmac_f32_e32 v0, v18, v18
	v_fmac_f32_e32 v0, v19, v19
	v_lshlrev_b32_e32 v14, 16, v35
	v_and_b32_e32 v15, 0xffff0000, v35
	v_fmac_f32_e32 v0, v22, v22
	v_pk_add_f32 v[20:21], v[2:3], v[14:15]
	v_fmac_f32_e32 v0, v23, v23
	v_fmac_f32_e32 v25, v16, v16
	v_fmac_f32_e32 v0, v20, v20
	v_fmac_f32_e32 v25, v17, v17
	v_fmac_f32_e32 v0, v21, v21
	v_add_f32_e32 v14, v25, v0
	v_cvt_pk_bf16_f32 v16, v4, v5
	ds_bpermute_b32 v1, v169, v110
	ds_bpermute_b32 v2, v169, v102
	ds_bpermute_b32 v4, v169, v86
	ds_bpermute_b32 v6, v169, v68
	ds_bpermute_b32 v8, v169, v69
	ds_bpermute_b32 v10, v169, v62
	ds_bpermute_b32 v12, v169, v24
	ds_bpermute_b32 v15, v169, v14
	s_waitcnt lgkmcnt(0)
	v_add_f32_e32 v0, v110, v1
	v_add_f32_e32 v2, v102, v2
	v_add_f32_e32 v4, v86, v4
	v_add_f32_e32 v6, v68, v6
	v_add_f32_e32 v8, v69, v8
	v_add_f32_e32 v10, v62, v10
	v_add_f32_e32 v12, v24, v12
	v_add_f32_e32 v14, v14, v15
	ds_bpermute_b32 v1, v170, v0
	ds_bpermute_b32 v3, v170, v2
	ds_bpermute_b32 v5, v170, v4
	ds_bpermute_b32 v7, v170, v6
	ds_bpermute_b32 v9, v170, v8
	ds_bpermute_b32 v11, v170, v10
	ds_bpermute_b32 v13, v170, v12
	ds_bpermute_b32 v15, v170, v14
	v_cvt_pk_bf16_f32 v17, v18, v19
	v_cvt_pk_bf16_f32 v18, v22, v23
	v_cvt_pk_bf16_f32 v19, v20, v21
	global_store_dwordx4 v[36:37], v[16:19], off offset:256
	s_and_saveexec_b64 s[42:43], s[4:5]
	s_cbranch_execz .LBB0_820
	s_waitcnt lgkmcnt(6)
	v_add_f32_e32 v2, v2, v3
	v_add_f32_e32 v0, v0, v1
	v_add_u32_e32 v1, s72, v171
	s_waitcnt lgkmcnt(2)
	v_add_f32_e32 v10, v10, v11
	v_add_f32_e32 v8, v8, v9
	v_add_f32_e32 v6, v6, v7
	v_add_f32_e32 v4, v4, v5
	ds_write2st64_b32 v1, v0, v2 offset1:1
	ds_write2st64_b32 v1, v4, v6 offset0:2 offset1:3
	v_add_u32_e32 v0, s72, v175
	s_waitcnt lgkmcnt(2)
	v_add_f32_e32 v14, v14, v15
	v_add_f32_e32 v12, v12, v13
	ds_write2st64_b32 v0, v8, v10 offset1:1
	ds_write2st64_b32 v0, v12, v14 offset0:2 offset1:3

.LBB0_889:
	ds_read_b128 v[128:131], v181
	ds_read_b128 v[132:135], v181 offset:1024
	ds_read_b128 v[136:139], v181 offset:2048
	ds_read_b128 v[140:143], v181 offset:3072
	s_add_u32 s42, s40, 0xfffc0080
	s_addc_u32 s43, s41, -1
	s_cmp_eq_u32 s80, 12
	s_cselect_b32 s45, s37, s43
	s_cselect_b32 s44, s36, s42
	s_cselect_b32 s43, s39, s79
	s_cselect_b32 s42, s38, s78
	v_lshl_add_u64 v[166:167], s[40:41], 0, v[152:153]
	s_add_i32 m0, s50, 0xc000
	ds_read_b128 v[158:161], v182
	ds_read_b128 v[162:165], v182 offset:1024
	ds_read_b128 v[184:187], v182 offset:2048
	ds_read_b128 v[188:191], v182 offset:3072
	ds_read_b128 v[192:195], v182 offset:4096
	ds_read_b128 v[200:203], v182 offset:5120
	ds_read_b128 v[204:207], v182 offset:6144
	ds_read_b128 v[208:211], v182 offset:7168
	global_load_lds_dwordx4 v[166:167], off
	v_lshl_add_u64 v[166:167], s[40:41], 0, v[154:155]
	s_add_i32 m0, s50, 0xe000
	s_nop 0
	global_load_lds_dwordx4 v[166:167], off
	s_waitcnt lgkmcnt(8)
	s_barrier
	s_waitcnt lgkmcnt(0)
	s_setprio 1
	s_waitcnt lgkmcnt(0)
	v_mfma_f32_16x16x32_bf16 v[124:127], v[128:131], v[158:161], v[124:127]
	v_mfma_f32_16x16x32_bf16 v[120:123], v[136:139], v[158:161], v[120:123]
	v_mfma_f32_16x16x32_bf16 v[116:119], v[128:131], v[184:187], v[116:119]
	v_mfma_f32_16x16x32_bf16 v[108:111], v[136:139], v[184:187], v[108:111]
	v_mfma_f32_16x16x32_bf16 v[92:95], v[128:131], v[192:195], v[92:95]
	v_mfma_f32_16x16x32_bf16 v[88:91], v[136:139], v[192:195], v[88:91]
	v_mfma_f32_16x16x32_bf16 v[76:79], v[128:131], v[204:207], v[76:79]
	v_mfma_f32_16x16x32_bf16 v[72:75], v[136:139], v[204:207], v[72:75]
	v_mfma_f32_16x16x32_bf16 v[124:127], v[132:135], v[162:165], v[124:127]
	v_mfma_f32_16x16x32_bf16 v[120:123], v[140:143], v[162:165], v[120:123]
	v_mfma_f32_16x16x32_bf16 v[116:119], v[132:135], v[188:191], v[116:119]
	v_mfma_f32_16x16x32_bf16 v[108:111], v[140:143], v[188:191], v[108:111]
	v_mfma_f32_16x16x32_bf16 v[92:95], v[132:135], v[200:203], v[92:95]
	v_mfma_f32_16x16x32_bf16 v[88:91], v[140:143], v[200:203], v[88:91]
	v_mfma_f32_16x16x32_bf16 v[76:79], v[132:135], v[208:211], v[76:79]
	v_mfma_f32_16x16x32_bf16 v[72:75], v[140:143], v[208:211], v[72:75]
	s_setprio 0
	s_barrier
	s_add_i32 s81, s70, s49
	v_lshl_add_u64 v[166:167], s[42:43], 0, v[146:147]
	s_mov_b32 m0, s81
	ds_read_b128 v[212:215], v183
	ds_read_b128 v[216:219], v183 offset:1024
	ds_read_b128 v[220:223], v183 offset:2048
	ds_read_b128 v[224:227], v183 offset:3072
	global_load_lds_dwordx4 v[166:167], off
	v_lshl_add_u64 v[228:229], s[42:43], 0, v[150:151]
	s_add_i32 m0, s81, 0x2000
	s_nop 0
	global_load_lds_dwordx4 v[228:229], off
	s_barrier
	s_waitcnt lgkmcnt(0)
	s_setprio 1
	s_waitcnt lgkmcnt(0)
	v_mfma_f32_16x16x32_bf16 v[112:115], v[212:215], v[158:161], v[112:115]
	v_mfma_f32_16x16x32_bf16 v[104:107], v[220:223], v[158:161], v[104:107]
	v_mfma_f32_16x16x32_bf16 v[100:103], v[212:215], v[184:187], v[100:103]
	v_mfma_f32_16x16x32_bf16 v[96:99], v[220:223], v[184:187], v[96:99]
	v_mfma_f32_16x16x32_bf16 v[84:87], v[212:215], v[192:195], v[84:87]
	v_mfma_f32_16x16x32_bf16 v[80:83], v[220:223], v[192:195], v[80:83]
	v_mfma_f32_16x16x32_bf16 v[68:71], v[212:215], v[204:207], v[68:71]
	v_mfma_f32_16x16x32_bf16 v[64:67], v[220:223], v[204:207], v[64:67]
	v_mfma_f32_16x16x32_bf16 v[112:115], v[216:219], v[162:165], v[112:115]
	v_mfma_f32_16x16x32_bf16 v[104:107], v[224:227], v[162:165], v[104:107]
	v_mfma_f32_16x16x32_bf16 v[100:103], v[216:219], v[188:191], v[100:103]
	v_mfma_f32_16x16x32_bf16 v[96:99], v[224:227], v[188:191], v[96:99]
	v_mfma_f32_16x16x32_bf16 v[84:87], v[216:219], v[200:203], v[84:87]
	v_mfma_f32_16x16x32_bf16 v[80:83], v[224:227], v[200:203], v[80:83]
	v_mfma_f32_16x16x32_bf16 v[68:71], v[216:219], v[208:211], v[68:71]
	v_mfma_f32_16x16x32_bf16 v[64:67], v[224:227], v[208:211], v[64:67]
	s_setprio 0
	s_mov_b32 m0, s50
	v_lshl_add_u64 v[230:231], s[44:45], 0, v[144:145]
	s_barrier
	ds_read_b128 v[158:161], v182 offset:16384
	ds_read_b128 v[162:165], v182 offset:17408
	ds_read_b128 v[184:187], v182 offset:18432
	ds_read_b128 v[188:191], v182 offset:19456
	ds_read_b128 v[192:195], v182 offset:20480
	ds_read_b128 v[200:203], v182 offset:21504
	ds_read_b128 v[204:207], v182 offset:22528
	ds_read_b128 v[208:211], v182 offset:23552
	global_load_lds_dwordx4 v[230:231], off
	v_lshl_add_u64 v[232:233], s[44:45], 0, v[148:149]
	s_mov_b32 m0, s51
	s_nop 0
	global_load_lds_dwordx4 v[232:233], off
	s_barrier
	s_waitcnt lgkmcnt(0)
	s_setprio 1
	s_waitcnt lgkmcnt(0)
	v_mfma_f32_16x16x32_bf16 v[60:63], v[128:131], v[158:161], v[60:63]
	v_mfma_f32_16x16x32_bf16 v[56:59], v[136:139], v[158:161], v[56:59]
	v_mfma_f32_16x16x32_bf16 v[44:47], v[128:131], v[184:187], v[44:47]
	v_mfma_f32_16x16x32_bf16 v[40:43], v[136:139], v[184:187], v[40:43]
	v_mfma_f32_16x16x32_bf16 v[28:31], v[128:131], v[192:195], v[28:31]
	v_mfma_f32_16x16x32_bf16 v[24:27], v[136:139], v[192:195], v[24:27]
	v_mfma_f32_16x16x32_bf16 v[16:19], v[128:131], v[204:207], v[16:19]
	v_mfma_f32_16x16x32_bf16 v[8:11], v[136:139], v[204:207], v[8:11]
	v_mfma_f32_16x16x32_bf16 v[60:63], v[132:135], v[162:165], v[60:63]
	v_mfma_f32_16x16x32_bf16 v[56:59], v[140:143], v[162:165], v[56:59]
	v_mfma_f32_16x16x32_bf16 v[44:47], v[132:135], v[188:191], v[44:47]
	v_mfma_f32_16x16x32_bf16 v[40:43], v[140:143], v[188:191], v[40:43]
	v_mfma_f32_16x16x32_bf16 v[28:31], v[132:135], v[200:203], v[28:31]
	v_mfma_f32_16x16x32_bf16 v[24:27], v[140:143], v[200:203], v[24:27]
	v_mfma_f32_16x16x32_bf16 v[16:19], v[132:135], v[208:211], v[16:19]
	v_mfma_f32_16x16x32_bf16 v[8:11], v[140:143], v[208:211], v[8:11]
	s_setprio 0
	s_barrier
	s_add_u32 s82, s42, 0x40000
	s_addc_u32 s83, s43, 0
	s_add_i32 s81, s71, s49
	v_lshl_add_u64 v[128:129], s[82:83], 0, v[146:147]
	s_mov_b32 m0, s81
	s_nop 0
	global_load_lds_dwordx4 v[128:129], off
	v_lshl_add_u64 v[128:129], s[82:83], 0, v[150:151]
	s_add_i32 m0, s81, 0x2000
	s_nop 0
	global_load_lds_dwordx4 v[128:129], off
	s_waitcnt vmcnt(6)
	s_barrier
	s_setprio 1
	v_mfma_f32_16x16x32_bf16 v[52:55], v[212:215], v[158:161], v[52:55]
	v_mfma_f32_16x16x32_bf16 v[48:51], v[220:223], v[158:161], v[48:51]
	v_mfma_f32_16x16x32_bf16 v[36:39], v[212:215], v[184:187], v[36:39]
	v_mfma_f32_16x16x32_bf16 v[32:35], v[220:223], v[184:187], v[32:35]
	v_mfma_f32_16x16x32_bf16 v[20:23], v[212:215], v[192:195], v[20:23]
	v_mfma_f32_16x16x32_bf16 v[12:15], v[220:223], v[192:195], v[12:15]
	v_mfma_f32_16x16x32_bf16 v[4:7], v[212:215], v[204:207], v[4:7]
	v_mfma_f32_16x16x32_bf16 v[0:3], v[220:223], v[204:207], v[0:3]
	v_mfma_f32_16x16x32_bf16 v[52:55], v[216:219], v[162:165], v[52:55]
	v_mfma_f32_16x16x32_bf16 v[48:51], v[224:227], v[162:165], v[48:51]
	v_mfma_f32_16x16x32_bf16 v[36:39], v[216:219], v[188:191], v[36:39]
	v_mfma_f32_16x16x32_bf16 v[32:35], v[224:227], v[188:191], v[32:35]
	v_mfma_f32_16x16x32_bf16 v[20:23], v[216:219], v[200:203], v[20:23]
	v_mfma_f32_16x16x32_bf16 v[12:15], v[224:227], v[200:203], v[12:15]
	v_mfma_f32_16x16x32_bf16 v[4:7], v[216:219], v[208:211], v[4:7]
	v_mfma_f32_16x16x32_bf16 v[0:3], v[224:227], v[208:211], v[0:3]
	s_setprio 0
	s_add_i32 s81, 0, 0x18000
	v_add_u32_e32 v140, s81, v169
	s_barrier
	ds_read_b128 v[128:131], v140
	ds_read_b128 v[132:135], v140 offset:1024
	ds_read_b128 v[136:139], v140 offset:2048
	ds_read_b128 v[140:143], v140 offset:3072
	s_add_u32 s44, s44, 0x40000
	s_addc_u32 s45, s45, 0
	s_mov_b32 m0, s52
	v_lshl_add_u64 v[212:213], s[44:45], 0, v[144:145]
	ds_read_b128 v[158:161], v182 offset:32768
	ds_read_b128 v[162:165], v182 offset:33792
	ds_read_b128 v[184:187], v182 offset:34816
	ds_read_b128 v[188:191], v182 offset:35840
	ds_read_b128 v[192:195], v182 offset:36864
	ds_read_b128 v[200:203], v182 offset:37888
	ds_read_b128 v[204:207], v182 offset:38912
	ds_read_b128 v[208:211], v182 offset:39936
	global_load_lds_dwordx4 v[212:213], off
	v_lshl_add_u64 v[212:213], s[44:45], 0, v[148:149]
	s_mov_b32 m0, s53
	s_nop 0
	global_load_lds_dwordx4 v[212:213], off
	s_waitcnt lgkmcnt(8)
	s_barrier
	s_waitcnt lgkmcnt(0)
	s_setprio 1
	s_waitcnt lgkmcnt(0)
	v_mfma_f32_16x16x32_bf16 v[124:127], v[128:131], v[158:161], v[124:127]
	v_mfma_f32_16x16x32_bf16 v[120:123], v[136:139], v[158:161], v[120:123]
	v_mfma_f32_16x16x32_bf16 v[116:119], v[128:131], v[184:187], v[116:119]
	v_mfma_f32_16x16x32_bf16 v[108:111], v[136:139], v[184:187], v[108:111]
	v_mfma_f32_16x16x32_bf16 v[92:95], v[128:131], v[192:195], v[92:95]
	v_mfma_f32_16x16x32_bf16 v[88:91], v[136:139], v[192:195], v[88:91]
	v_mfma_f32_16x16x32_bf16 v[76:79], v[128:131], v[204:207], v[76:79]
	v_mfma_f32_16x16x32_bf16 v[72:75], v[136:139], v[204:207], v[72:75]
	v_mfma_f32_16x16x32_bf16 v[124:127], v[132:135], v[162:165], v[124:127]
	v_mfma_f32_16x16x32_bf16 v[120:123], v[140:143], v[162:165], v[120:123]
	v_mfma_f32_16x16x32_bf16 v[116:119], v[132:135], v[188:191], v[116:119]
	v_mfma_f32_16x16x32_bf16 v[108:111], v[140:143], v[188:191], v[108:111]
	v_mfma_f32_16x16x32_bf16 v[92:95], v[132:135], v[200:203], v[92:95]
	v_mfma_f32_16x16x32_bf16 v[88:91], v[140:143], v[200:203], v[88:91]
	v_mfma_f32_16x16x32_bf16 v[76:79], v[132:135], v[208:211], v[76:79]
	v_mfma_f32_16x16x32_bf16 v[72:75], v[140:143], v[208:211], v[72:75]
	s_setprio 0
	s_barrier
	s_add_i32 s44, 0, 0x1c000
	s_add_i32 s45, s81, s49
	v_add_u32_e32 v224, s44, v169
	v_lshl_add_u64 v[166:167], v[166:167], 0, s[20:21]
	s_mov_b32 m0, s45
	ds_read_b128 v[212:215], v224
	ds_read_b128 v[216:219], v224 offset:1024
	ds_read_b128 v[220:223], v224 offset:2048
	ds_read_b128 v[224:227], v224 offset:3072
	global_load_lds_dwordx4 v[166:167], off
	v_lshl_add_u64 v[166:167], v[228:229], 0, s[20:21]
	s_add_i32 m0, s45, 0x2000
	s_nop 0
	global_load_lds_dwordx4 v[166:167], off
	s_barrier
	s_waitcnt lgkmcnt(0)
	s_setprio 1
	s_waitcnt lgkmcnt(0)
	v_mfma_f32_16x16x32_bf16 v[112:115], v[212:215], v[158:161], v[112:115]
	v_mfma_f32_16x16x32_bf16 v[104:107], v[220:223], v[158:161], v[104:107]
	v_mfma_f32_16x16x32_bf16 v[100:103], v[212:215], v[184:187], v[100:103]
	v_mfma_f32_16x16x32_bf16 v[96:99], v[220:223], v[184:187], v[96:99]
	v_mfma_f32_16x16x32_bf16 v[84:87], v[212:215], v[192:195], v[84:87]
	v_mfma_f32_16x16x32_bf16 v[80:83], v[220:223], v[192:195], v[80:83]
	v_mfma_f32_16x16x32_bf16 v[68:71], v[212:215], v[204:207], v[68:71]
	v_mfma_f32_16x16x32_bf16 v[64:67], v[220:223], v[204:207], v[64:67]
	v_mfma_f32_16x16x32_bf16 v[112:115], v[216:219], v[162:165], v[112:115]
	v_mfma_f32_16x16x32_bf16 v[104:107], v[224:227], v[162:165], v[104:107]
	v_mfma_f32_16x16x32_bf16 v[100:103], v[216:219], v[188:191], v[100:103]
	v_mfma_f32_16x16x32_bf16 v[96:99], v[224:227], v[188:191], v[96:99]
	v_mfma_f32_16x16x32_bf16 v[84:87], v[216:219], v[200:203], v[84:87]
	v_mfma_f32_16x16x32_bf16 v[80:83], v[224:227], v[200:203], v[80:83]
	v_mfma_f32_16x16x32_bf16 v[68:71], v[216:219], v[208:211], v[68:71]
	v_mfma_f32_16x16x32_bf16 v[64:67], v[224:227], v[208:211], v[64:67]
	s_setprio 0
	s_mov_b32 m0, s65
	v_lshl_add_u64 v[166:167], v[230:231], 0, s[20:21]
	s_barrier
	ds_read_b128 v[158:161], v182 offset:49152
	ds_read_b128 v[162:165], v182 offset:50176
	ds_read_b128 v[184:187], v182 offset:51200
	ds_read_b128 v[188:191], v182 offset:52224
	ds_read_b128 v[192:195], v182 offset:53248
	ds_read_b128 v[200:203], v182 offset:54272
	ds_read_b128 v[204:207], v182 offset:55296
	ds_read_b128 v[208:211], v182 offset:56320
	global_load_lds_dwordx4 v[166:167], off
	v_lshl_add_u64 v[166:167], v[232:233], 0, s[20:21]
	s_mov_b32 m0, s66
	s_nop 0
	global_load_lds_dwordx4 v[166:167], off
	s_barrier
	s_waitcnt lgkmcnt(0)
	s_setprio 1
	s_waitcnt lgkmcnt(0)
	v_mfma_f32_16x16x32_bf16 v[60:63], v[128:131], v[158:161], v[60:63]
	v_mfma_f32_16x16x32_bf16 v[56:59], v[136:139], v[158:161], v[56:59]
	v_mfma_f32_16x16x32_bf16 v[44:47], v[128:131], v[184:187], v[44:47]
	v_mfma_f32_16x16x32_bf16 v[40:43], v[136:139], v[184:187], v[40:43]
	v_mfma_f32_16x16x32_bf16 v[28:31], v[128:131], v[192:195], v[28:31]
	v_mfma_f32_16x16x32_bf16 v[24:27], v[136:139], v[192:195], v[24:27]
	v_mfma_f32_16x16x32_bf16 v[16:19], v[128:131], v[204:207], v[16:19]
	v_mfma_f32_16x16x32_bf16 v[8:11], v[136:139], v[204:207], v[8:11]
	v_mfma_f32_16x16x32_bf16 v[60:63], v[132:135], v[162:165], v[60:63]
	v_mfma_f32_16x16x32_bf16 v[56:59], v[140:143], v[162:165], v[56:59]
	v_mfma_f32_16x16x32_bf16 v[44:47], v[132:135], v[188:191], v[44:47]
	v_mfma_f32_16x16x32_bf16 v[40:43], v[140:143], v[188:191], v[40:43]
	v_mfma_f32_16x16x32_bf16 v[28:31], v[132:135], v[200:203], v[28:31]
	v_mfma_f32_16x16x32_bf16 v[24:27], v[140:143], v[200:203], v[24:27]
	v_mfma_f32_16x16x32_bf16 v[16:19], v[132:135], v[208:211], v[16:19]
	v_mfma_f32_16x16x32_bf16 v[8:11], v[140:143], v[208:211], v[8:11]
	s_setprio 0
	s_barrier
	s_add_u32 s42, s42, 0x40080
	s_addc_u32 s43, s43, 0
	s_add_i32 s44, s44, s49
	v_lshl_add_u64 v[128:129], s[42:43], 0, v[146:147]
	s_mov_b32 m0, s44
	s_nop 0
	global_load_lds_dwordx4 v[128:129], off
	v_lshl_add_u64 v[128:129], s[42:43], 0, v[150:151]
	s_add_i32 m0, s44, 0x2000
	s_nop 0
	global_load_lds_dwordx4 v[128:129], off
	s_waitcnt vmcnt(6)
	s_barrier
	s_setprio 1
	v_mfma_f32_16x16x32_bf16 v[52:55], v[212:215], v[158:161], v[52:55]
	v_mfma_f32_16x16x32_bf16 v[48:51], v[220:223], v[158:161], v[48:51]
	v_mfma_f32_16x16x32_bf16 v[36:39], v[212:215], v[184:187], v[36:39]
	v_mfma_f32_16x16x32_bf16 v[32:35], v[220:223], v[184:187], v[32:35]
	v_mfma_f32_16x16x32_bf16 v[20:23], v[212:215], v[192:195], v[20:23]
	v_mfma_f32_16x16x32_bf16 v[12:15], v[220:223], v[192:195], v[12:15]
	v_mfma_f32_16x16x32_bf16 v[4:7], v[212:215], v[204:207], v[4:7]
	v_mfma_f32_16x16x32_bf16 v[0:3], v[220:223], v[204:207], v[0:3]
	v_mfma_f32_16x16x32_bf16 v[52:55], v[216:219], v[162:165], v[52:55]
	v_mfma_f32_16x16x32_bf16 v[48:51], v[224:227], v[162:165], v[48:51]
	v_mfma_f32_16x16x32_bf16 v[36:39], v[216:219], v[188:191], v[36:39]
	v_mfma_f32_16x16x32_bf16 v[32:35], v[224:227], v[188:191], v[32:35]
	v_mfma_f32_16x16x32_bf16 v[20:23], v[216:219], v[200:203], v[20:23]
	v_mfma_f32_16x16x32_bf16 v[12:15], v[224:227], v[200:203], v[12:15]
	v_mfma_f32_16x16x32_bf16 v[4:7], v[216:219], v[208:211], v[4:7]
	v_mfma_f32_16x16x32_bf16 v[0:3], v[224:227], v[208:211], v[0:3]
	s_setprio 0
	s_add_i32 s80, s80, 2
	s_add_u32 s40, s40, 0x100
	s_addc_u32 s41, s41, 0
	s_add_u32 s78, s78, 0x100
	s_addc_u32 s79, s79, 0
	s_cmp_gt_u32 s80, 13
	s_barrier
	s_cbranch_scc0 .LBB0_889
	v_add_u32_e32 v158, s33, v168
	v_ashrrev_i32_e32 v159, 31, v158
	v_readlane_b32 s40, v254, 56
	v_add_u32_e32 v128, s64, v170
	v_lshlrev_b64 v[130:131], 11, v[158:159]
	v_readlane_b32 s41, v254, 57
	v_ashrrev_i32_e32 v129, 31, v128
	s_nop 0
	v_lshl_add_u64 v[130:131], s[40:41], 0, v[130:131]
	v_lshl_add_u64 v[160:161], v[128:129], 1, v[130:131]
	v_add_co_u32_e32 v192, vcc, s68, v160
	global_load_dwordx4 v[132:135], v[160:161], off
	global_load_dwordx4 v[140:143], v[160:161], off offset:256
	v_addc_co_u32_e32 v193, vcc, 0, v161, vcc
	global_load_dwordx4 v[184:187], v[192:193], off
	v_lshl_add_u64 v[164:165], v[160:161], 0, s[22:23]
	global_load_dwordx4 v[188:191], v[164:165], off offset:256
	v_add_co_u32_e32 v166, vcc, s61, v160
	v_lshl_add_u64 v[162:163], v[160:161], 0, s[24:25]
	s_nop 0
	v_addc_co_u32_e32 v167, vcc, 0, v161, vcc
	global_load_dwordx4 v[136:139], v[166:167], off
	global_load_dwordx4 v[128:131], v[162:163], off offset:256
	s_mov_b32 s98, s67
	s_mov_b32 s99, 0
	v_lshl_add_u64 v[246:247], v[160:161], 0, s[98:99]
	global_load_dwordx4 v[206:209], v[246:247], off
	v_lshl_add_u64 v[246:247], v[160:161], 0, s[26:27]
	global_load_dwordx4 v[210:213], v[246:247], off offset:256
	s_mov_b32 s98, s72
	s_mov_b32 s99, 0
	v_lshl_add_u64 v[246:247], v[160:161], 0, s[98:99]
	global_load_dwordx4 v[214:217], v[246:247], off
	v_lshl_add_u64 v[246:247], v[160:161], 0, s[18:19]
	global_load_dwordx4 v[218:221], v[246:247], off offset:256
	s_mov_b32 s98, s73
	s_mov_b32 s99, 0
	v_lshl_add_u64 v[246:247], v[160:161], 0, s[98:99]
	global_load_dwordx4 v[222:225], v[246:247], off
	v_lshl_add_u64 v[246:247], v[160:161], 0, s[28:29]
	global_load_dwordx4 v[226:229], v[246:247], off offset:256
	s_mov_b32 s98, s74
	s_mov_b32 s99, 0
	v_lshl_add_u64 v[246:247], v[160:161], 0, s[98:99]
	global_load_dwordx4 v[230:233], v[246:247], off
	v_lshl_add_u64 v[246:247], v[160:161], 0, s[30:31]
	global_load_dwordx4 v[234:237], v[246:247], off offset:256
	s_mov_b32 s98, s75
	s_mov_b32 s99, 0
	v_lshl_add_u64 v[246:247], v[160:161], 0, s[98:99]
	global_load_dwordx4 v[238:241], v[246:247], off
	v_lshl_add_u64 v[246:247], v[160:161], 0, s[34:35]
	global_load_dwordx4 v[242:245], v[246:247], off offset:256
	s_waitcnt vmcnt(10)
	v_lshlrev_b32_e32 v194, 16, v132
	v_and_b32_e32 v195, 0xffff0000, v132
	v_lshlrev_b32_e32 v200, 16, v134
	v_and_b32_e32 v201, 0xffff0000, v134
	v_pk_add_f32 v[124:125], v[124:125], v[194:195]
	v_lshlrev_b32_e32 v194, 16, v184
	v_and_b32_e32 v195, 0xffff0000, v184
	v_pk_add_f32 v[120:121], v[120:121], v[200:201]
	v_lshlrev_b32_e32 v184, 16, v185
	v_and_b32_e32 v185, 0xffff0000, v185
	v_lshlrev_b32_e32 v200, 16, v186
	v_and_b32_e32 v201, 0xffff0000, v186
	v_lshlrev_b32_e32 v186, 16, v187
	v_and_b32_e32 v187, 0xffff0000, v187
	v_pk_add_f32 v[116:117], v[116:117], v[194:195]
	v_pk_add_f32 v[118:119], v[118:119], v[184:185]
	v_pk_add_f32 v[184:185], v[110:111], v[186:187]
	v_mul_f32_e32 v111, v117, v117
	v_fmac_f32_e32 v111, v116, v116
	v_lshlrev_b32_e32 v132, 16, v133
	v_and_b32_e32 v133, 0xffff0000, v133
	v_lshlrev_b32_e32 v202, 16, v140
	v_and_b32_e32 v203, 0xffff0000, v140
	v_lshlrev_b32_e32 v140, 16, v141
	v_and_b32_e32 v141, 0xffff0000, v141
	v_lshlrev_b32_e32 v204, 16, v142
	v_and_b32_e32 v205, 0xffff0000, v142
	v_lshlrev_b32_e32 v142, 16, v143
	v_and_b32_e32 v143, 0xffff0000, v143
	v_fmac_f32_e32 v111, v118, v118
	v_lshlrev_b32_e32 v134, 16, v135
	v_and_b32_e32 v135, 0xffff0000, v135
	v_pk_add_f32 v[126:127], v[126:127], v[132:133]
	v_pk_add_f32 v[132:133], v[114:115], v[140:141]
	v_pk_add_f32 v[140:141], v[106:107], v[142:143]
	v_cvt_pk_bf16_f32 v106, v120, v121
	v_pk_add_f32 v[108:109], v[108:109], v[200:201]
	v_fmac_f32_e32 v111, v119, v119
	v_pk_add_f32 v[122:123], v[122:123], v[134:135]
	v_pk_add_f32 v[134:135], v[112:113], v[202:203]
	v_pk_add_f32 v[142:143], v[104:105], v[204:205]
	v_cvt_pk_bf16_f32 v104, v124, v125
	v_cvt_pk_bf16_f32 v105, v126, v127
	v_cvt_pk_bf16_f32 v107, v122, v123
	v_cvt_pk_bf16_f32 v112, v134, v135
	v_cvt_pk_bf16_f32 v113, v132, v133
	s_nop 0
	v_cvt_pk_bf16_f32 v114, v142, v143
	v_cvt_pk_bf16_f32 v115, v140, v141
	global_store_dwordx4 v[160:161], v[104:107], off
	v_fmac_f32_e32 v111, v108, v108
	global_store_dwordx4 v[160:161], v[112:115], off offset:256
	v_cvt_pk_bf16_f32 v106, v108, v109
	v_add_co_u32_e32 v108, vcc, s67, v160
	v_cvt_pk_bf16_f32 v104, v116, v117
	v_cvt_pk_bf16_f32 v105, v118, v119
	v_cvt_pk_bf16_f32 v107, v184, v185
	v_fmac_f32_e32 v111, v109, v109
	v_lshlrev_b32_e32 v112, 16, v188
	v_and_b32_e32 v113, 0xffff0000, v188
	v_lshlrev_b32_e32 v114, 16, v189
	v_and_b32_e32 v115, 0xffff0000, v189
	v_lshlrev_b32_e32 v116, 16, v190
	v_addc_co_u32_e32 v109, vcc, 0, v161, vcc
	v_and_b32_e32 v117, 0xffff0000, v190
	global_store_dwordx4 v[192:193], v[104:107], off
	s_nop 0
	v_lshlrev_b32_e32 v118, 16, v191
	v_and_b32_e32 v119, 0xffff0000, v191
	v_pk_add_f32 v[102:103], v[102:103], v[114:115]
	v_pk_add_f32 v[100:101], v[100:101], v[112:113]
	v_pk_add_f32 v[114:115], v[96:97], v[116:117]
	v_cvt_pk_bf16_f32 v96, v100, v101
	v_pk_add_f32 v[112:113], v[98:99], v[118:119]
	v_cvt_pk_bf16_f32 v97, v102, v103
	v_cvt_pk_bf16_f32 v98, v114, v115
	v_fmac_f32_e32 v111, v184, v184
	v_cvt_pk_bf16_f32 v99, v112, v113
	global_store_dwordx4 v[164:165], v[96:99], off offset:256
	v_fmac_f32_e32 v111, v185, v185
	v_lshlrev_b32_e32 v116, 16, v138
	v_mul_f32_e32 v96, v101, v101
	v_fmac_f32_e32 v96, v100, v100
	v_fmac_f32_e32 v96, v102, v102
	v_fmac_f32_e32 v96, v103, v103
	v_fmac_f32_e32 v96, v114, v114
	v_fmac_f32_e32 v96, v115, v115
	v_fmac_f32_e32 v96, v112, v112
	v_fmac_f32_e32 v96, v113, v113
	v_lshl_add_u64 v[100:101], v[160:161], 0, s[26:27]
	v_add_f32_e32 v102, v111, v96
	s_nop 0
	v_lshlrev_b32_e32 v112, 16, v136
	v_and_b32_e32 v113, 0xffff0000, v136
	v_lshlrev_b32_e32 v114, 16, v137
	v_and_b32_e32 v115, 0xffff0000, v137
	v_and_b32_e32 v117, 0xffff0000, v138
	v_lshlrev_b32_e32 v118, 16, v139
	v_and_b32_e32 v119, 0xffff0000, v139
	v_pk_add_f32 v[94:95], v[94:95], v[114:115]
	v_pk_add_f32 v[92:93], v[92:93], v[112:113]
	v_pk_add_f32 v[114:115], v[88:89], v[116:117]
	v_cvt_pk_bf16_f32 v88, v92, v93
	v_pk_add_f32 v[112:113], v[90:91], v[118:119]
	v_cvt_pk_bf16_f32 v89, v94, v95
	v_cvt_pk_bf16_f32 v90, v114, v115
	v_mul_f32_e32 v103, v93, v93
	v_cvt_pk_bf16_f32 v91, v112, v113
	global_store_dwordx4 v[166:167], v[88:91], off
	v_fmac_f32_e32 v103, v92, v92
	v_fmac_f32_e32 v103, v94, v94
	v_add_co_u32_e32 v88, vcc, s72, v160
	v_fmac_f32_e32 v103, v95, v95
	s_nop 0
	v_addc_co_u32_e32 v89, vcc, 0, v161, vcc
	s_nop 0
	v_fmac_f32_e32 v103, v114, v114
	v_fmac_f32_e32 v103, v115, v115
	v_fmac_f32_e32 v103, v112, v112
	v_fmac_f32_e32 v103, v113, v113
	v_lshlrev_b32_e32 v94, 16, v128
	v_and_b32_e32 v95, 0xffff0000, v128
	v_lshlrev_b32_e32 v112, 16, v129
	v_and_b32_e32 v113, 0xffff0000, v129
	v_lshlrev_b32_e32 v114, 16, v130
	v_and_b32_e32 v115, 0xffff0000, v130
	v_lshlrev_b32_e32 v116, 16, v131
	v_and_b32_e32 v117, 0xffff0000, v131
	v_pk_add_f32 v[86:87], v[86:87], v[112:113]
	v_pk_add_f32 v[84:85], v[84:85], v[94:95]
	v_pk_add_f32 v[112:113], v[80:81], v[114:115]
	v_cvt_pk_bf16_f32 v80, v84, v85
	v_pk_add_f32 v[94:95], v[82:83], v[116:117]
	v_cvt_pk_bf16_f32 v81, v86, v87
	v_cvt_pk_bf16_f32 v82, v112, v113
	v_mul_f32_e32 v125, v125, v125
	v_cvt_pk_bf16_f32 v83, v94, v95
	global_store_dwordx4 v[162:163], v[80:83], off offset:256
	v_mul_f32_e32 v135, v135, v135
	v_fmac_f32_e32 v125, v124, v124
	v_mul_f32_e32 v80, v85, v85
	v_fmac_f32_e32 v80, v84, v84
	v_fmac_f32_e32 v80, v86, v86
	v_fmac_f32_e32 v80, v87, v87
	v_fmac_f32_e32 v80, v112, v112
	v_fmac_f32_e32 v80, v113, v113
	v_fmac_f32_e32 v80, v94, v94
	v_fmac_f32_e32 v80, v95, v95
	v_lshl_add_u64 v[84:85], v[160:161], 0, s[18:19]
	v_add_f32_e32 v86, v103, v80
	s_nop 0
	s_waitcnt vmcnt(12)
	s_nop 1
	v_mov_b32_e32 v104, v206
	v_mov_b32_e32 v105, v207
	v_mov_b32_e32 v106, v208
	v_mov_b32_e32 v107, v209
	v_mov_b32_e32 v96, v210
	v_mov_b32_e32 v97, v211
	v_mov_b32_e32 v98, v212
	v_mov_b32_e32 v99, v213
	v_mov_b32_e32 v90, v214
	v_mov_b32_e32 v91, v215
	v_mov_b32_e32 v92, v216
	v_mov_b32_e32 v93, v217
	v_mov_b32_e32 v80, v218
	v_mov_b32_e32 v81, v219
	v_mov_b32_e32 v82, v220
	v_mov_b32_e32 v83, v221
	v_lshlrev_b32_e32 v94, 16, v104
	v_and_b32_e32 v95, 0xffff0000, v104
	v_pk_add_f32 v[76:77], v[76:77], v[94:95]
	v_lshlrev_b32_e32 v104, 16, v105
	v_and_b32_e32 v105, 0xffff0000, v105
	v_mul_f32_e32 v87, v77, v77
	v_pk_add_f32 v[78:79], v[78:79], v[104:105]
	v_fmac_f32_e32 v87, v76, v76
	v_lshlrev_b32_e32 v112, 16, v106
	v_and_b32_e32 v113, 0xffff0000, v106
	v_fmac_f32_e32 v87, v78, v78
	v_pk_add_f32 v[104:105], v[72:73], v[112:113]
	v_fmac_f32_e32 v87, v79, v79
	v_lshlrev_b32_e32 v106, 16, v107
	v_and_b32_e32 v107, 0xffff0000, v107
	v_fmac_f32_e32 v87, v104, v104
	v_pk_add_f32 v[94:95], v[74:75], v[106:107]
	v_fmac_f32_e32 v87, v105, v105
	v_fmac_f32_e32 v87, v94, v94
	v_cvt_pk_bf16_f32 v73, v78, v79
	v_cvt_pk_bf16_f32 v75, v94, v95
	v_fmac_f32_e32 v87, v95, v95
	v_lshlrev_b32_e32 v78, 16, v96
	v_and_b32_e32 v79, 0xffff0000, v96
	v_lshlrev_b32_e32 v94, 16, v97
	v_and_b32_e32 v95, 0xffff0000, v97
	v_lshlrev_b32_e32 v96, 16, v98
	v_and_b32_e32 v97, 0xffff0000, v98
	v_cvt_pk_bf16_f32 v72, v76, v77
	v_add_co_u32_e32 v76, vcc, s73, v160
	v_lshlrev_b32_e32 v98, 16, v99
	v_and_b32_e32 v99, 0xffff0000, v99
	v_pk_add_f32 v[70:71], v[70:71], v[94:95]
	v_pk_add_f32 v[68:69], v[68:69], v[78:79]
	v_pk_add_f32 v[94:95], v[64:65], v[96:97]
	v_cvt_pk_bf16_f32 v64, v68, v69
	v_cvt_pk_bf16_f32 v74, v104, v105
	v_addc_co_u32_e32 v77, vcc, 0, v161, vcc
	v_pk_add_f32 v[78:79], v[66:67], v[98:99]
	v_cvt_pk_bf16_f32 v65, v70, v71
	v_cvt_pk_bf16_f32 v66, v94, v95
	global_store_dwordx4 v[108:109], v[72:75], off
	v_cvt_pk_bf16_f32 v67, v78, v79
	global_store_dwordx4 v[100:101], v[64:67], off offset:256
	s_nop 0
	v_fmac_f32_e32 v135, v134, v134
	v_mul_f32_e32 v64, v69, v69
	v_fmac_f32_e32 v64, v68, v68
	v_fmac_f32_e32 v64, v70, v70
	v_fmac_f32_e32 v64, v71, v71
	v_fmac_f32_e32 v64, v94, v94
	v_fmac_f32_e32 v64, v95, v95
	v_fmac_f32_e32 v64, v78, v78
	v_fmac_f32_e32 v64, v79, v79
	v_add_f32_e32 v68, v87, v64
	v_lshlrev_b32_e32 v64, 16, v91
	v_and_b32_e32 v65, 0xffff0000, v91
	v_lshl_add_u64 v[66:67], v[160:161], 0, s[28:29]
	v_lshlrev_b32_e32 v70, 16, v90
	v_and_b32_e32 v71, 0xffff0000, v90
	v_lshlrev_b32_e32 v78, 16, v92
	v_and_b32_e32 v79, 0xffff0000, v92
	v_lshlrev_b32_e32 v90, 16, v93
	v_and_b32_e32 v91, 0xffff0000, v93
	v_pk_add_f32 v[92:93], v[62:63], v[64:65]
	s_nop 0
	v_pk_add_f32 v[60:61], v[60:61], v[70:71]
	v_pk_add_f32 v[78:79], v[56:57], v[78:79]
	v_mul_f32_e32 v69, v61, v61
	v_fmac_f32_e32 v69, v60, v60
	v_fmac_f32_e32 v69, v92, v92
	v_fmac_f32_e32 v69, v93, v93
	v_fmac_f32_e32 v69, v78, v78
	v_pk_add_f32 v[70:71], v[58:59], v[90:91]
	v_fmac_f32_e32 v69, v79, v79
	v_fmac_f32_e32 v69, v70, v70
	v_cvt_pk_bf16_f32 v58, v78, v79
	v_cvt_pk_bf16_f32 v59, v70, v71
	v_fmac_f32_e32 v69, v71, v71
	v_lshlrev_b32_e32 v70, 16, v80
	v_and_b32_e32 v71, 0xffff0000, v80
	v_lshlrev_b32_e32 v78, 16, v81
	v_and_b32_e32 v79, 0xffff0000, v81
	v_lshlrev_b32_e32 v80, 16, v82
	v_and_b32_e32 v81, 0xffff0000, v82
	v_lshlrev_b32_e32 v82, 16, v83
	v_and_b32_e32 v83, 0xffff0000, v83
	v_pk_add_f32 v[54:55], v[54:55], v[78:79]
	v_pk_add_f32 v[52:53], v[52:53], v[70:71]
	v_pk_add_f32 v[78:79], v[48:49], v[80:81]
	v_cvt_pk_bf16_f32 v48, v52, v53
	v_pk_add_f32 v[70:71], v[50:51], v[82:83]
	v_cvt_pk_bf16_f32 v49, v54, v55
	v_cvt_pk_bf16_f32 v50, v78, v79
	v_cvt_pk_bf16_f32 v56, v60, v61
	v_add_co_u32_e32 v60, vcc, s74, v160
	v_cvt_pk_bf16_f32 v51, v70, v71
	global_store_dwordx4 v[84:85], v[48:51], off offset:256
	v_cvt_pk_bf16_f32 v57, v92, v93
	s_nop 0
	v_addc_co_u32_e32 v61, vcc, 0, v161, vcc
	v_mul_f32_e32 v48, v53, v53
	v_fmac_f32_e32 v48, v52, v52
	v_fmac_f32_e32 v48, v54, v54
	v_fmac_f32_e32 v48, v55, v55
	v_fmac_f32_e32 v48, v78, v78
	global_store_dwordx4 v[88:89], v[56:59], off
	s_nop 0
	v_fmac_f32_e32 v48, v79, v79
	v_fmac_f32_e32 v48, v70, v70
	v_fmac_f32_e32 v48, v71, v71
	v_add_f32_e32 v69, v69, v48
	v_lshl_add_u64 v[48:49], v[160:161], 0, s[30:31]
	s_nop 0
	v_fmac_f32_e32 v125, v126, v126
	v_fmac_f32_e32 v135, v132, v132
	v_fmac_f32_e32 v125, v127, v127
	v_fmac_f32_e32 v135, v133, v133
	v_fmac_f32_e32 v125, v120, v120
	v_fmac_f32_e32 v135, v142, v142
	v_fmac_f32_e32 v125, v121, v121
	v_fmac_f32_e32 v135, v143, v143
	v_fmac_f32_e32 v125, v122, v122
	s_waitcnt vmcnt(12)
	s_nop 1
	v_mov_b32_e32 v72, v222
	v_mov_b32_e32 v73, v223
	v_mov_b32_e32 v74, v224
	v_mov_b32_e32 v75, v225
	v_mov_b32_e32 v62, v226
	v_mov_b32_e32 v63, v227
	v_mov_b32_e32 v64, v228
	v_mov_b32_e32 v65, v229
	v_mov_b32_e32 v56, v230
	v_mov_b32_e32 v57, v231
	v_mov_b32_e32 v58, v232
	v_mov_b32_e32 v59, v233
	v_mov_b32_e32 v50, v234
	v_mov_b32_e32 v51, v235
	v_mov_b32_e32 v52, v236
	v_mov_b32_e32 v53, v237
	v_lshlrev_b32_e32 v54, 16, v72
	v_and_b32_e32 v55, 0xffff0000, v72
	v_lshlrev_b32_e32 v70, 16, v73
	v_and_b32_e32 v71, 0xffff0000, v73
	v_lshlrev_b32_e32 v72, 16, v74
	v_and_b32_e32 v73, 0xffff0000, v74
	v_pk_add_f32 v[44:45], v[44:45], v[54:55]
	v_pk_add_f32 v[46:47], v[46:47], v[70:71]
	v_pk_add_f32 v[70:71], v[40:41], v[72:73]
	v_mul_f32_e32 v72, v45, v45
	v_fmac_f32_e32 v72, v44, v44
	v_fmac_f32_e32 v72, v46, v46
	v_fmac_f32_e32 v72, v47, v47
	v_lshlrev_b32_e32 v74, 16, v75
	v_and_b32_e32 v75, 0xffff0000, v75
	v_cvt_pk_bf16_f32 v40, v44, v45
	v_fmac_f32_e32 v72, v70, v70
	v_add_co_u32_e32 v44, vcc, s75, v160
	v_pk_add_f32 v[54:55], v[42:43], v[74:75]
	v_cvt_pk_bf16_f32 v41, v46, v47
	v_cvt_pk_bf16_f32 v42, v70, v71
	v_fmac_f32_e32 v72, v71, v71
	v_cvt_pk_bf16_f32 v43, v54, v55
	v_addc_co_u32_e32 v45, vcc, 0, v161, vcc
	global_store_dwordx4 v[76:77], v[40:43], off
	v_fmac_f32_e32 v72, v54, v54
	s_nop 0
	v_lshlrev_b32_e32 v46, 16, v62
	v_and_b32_e32 v47, 0xffff0000, v62
	v_fmac_f32_e32 v72, v55, v55
	v_lshlrev_b32_e32 v54, 16, v63
	v_and_b32_e32 v55, 0xffff0000, v63
	v_lshlrev_b32_e32 v62, 16, v64
	v_and_b32_e32 v63, 0xffff0000, v64
	v_pk_add_f32 v[36:37], v[36:37], v[46:47]
	v_lshlrev_b32_e32 v64, 16, v65
	v_and_b32_e32 v65, 0xffff0000, v65
	v_pk_add_f32 v[38:39], v[38:39], v[54:55]
	v_pk_add_f32 v[54:55], v[32:33], v[62:63]
	v_mul_f32_e32 v62, v37, v37
	v_pk_add_f32 v[46:47], v[34:35], v[64:65]
	v_cvt_pk_bf16_f32 v32, v36, v37
	v_cvt_pk_bf16_f32 v33, v38, v39
	v_cvt_pk_bf16_f32 v34, v54, v55
	v_fmac_f32_e32 v62, v36, v36
	v_cvt_pk_bf16_f32 v35, v46, v47
	v_lshl_add_u64 v[36:37], v[160:161], 0, s[34:35]
	global_store_dwordx4 v[66:67], v[32:35], off offset:256
	s_nop 0
	v_fmac_f32_e32 v62, v38, v38
	v_fmac_f32_e32 v62, v39, v39
	v_fmac_f32_e32 v62, v54, v54
	v_fmac_f32_e32 v62, v55, v55
	v_fmac_f32_e32 v62, v46, v46
	v_fmac_f32_e32 v62, v47, v47
	v_fmac_f32_e32 v135, v140, v140
	v_fmac_f32_e32 v125, v123, v123
	v_fmac_f32_e32 v135, v141, v141
	v_add_f32_e32 v110, v125, v135
	v_add_f32_e32 v62, v72, v62
	v_lshlrev_b32_e32 v38, 16, v56
	v_and_b32_e32 v39, 0xffff0000, v56
	v_lshlrev_b32_e32 v46, 16, v57
	v_and_b32_e32 v47, 0xffff0000, v57
	v_lshlrev_b32_e32 v54, 16, v58
	v_and_b32_e32 v55, 0xffff0000, v58
	v_pk_add_f32 v[28:29], v[28:29], v[38:39]
	v_lshlrev_b32_e32 v56, 16, v59
	v_and_b32_e32 v57, 0xffff0000, v59
	v_pk_add_f32 v[30:31], v[30:31], v[46:47]
	v_pk_add_f32 v[46:47], v[24:25], v[54:55]
	v_mul_f32_e32 v54, v29, v29
	v_pk_add_f32 v[38:39], v[26:27], v[56:57]
	v_cvt_pk_bf16_f32 v24, v28, v29
	v_cvt_pk_bf16_f32 v25, v30, v31
	v_cvt_pk_bf16_f32 v26, v46, v47
	v_fmac_f32_e32 v54, v28, v28
	v_cvt_pk_bf16_f32 v27, v38, v39
	global_store_dwordx4 v[60:61], v[24:27], off
	v_fmac_f32_e32 v54, v30, v30
	v_lshlrev_b32_e32 v28, 16, v52
	v_lshlrev_b32_e32 v24, 16, v50
	v_and_b32_e32 v25, 0xffff0000, v50
	v_lshlrev_b32_e32 v26, 16, v51
	v_and_b32_e32 v27, 0xffff0000, v51
	v_and_b32_e32 v29, 0xffff0000, v52
	v_fmac_f32_e32 v54, v31, v31
	v_lshlrev_b32_e32 v30, 16, v53
	v_and_b32_e32 v31, 0xffff0000, v53
	v_pk_add_f32 v[22:23], v[22:23], v[26:27]
	v_pk_add_f32 v[20:21], v[20:21], v[24:25]
	v_pk_add_f32 v[26:27], v[12:13], v[28:29]
	v_cvt_pk_bf16_f32 v12, v20, v21
	v_pk_add_f32 v[24:25], v[14:15], v[30:31]
	v_cvt_pk_bf16_f32 v13, v22, v23
	v_cvt_pk_bf16_f32 v14, v26, v27
	v_fmac_f32_e32 v54, v46, v46
	v_cvt_pk_bf16_f32 v15, v24, v25
	global_store_dwordx4 v[48:49], v[12:15], off offset:256
	v_fmac_f32_e32 v54, v47, v47
	v_fmac_f32_e32 v54, v38, v38
	v_mul_f32_e32 v12, v21, v21
	v_fmac_f32_e32 v12, v20, v20
	v_fmac_f32_e32 v12, v22, v22
	v_fmac_f32_e32 v12, v23, v23
	v_fmac_f32_e32 v12, v26, v26
	v_fmac_f32_e32 v12, v27, v27
	v_fmac_f32_e32 v12, v24, v24
	v_fmac_f32_e32 v54, v39, v39
	v_fmac_f32_e32 v12, v25, v25
	v_add_f32_e32 v24, v54, v12
	s_waitcnt vmcnt(14)
	s_nop 1
	v_mov_b32_e32 v40, v238
	v_mov_b32_e32 v41, v239
	v_mov_b32_e32 v42, v240
	v_mov_b32_e32 v43, v241
	v_mov_b32_e32 v32, v242
	v_mov_b32_e32 v33, v243
	v_mov_b32_e32 v34, v244
	v_mov_b32_e32 v35, v245
	v_lshlrev_b32_e32 v12, 16, v40
	v_and_b32_e32 v13, 0xffff0000, v40
	v_pk_add_f32 v[12:13], v[16:17], v[12:13]
	v_lshlrev_b32_e32 v14, 16, v41
	v_and_b32_e32 v15, 0xffff0000, v41
	v_lshlrev_b32_e32 v20, 16, v42
	v_and_b32_e32 v21, 0xffff0000, v42
	v_mul_f32_e32 v25, v13, v13
	v_lshlrev_b32_e32 v22, 16, v43
	v_and_b32_e32 v23, 0xffff0000, v43
	v_pk_add_f32 v[14:15], v[18:19], v[14:15]
	v_pk_add_f32 v[18:19], v[8:9], v[20:21]
	v_cvt_pk_bf16_f32 v8, v12, v13
	v_cvt_pk_bf16_f32 v9, v14, v15
	v_fmac_f32_e32 v25, v12, v12
	v_pk_add_f32 v[16:17], v[10:11], v[22:23]
	v_cvt_pk_bf16_f32 v10, v18, v19
	v_fmac_f32_e32 v25, v14, v14
	v_cvt_pk_bf16_f32 v11, v16, v17
	global_store_dwordx4 v[44:45], v[8:11], off
	v_fmac_f32_e32 v25, v15, v15
	v_lshlrev_b32_e32 v12, 16, v34
	v_lshlrev_b32_e32 v8, 16, v32
	v_and_b32_e32 v9, 0xffff0000, v32
	v_and_b32_e32 v13, 0xffff0000, v34
	v_pk_add_f32 v[4:5], v[4:5], v[8:9]
	v_fmac_f32_e32 v25, v18, v18
	v_lshlrev_b32_e32 v10, 16, v33
	v_and_b32_e32 v11, 0xffff0000, v33
	v_pk_add_f32 v[22:23], v[0:1], v[12:13]
	v_mul_f32_e32 v0, v5, v5
	v_fmac_f32_e32 v25, v19, v19
	v_pk_add_f32 v[18:19], v[6:7], v[10:11]
	v_fmac_f32_e32 v0, v4, v4
	v_fmac_f32_e32 v0, v18, v18
	v_fmac_f32_e32 v0, v19, v19
	v_lshlrev_b32_e32 v14, 16, v35
	v_and_b32_e32 v15, 0xffff0000, v35
	v_fmac_f32_e32 v0, v22, v22
	v_pk_add_f32 v[20:21], v[2:3], v[14:15]
	v_fmac_f32_e32 v0, v23, v23
	v_fmac_f32_e32 v25, v16, v16
	v_fmac_f32_e32 v0, v20, v20
	v_fmac_f32_e32 v25, v17, v17
	v_fmac_f32_e32 v0, v21, v21
	v_add_f32_e32 v14, v25, v0
	v_cvt_pk_bf16_f32 v16, v4, v5
	ds_bpermute_b32 v1, v171, v110
	ds_bpermute_b32 v2, v171, v102
	ds_bpermute_b32 v4, v171, v86
	ds_bpermute_b32 v6, v171, v68
	ds_bpermute_b32 v8, v171, v69
	ds_bpermute_b32 v10, v171, v62
	ds_bpermute_b32 v12, v171, v24
	ds_bpermute_b32 v15, v171, v14
	s_waitcnt lgkmcnt(0)
	v_add_f32_e32 v0, v110, v1
	v_add_f32_e32 v2, v102, v2
	v_add_f32_e32 v4, v86, v4
	v_add_f32_e32 v6, v68, v6
	v_add_f32_e32 v8, v69, v8
	v_add_f32_e32 v10, v62, v10
	v_add_f32_e32 v12, v24, v12
	v_add_f32_e32 v14, v14, v15
	ds_bpermute_b32 v1, v172, v0
	ds_bpermute_b32 v3, v172, v2
	ds_bpermute_b32 v5, v172, v4
	ds_bpermute_b32 v7, v172, v6
	ds_bpermute_b32 v9, v172, v8
	ds_bpermute_b32 v11, v172, v10
	ds_bpermute_b32 v13, v172, v12
	ds_bpermute_b32 v15, v172, v14
	v_cvt_pk_bf16_f32 v17, v18, v19
	v_cvt_pk_bf16_f32 v18, v22, v23
	v_cvt_pk_bf16_f32 v19, v20, v21
	global_store_dwordx4 v[36:37], v[16:19], off offset:256
	s_and_saveexec_b64 s[40:41], s[4:5]
	s_cbranch_execz .LBB0_892
	s_waitcnt lgkmcnt(6)
	v_add_f32_e32 v2, v2, v3
	v_add_f32_e32 v0, v0, v1
	v_add_u32_e32 v1, s69, v173
	s_waitcnt lgkmcnt(2)
	v_add_f32_e32 v10, v10, v11
	v_add_f32_e32 v8, v8, v9
	v_add_f32_e32 v6, v6, v7
	v_add_f32_e32 v4, v4, v5
	ds_write2st64_b32 v1, v0, v2 offset1:1
	ds_write2st64_b32 v1, v4, v6 offset0:2 offset1:3
	v_add_u32_e32 v0, s69, v177
	s_waitcnt lgkmcnt(2)
	v_add_f32_e32 v14, v14, v15
	v_add_f32_e32 v12, v12, v13
	ds_write2st64_b32 v0, v8, v10 offset1:1
	ds_write2st64_b32 v0, v12, v14 offset0:2 offset1:3

.LBB0_955:
	s_add_u32 s42, s40, 0xfff00080
	s_addc_u32 s43, s41, -1
	s_add_i32 s83, 0, 0x10000
	v_add_u32_e32 v140, s83, v179
	ds_read_b128 v[128:131], v140
	ds_read_b128 v[132:135], v140 offset:1024
	ds_read_b128 v[136:139], v140 offset:2048
	ds_read_b128 v[140:143], v140 offset:3072
	s_cmp_eq_u32 s82, 60
	s_cselect_b32 s45, s37, s43
	s_cselect_b32 s44, s36, s42
	s_cselect_b32 s43, s39, s81
	s_cselect_b32 s42, s38, s80
	v_lshl_add_u64 v[212:213], s[40:41], 0, v[160:161]
	s_add_i32 m0, s69, 0xc000
	ds_read_b128 v[144:147], v191
	ds_read_b128 v[164:167], v191 offset:1024
	ds_read_b128 v[168:171], v191 offset:2048
	ds_read_b128 v[172:175], v191 offset:3072
	ds_read_b128 v[192:195], v191 offset:4096
	ds_read_b128 v[200:203], v191 offset:5120
	ds_read_b128 v[204:207], v191 offset:6144
	ds_read_b128 v[208:211], v191 offset:7168
	global_load_lds_dwordx4 v[212:213], off
	v_lshl_add_u64 v[212:213], s[40:41], 0, v[162:163]
	s_add_i32 m0, s69, 0xe000
	s_nop 0
	global_load_lds_dwordx4 v[212:213], off
	s_waitcnt lgkmcnt(8)
	s_barrier
	s_waitcnt lgkmcnt(0)
	s_setprio 1
	s_waitcnt lgkmcnt(0)
	v_mfma_f32_16x16x32_bf16 v[124:127], v[128:131], v[144:147], v[124:127]
	v_mfma_f32_16x16x32_bf16 v[120:123], v[136:139], v[144:147], v[120:123]
	v_mfma_f32_16x16x32_bf16 v[116:119], v[128:131], v[168:171], v[116:119]
	v_mfma_f32_16x16x32_bf16 v[108:111], v[136:139], v[168:171], v[108:111]
	v_mfma_f32_16x16x32_bf16 v[92:95], v[128:131], v[192:195], v[92:95]
	v_mfma_f32_16x16x32_bf16 v[88:91], v[136:139], v[192:195], v[88:91]
	v_mfma_f32_16x16x32_bf16 v[76:79], v[128:131], v[204:207], v[76:79]
	v_mfma_f32_16x16x32_bf16 v[72:75], v[136:139], v[204:207], v[72:75]
	v_mfma_f32_16x16x32_bf16 v[124:127], v[132:135], v[164:167], v[124:127]
	v_mfma_f32_16x16x32_bf16 v[120:123], v[140:143], v[164:167], v[120:123]
	v_mfma_f32_16x16x32_bf16 v[116:119], v[132:135], v[172:175], v[116:119]
	v_mfma_f32_16x16x32_bf16 v[108:111], v[140:143], v[172:175], v[108:111]
	v_mfma_f32_16x16x32_bf16 v[92:95], v[132:135], v[200:203], v[92:95]
	v_mfma_f32_16x16x32_bf16 v[88:91], v[140:143], v[200:203], v[88:91]
	v_mfma_f32_16x16x32_bf16 v[76:79], v[132:135], v[208:211], v[76:79]
	v_mfma_f32_16x16x32_bf16 v[72:75], v[140:143], v[208:211], v[72:75]
	s_setprio 0
	s_barrier
	s_add_i32 s86, 0, 0x14000
	s_add_i32 s83, s83, s68
	v_add_u32_e32 v199, s86, v179
	v_lshl_add_u64 v[228:229], s[42:43], 0, v[158:159]
	s_mov_b32 m0, s83
	ds_read_b128 v[212:215], v199
	ds_read_b128 v[216:219], v199 offset:1024
	ds_read_b128 v[220:223], v199 offset:2048
	ds_read_b128 v[224:227], v199 offset:3072
	global_load_lds_dwordx4 v[228:229], off
	v_lshl_add_u64 v[230:231], s[42:43], 0, v[154:155]
	s_add_i32 m0, s83, 0x2000
	s_nop 0
	global_load_lds_dwordx4 v[230:231], off
	s_barrier
	s_waitcnt lgkmcnt(0)
	s_setprio 1
	s_waitcnt lgkmcnt(0)
	v_mfma_f32_16x16x32_bf16 v[112:115], v[212:215], v[144:147], v[112:115]
	v_mfma_f32_16x16x32_bf16 v[104:107], v[220:223], v[144:147], v[104:107]
	v_mfma_f32_16x16x32_bf16 v[100:103], v[212:215], v[168:171], v[100:103]
	v_mfma_f32_16x16x32_bf16 v[96:99], v[220:223], v[168:171], v[96:99]
	v_mfma_f32_16x16x32_bf16 v[84:87], v[212:215], v[192:195], v[84:87]
	v_mfma_f32_16x16x32_bf16 v[80:83], v[220:223], v[192:195], v[80:83]
	v_mfma_f32_16x16x32_bf16 v[68:71], v[212:215], v[204:207], v[68:71]
	v_mfma_f32_16x16x32_bf16 v[64:67], v[220:223], v[204:207], v[64:67]
	v_mfma_f32_16x16x32_bf16 v[112:115], v[216:219], v[164:167], v[112:115]
	v_mfma_f32_16x16x32_bf16 v[104:107], v[224:227], v[164:167], v[104:107]
	v_mfma_f32_16x16x32_bf16 v[100:103], v[216:219], v[172:175], v[100:103]
	v_mfma_f32_16x16x32_bf16 v[96:99], v[224:227], v[172:175], v[96:99]
	v_mfma_f32_16x16x32_bf16 v[84:87], v[216:219], v[200:203], v[84:87]
	v_mfma_f32_16x16x32_bf16 v[80:83], v[224:227], v[200:203], v[80:83]
	v_mfma_f32_16x16x32_bf16 v[68:71], v[216:219], v[208:211], v[68:71]
	v_mfma_f32_16x16x32_bf16 v[64:67], v[224:227], v[208:211], v[64:67]
	s_setprio 0
	s_mov_b32 m0, s69
	v_lshl_add_u64 v[232:233], s[44:45], 0, v[148:149]
	s_barrier
	ds_read_b128 v[144:147], v191 offset:16384
	ds_read_b128 v[164:167], v191 offset:17408
	ds_read_b128 v[168:171], v191 offset:18432
	ds_read_b128 v[172:175], v191 offset:19456
	ds_read_b128 v[192:195], v191 offset:20480
	ds_read_b128 v[200:203], v191 offset:21504
	ds_read_b128 v[204:207], v191 offset:22528
	ds_read_b128 v[208:211], v191 offset:23552
	global_load_lds_dwordx4 v[232:233], off
	v_lshl_add_u64 v[234:235], s[44:45], 0, v[156:157]
	s_mov_b32 m0, s70
	s_nop 0
	global_load_lds_dwordx4 v[234:235], off
	s_barrier
	s_waitcnt lgkmcnt(0)
	s_setprio 1
	s_waitcnt lgkmcnt(0)
	v_mfma_f32_16x16x32_bf16 v[60:63], v[128:131], v[144:147], v[60:63]
	v_mfma_f32_16x16x32_bf16 v[56:59], v[136:139], v[144:147], v[56:59]
	v_mfma_f32_16x16x32_bf16 v[44:47], v[128:131], v[168:171], v[44:47]
	v_mfma_f32_16x16x32_bf16 v[40:43], v[136:139], v[168:171], v[40:43]
	v_mfma_f32_16x16x32_bf16 v[28:31], v[128:131], v[192:195], v[28:31]
	v_mfma_f32_16x16x32_bf16 v[24:27], v[136:139], v[192:195], v[24:27]
	v_mfma_f32_16x16x32_bf16 v[16:19], v[128:131], v[204:207], v[16:19]
	v_mfma_f32_16x16x32_bf16 v[8:11], v[136:139], v[204:207], v[8:11]
	v_mfma_f32_16x16x32_bf16 v[60:63], v[132:135], v[164:167], v[60:63]
	v_mfma_f32_16x16x32_bf16 v[56:59], v[140:143], v[164:167], v[56:59]
	v_mfma_f32_16x16x32_bf16 v[44:47], v[132:135], v[172:175], v[44:47]
	v_mfma_f32_16x16x32_bf16 v[40:43], v[140:143], v[172:175], v[40:43]
	v_mfma_f32_16x16x32_bf16 v[28:31], v[132:135], v[200:203], v[28:31]
	v_mfma_f32_16x16x32_bf16 v[24:27], v[140:143], v[200:203], v[24:27]
	v_mfma_f32_16x16x32_bf16 v[16:19], v[132:135], v[208:211], v[16:19]
	v_mfma_f32_16x16x32_bf16 v[8:11], v[140:143], v[208:211], v[8:11]
	s_setprio 0
	s_barrier
	s_add_u32 s84, s42, 0x100000
	s_addc_u32 s85, s43, 0
	s_add_i32 s83, s86, s68
	v_lshl_add_u64 v[128:129], s[84:85], 0, v[158:159]
	s_mov_b32 m0, s83
	s_nop 0
	global_load_lds_dwordx4 v[128:129], off
	v_lshl_add_u64 v[128:129], s[84:85], 0, v[154:155]
	s_add_i32 m0, s83, 0x2000
	s_nop 0
	global_load_lds_dwordx4 v[128:129], off
	s_waitcnt vmcnt(6)
	s_barrier
	s_setprio 1
	v_mfma_f32_16x16x32_bf16 v[52:55], v[212:215], v[144:147], v[52:55]
	v_mfma_f32_16x16x32_bf16 v[48:51], v[220:223], v[144:147], v[48:51]
	v_mfma_f32_16x16x32_bf16 v[36:39], v[212:215], v[168:171], v[36:39]
	v_mfma_f32_16x16x32_bf16 v[32:35], v[220:223], v[168:171], v[32:35]
	v_mfma_f32_16x16x32_bf16 v[20:23], v[212:215], v[192:195], v[20:23]
	v_mfma_f32_16x16x32_bf16 v[12:15], v[220:223], v[192:195], v[12:15]
	v_mfma_f32_16x16x32_bf16 v[4:7], v[212:215], v[204:207], v[4:7]
	v_mfma_f32_16x16x32_bf16 v[0:3], v[220:223], v[204:207], v[0:3]
	v_mfma_f32_16x16x32_bf16 v[52:55], v[216:219], v[164:167], v[52:55]
	v_mfma_f32_16x16x32_bf16 v[48:51], v[224:227], v[164:167], v[48:51]
	v_mfma_f32_16x16x32_bf16 v[36:39], v[216:219], v[172:175], v[36:39]
	v_mfma_f32_16x16x32_bf16 v[32:35], v[224:227], v[172:175], v[32:35]
	v_mfma_f32_16x16x32_bf16 v[20:23], v[216:219], v[200:203], v[20:23]
	v_mfma_f32_16x16x32_bf16 v[12:15], v[224:227], v[200:203], v[12:15]
	v_mfma_f32_16x16x32_bf16 v[4:7], v[216:219], v[208:211], v[4:7]
	v_mfma_f32_16x16x32_bf16 v[0:3], v[224:227], v[208:211], v[0:3]
	s_setprio 0
	s_add_i32 s83, 0, 0x18000
	v_add_u32_e32 v140, s83, v179
	s_barrier
	ds_read_b128 v[128:131], v140
	ds_read_b128 v[132:135], v140 offset:1024
	ds_read_b128 v[136:139], v140 offset:2048
	ds_read_b128 v[140:143], v140 offset:3072
	s_add_u32 s44, s44, 0x100000
	s_addc_u32 s45, s45, 0
	s_mov_b32 m0, s71
	v_lshl_add_u64 v[212:213], s[44:45], 0, v[148:149]
	ds_read_b128 v[144:147], v191 offset:32768
	ds_read_b128 v[164:167], v191 offset:33792
	ds_read_b128 v[168:171], v191 offset:34816
	ds_read_b128 v[172:175], v191 offset:35840
	ds_read_b128 v[192:195], v191 offset:36864
	ds_read_b128 v[200:203], v191 offset:37888
	ds_read_b128 v[204:207], v191 offset:38912
	ds_read_b128 v[208:211], v191 offset:39936
	global_load_lds_dwordx4 v[212:213], off
	v_lshl_add_u64 v[212:213], s[44:45], 0, v[156:157]
	s_mov_b32 m0, s72
	s_nop 0
	global_load_lds_dwordx4 v[212:213], off
	s_waitcnt lgkmcnt(8)
	s_barrier
	s_waitcnt lgkmcnt(0)
	s_setprio 1
	s_waitcnt lgkmcnt(0)
	v_mfma_f32_16x16x32_bf16 v[124:127], v[128:131], v[144:147], v[124:127]
	v_mfma_f32_16x16x32_bf16 v[120:123], v[136:139], v[144:147], v[120:123]
	v_mfma_f32_16x16x32_bf16 v[116:119], v[128:131], v[168:171], v[116:119]
	v_mfma_f32_16x16x32_bf16 v[108:111], v[136:139], v[168:171], v[108:111]
	v_mfma_f32_16x16x32_bf16 v[92:95], v[128:131], v[192:195], v[92:95]
	v_mfma_f32_16x16x32_bf16 v[88:91], v[136:139], v[192:195], v[88:91]
	v_mfma_f32_16x16x32_bf16 v[76:79], v[128:131], v[204:207], v[76:79]
	v_mfma_f32_16x16x32_bf16 v[72:75], v[136:139], v[204:207], v[72:75]
	v_mfma_f32_16x16x32_bf16 v[124:127], v[132:135], v[164:167], v[124:127]
	v_mfma_f32_16x16x32_bf16 v[120:123], v[140:143], v[164:167], v[120:123]
	v_mfma_f32_16x16x32_bf16 v[116:119], v[132:135], v[172:175], v[116:119]
	v_mfma_f32_16x16x32_bf16 v[108:111], v[140:143], v[172:175], v[108:111]
	v_mfma_f32_16x16x32_bf16 v[92:95], v[132:135], v[200:203], v[92:95]
	v_mfma_f32_16x16x32_bf16 v[88:91], v[140:143], v[200:203], v[88:91]
	v_mfma_f32_16x16x32_bf16 v[76:79], v[132:135], v[208:211], v[76:79]
	v_mfma_f32_16x16x32_bf16 v[72:75], v[140:143], v[208:211], v[72:75]
	s_setprio 0
	s_barrier
	s_add_i32 s44, 0, 0x1c000
	s_add_i32 s45, s83, s68
	v_add_u32_e32 v199, s44, v179
	v_lshl_add_u64 v[228:229], v[228:229], 0, s[26:27]
	s_mov_b32 m0, s45
	ds_read_b128 v[212:215], v199
	ds_read_b128 v[216:219], v199 offset:1024
	ds_read_b128 v[220:223], v199 offset:2048
	ds_read_b128 v[224:227], v199 offset:3072
	global_load_lds_dwordx4 v[228:229], off
	v_lshl_add_u64 v[228:229], v[230:231], 0, s[26:27]
	s_add_i32 m0, s45, 0x2000
	s_nop 0
	global_load_lds_dwordx4 v[228:229], off
	s_barrier
	s_waitcnt lgkmcnt(0)
	s_setprio 1
	s_waitcnt lgkmcnt(0)
	v_mfma_f32_16x16x32_bf16 v[112:115], v[212:215], v[144:147], v[112:115]
	v_mfma_f32_16x16x32_bf16 v[104:107], v[220:223], v[144:147], v[104:107]
	v_mfma_f32_16x16x32_bf16 v[100:103], v[212:215], v[168:171], v[100:103]
	v_mfma_f32_16x16x32_bf16 v[96:99], v[220:223], v[168:171], v[96:99]
	v_mfma_f32_16x16x32_bf16 v[84:87], v[212:215], v[192:195], v[84:87]
	v_mfma_f32_16x16x32_bf16 v[80:83], v[220:223], v[192:195], v[80:83]
	v_mfma_f32_16x16x32_bf16 v[68:71], v[212:215], v[204:207], v[68:71]
	v_mfma_f32_16x16x32_bf16 v[64:67], v[220:223], v[204:207], v[64:67]
	v_mfma_f32_16x16x32_bf16 v[112:115], v[216:219], v[164:167], v[112:115]
	v_mfma_f32_16x16x32_bf16 v[104:107], v[224:227], v[164:167], v[104:107]
	v_mfma_f32_16x16x32_bf16 v[100:103], v[216:219], v[172:175], v[100:103]
	v_mfma_f32_16x16x32_bf16 v[96:99], v[224:227], v[172:175], v[96:99]
	v_mfma_f32_16x16x32_bf16 v[84:87], v[216:219], v[200:203], v[84:87]
	v_mfma_f32_16x16x32_bf16 v[80:83], v[224:227], v[200:203], v[80:83]
	v_mfma_f32_16x16x32_bf16 v[68:71], v[216:219], v[208:211], v[68:71]
	v_mfma_f32_16x16x32_bf16 v[64:67], v[224:227], v[208:211], v[64:67]
	s_setprio 0
	s_mov_b32 m0, s73
	v_lshl_add_u64 v[228:229], v[232:233], 0, s[26:27]
	s_barrier
	ds_read_b128 v[144:147], v191 offset:49152
	ds_read_b128 v[164:167], v191 offset:50176
	ds_read_b128 v[168:171], v191 offset:51200
	ds_read_b128 v[172:175], v191 offset:52224
	ds_read_b128 v[192:195], v191 offset:53248
	ds_read_b128 v[200:203], v191 offset:54272
	ds_read_b128 v[204:207], v191 offset:55296
	ds_read_b128 v[208:211], v191 offset:56320
	global_load_lds_dwordx4 v[228:229], off
	v_lshl_add_u64 v[228:229], v[234:235], 0, s[26:27]
	s_mov_b32 m0, s74
	s_nop 0
	global_load_lds_dwordx4 v[228:229], off
	s_barrier
	s_waitcnt lgkmcnt(0)
	s_setprio 1
	s_waitcnt lgkmcnt(0)
	v_mfma_f32_16x16x32_bf16 v[60:63], v[128:131], v[144:147], v[60:63]
	v_mfma_f32_16x16x32_bf16 v[56:59], v[136:139], v[144:147], v[56:59]
	v_mfma_f32_16x16x32_bf16 v[44:47], v[128:131], v[168:171], v[44:47]
	v_mfma_f32_16x16x32_bf16 v[40:43], v[136:139], v[168:171], v[40:43]
	v_mfma_f32_16x16x32_bf16 v[28:31], v[128:131], v[192:195], v[28:31]
	v_mfma_f32_16x16x32_bf16 v[24:27], v[136:139], v[192:195], v[24:27]
	v_mfma_f32_16x16x32_bf16 v[16:19], v[128:131], v[204:207], v[16:19]
	v_mfma_f32_16x16x32_bf16 v[8:11], v[136:139], v[204:207], v[8:11]
	v_mfma_f32_16x16x32_bf16 v[60:63], v[132:135], v[164:167], v[60:63]
	v_mfma_f32_16x16x32_bf16 v[56:59], v[140:143], v[164:167], v[56:59]
	v_mfma_f32_16x16x32_bf16 v[44:47], v[132:135], v[172:175], v[44:47]
	v_mfma_f32_16x16x32_bf16 v[40:43], v[140:143], v[172:175], v[40:43]
	v_mfma_f32_16x16x32_bf16 v[28:31], v[132:135], v[200:203], v[28:31]
	v_mfma_f32_16x16x32_bf16 v[24:27], v[140:143], v[200:203], v[24:27]
	v_mfma_f32_16x16x32_bf16 v[16:19], v[132:135], v[208:211], v[16:19]
	v_mfma_f32_16x16x32_bf16 v[8:11], v[140:143], v[208:211], v[8:11]
	s_setprio 0
	s_barrier
	s_add_u32 s42, s42, 0x100080
	s_addc_u32 s43, s43, 0
	s_add_i32 s44, s44, s68
	v_lshl_add_u64 v[128:129], s[42:43], 0, v[158:159]
	s_mov_b32 m0, s44
	s_nop 0
	global_load_lds_dwordx4 v[128:129], off
	v_lshl_add_u64 v[128:129], s[42:43], 0, v[154:155]
	s_add_i32 m0, s44, 0x2000
	s_nop 0
	global_load_lds_dwordx4 v[128:129], off
	s_waitcnt vmcnt(6)
	s_barrier
	s_setprio 1
	v_mfma_f32_16x16x32_bf16 v[52:55], v[212:215], v[144:147], v[52:55]
	v_mfma_f32_16x16x32_bf16 v[48:51], v[220:223], v[144:147], v[48:51]
	v_mfma_f32_16x16x32_bf16 v[36:39], v[212:215], v[168:171], v[36:39]
	v_mfma_f32_16x16x32_bf16 v[32:35], v[220:223], v[168:171], v[32:35]
	v_mfma_f32_16x16x32_bf16 v[20:23], v[212:215], v[192:195], v[20:23]
	v_mfma_f32_16x16x32_bf16 v[12:15], v[220:223], v[192:195], v[12:15]
	v_mfma_f32_16x16x32_bf16 v[4:7], v[212:215], v[204:207], v[4:7]
	v_mfma_f32_16x16x32_bf16 v[0:3], v[220:223], v[204:207], v[0:3]
	v_mfma_f32_16x16x32_bf16 v[52:55], v[216:219], v[164:167], v[52:55]
	v_mfma_f32_16x16x32_bf16 v[48:51], v[224:227], v[164:167], v[48:51]
	v_mfma_f32_16x16x32_bf16 v[36:39], v[216:219], v[172:175], v[36:39]
	v_mfma_f32_16x16x32_bf16 v[32:35], v[224:227], v[172:175], v[32:35]
	v_mfma_f32_16x16x32_bf16 v[20:23], v[216:219], v[200:203], v[20:23]
	v_mfma_f32_16x16x32_bf16 v[12:15], v[224:227], v[200:203], v[12:15]
	v_mfma_f32_16x16x32_bf16 v[4:7], v[216:219], v[208:211], v[4:7]
	v_mfma_f32_16x16x32_bf16 v[0:3], v[224:227], v[208:211], v[0:3]
	s_setprio 0
	s_add_i32 s82, s82, 2
	s_add_u32 s40, s40, 0x100
	s_addc_u32 s41, s41, 0
	s_add_u32 s80, s80, 0x100
	s_addc_u32 s81, s81, 0
	s_cmp_gt_u32 s82, 61
	s_barrier
	s_cbranch_scc0 .LBB0_955
	v_add_u32_e32 v164, s33, v178
	v_ashrrev_i32_e32 v165, 31, v164
	v_readlane_b32 s40, v254, 56
	v_add_u32_e32 v128, s77, v180
	v_lshlrev_b64 v[130:131], 11, v[164:165]
	v_readlane_b32 s41, v254, 57
	v_ashrrev_i32_e32 v129, 31, v128
	s_mov_b32 s33, 0x8000
	v_lshl_add_u64 v[130:131], s[40:41], 0, v[130:131]
	v_lshl_add_u64 v[166:167], v[128:129], 1, v[130:131]
	v_add_co_u32_e32 v174, vcc, s33, v166
	global_load_dwordx4 v[136:139], v[166:167], off
	global_load_dwordx4 v[140:143], v[166:167], off offset:256
	v_addc_co_u32_e32 v175, vcc, 0, v167, vcc
	global_load_dwordx4 v[144:147], v[174:175], off
	s_mov_b64 s[40:41], 0x8000
	v_lshl_add_u64 v[172:173], v[166:167], 0, s[40:41]
	global_load_dwordx4 v[192:195], v[172:173], off offset:256
	s_mov_b32 s33, 0x10000
	v_add_co_u32_e32 v170, vcc, s33, v166
	s_mov_b64 s[42:43], 0x10000
	s_nop 0
	v_addc_co_u32_e32 v171, vcc, 0, v167, vcc
	v_lshl_add_u64 v[168:169], v[166:167], 0, s[42:43]
	global_load_dwordx4 v[128:131], v[170:171], off
	global_load_dwordx4 v[132:135], v[168:169], off offset:256
	s_mov_b32 s98, 0x18000
	s_mov_b32 s99, 0
	v_lshl_add_u64 v[248:249], v[166:167], 0, s[98:99]
	global_load_dwordx4 v[208:211], v[248:249], off
	s_mov_b64 s[98:99], 0x18000
	v_lshl_add_u64 v[248:249], v[166:167], 0, s[98:99]
	global_load_dwordx4 v[212:215], v[248:249], off offset:256
	s_mov_b32 s98, 0x40000
	s_mov_b32 s99, 0
	v_lshl_add_u64 v[248:249], v[166:167], 0, s[98:99]
	global_load_dwordx4 v[216:219], v[248:249], off
	s_mov_b64 s[98:99], 0x40000
	v_lshl_add_u64 v[248:249], v[166:167], 0, s[98:99]
	global_load_dwordx4 v[220:223], v[248:249], off offset:256
	s_mov_b32 s98, 0x48000
	s_mov_b32 s99, 0
	v_lshl_add_u64 v[248:249], v[166:167], 0, s[98:99]
	global_load_dwordx4 v[224:227], v[248:249], off
	s_mov_b64 s[98:99], 0x48000
	v_lshl_add_u64 v[248:249], v[166:167], 0, s[98:99]
	global_load_dwordx4 v[228:231], v[248:249], off offset:256
	s_mov_b32 s98, s61
	s_mov_b32 s99, 0
	v_lshl_add_u64 v[248:249], v[166:167], 0, s[98:99]
	global_load_dwordx4 v[232:235], v[248:249], off
	v_lshl_add_u64 v[248:249], v[166:167], 0, s[28:29]
	global_load_dwordx4 v[236:239], v[248:249], off offset:256
	s_mov_b32 s98, s62
	s_mov_b32 s99, 0
	v_lshl_add_u64 v[248:249], v[166:167], 0, s[98:99]
	global_load_dwordx4 v[240:243], v[248:249], off
	v_lshl_add_u64 v[248:249], v[166:167], 0, s[30:31]
	global_load_dwordx4 v[244:247], v[248:249], off offset:256
	s_mov_b32 s33, 0x18000
	s_mov_b64 s[40:41], 0x18000
	s_waitcnt vmcnt(10)
	v_lshlrev_b32_e32 v200, 16, v136
	v_and_b32_e32 v201, 0xffff0000, v136
	v_pk_add_f32 v[124:125], v[124:125], v[200:201]
	v_lshlrev_b32_e32 v202, 16, v138
	v_lshlrev_b32_e32 v200, 16, v144
	v_and_b32_e32 v201, 0xffff0000, v144
	v_lshlrev_b32_e32 v144, 16, v145
	v_and_b32_e32 v145, 0xffff0000, v145
	v_pk_add_f32 v[116:117], v[116:117], v[200:201]
	v_pk_add_f32 v[144:145], v[118:119], v[144:145]
	v_mul_f32_e32 v119, v117, v117
	v_and_b32_e32 v203, 0xffff0000, v138
	v_fmac_f32_e32 v119, v116, v116
	v_pk_add_f32 v[120:121], v[120:121], v[202:203]
	v_lshlrev_b32_e32 v202, 16, v146
	v_and_b32_e32 v203, 0xffff0000, v146
	v_fmac_f32_e32 v119, v144, v144
	v_pk_add_f32 v[108:109], v[108:109], v[202:203]
	v_fmac_f32_e32 v119, v145, v145
	v_lshlrev_b32_e32 v136, 16, v137
	v_and_b32_e32 v137, 0xffff0000, v137
	v_lshlrev_b32_e32 v204, 16, v140
	v_and_b32_e32 v205, 0xffff0000, v140
	v_lshlrev_b32_e32 v140, 16, v141
	v_and_b32_e32 v141, 0xffff0000, v141
	v_lshlrev_b32_e32 v206, 16, v142
	v_and_b32_e32 v207, 0xffff0000, v142
	v_lshlrev_b32_e32 v142, 16, v143
	v_and_b32_e32 v143, 0xffff0000, v143
	v_lshlrev_b32_e32 v146, 16, v147
	v_and_b32_e32 v147, 0xffff0000, v147
	v_fmac_f32_e32 v119, v108, v108
	v_lshlrev_b32_e32 v138, 16, v139
	v_and_b32_e32 v139, 0xffff0000, v139
	v_pk_add_f32 v[126:127], v[126:127], v[136:137]
	v_pk_add_f32 v[136:137], v[114:115], v[140:141]
	v_pk_add_f32 v[140:141], v[106:107], v[142:143]
	v_cvt_pk_bf16_f32 v106, v120, v121
	v_pk_add_f32 v[110:111], v[110:111], v[146:147]
	v_fmac_f32_e32 v119, v109, v109
	v_pk_add_f32 v[122:123], v[122:123], v[138:139]
	v_pk_add_f32 v[138:139], v[112:113], v[204:205]
	v_pk_add_f32 v[142:143], v[104:105], v[206:207]
	v_cvt_pk_bf16_f32 v104, v124, v125
	v_cvt_pk_bf16_f32 v105, v126, v127
	v_cvt_pk_bf16_f32 v107, v122, v123
	v_cvt_pk_bf16_f32 v112, v138, v139
	v_cvt_pk_bf16_f32 v113, v136, v137
	global_store_dwordx4 v[166:167], v[104:107], off
	v_fmac_f32_e32 v119, v110, v110
	v_cvt_pk_bf16_f32 v114, v142, v143
	v_cvt_pk_bf16_f32 v115, v140, v141
	global_store_dwordx4 v[166:167], v[112:115], off offset:256
	v_cvt_pk_bf16_f32 v106, v108, v109
	v_add_co_u32_e32 v108, vcc, s33, v166
	v_cvt_pk_bf16_f32 v104, v116, v117
	v_cvt_pk_bf16_f32 v105, v144, v145
	v_cvt_pk_bf16_f32 v107, v110, v111
	v_fmac_f32_e32 v119, v111, v111
	v_lshlrev_b32_e32 v110, 16, v192
	v_and_b32_e32 v111, 0xffff0000, v192
	v_lshlrev_b32_e32 v112, 16, v194
	v_and_b32_e32 v113, 0xffff0000, v194
	v_addc_co_u32_e32 v109, vcc, 0, v167, vcc
	global_store_dwordx4 v[174:175], v[104:107], off
	v_lshlrev_b32_e32 v114, 16, v193
	v_and_b32_e32 v115, 0xffff0000, v193
	v_lshlrev_b32_e32 v116, 16, v195
	v_and_b32_e32 v117, 0xffff0000, v195
	s_nop 0
	v_pk_add_f32 v[100:101], v[100:101], v[110:111]
	v_pk_add_f32 v[112:113], v[96:97], v[112:113]
	v_cvt_pk_bf16_f32 v96, v100, v101
	v_pk_add_f32 v[102:103], v[102:103], v[114:115]
	v_pk_add_f32 v[110:111], v[98:99], v[116:117]
	v_cvt_pk_bf16_f32 v97, v102, v103
	v_cvt_pk_bf16_f32 v98, v112, v113
	v_lshlrev_b32_e32 v114, 16, v130
	v_cvt_pk_bf16_f32 v99, v110, v111
	global_store_dwordx4 v[172:173], v[96:99], off offset:256
	v_and_b32_e32 v115, 0xffff0000, v130
	s_mov_b32 s33, 0x40000
	v_mul_f32_e32 v96, v101, v101
	v_fmac_f32_e32 v96, v100, v100
	v_fmac_f32_e32 v96, v102, v102
	v_fmac_f32_e32 v96, v103, v103
	v_fmac_f32_e32 v96, v112, v112
	v_fmac_f32_e32 v96, v113, v113
	v_fmac_f32_e32 v96, v110, v110
	v_fmac_f32_e32 v96, v111, v111
	v_lshl_add_u64 v[100:101], v[166:167], 0, s[40:41]
	v_add_f32_e32 v102, v119, v96
	s_nop 0
	v_lshlrev_b32_e32 v110, 16, v128
	v_and_b32_e32 v111, 0xffff0000, v128
	v_pk_add_f32 v[92:93], v[92:93], v[110:111]
	v_lshlrev_b32_e32 v112, 16, v129
	v_and_b32_e32 v113, 0xffff0000, v129
	v_mul_f32_e32 v103, v93, v93
	v_lshlrev_b32_e32 v116, 16, v131
	v_and_b32_e32 v117, 0xffff0000, v131
	v_pk_add_f32 v[94:95], v[94:95], v[112:113]
	v_pk_add_f32 v[112:113], v[88:89], v[114:115]
	v_cvt_pk_bf16_f32 v88, v92, v93
	v_fmac_f32_e32 v103, v92, v92
	v_add_co_u32_e32 v92, vcc, s33, v166
	v_pk_add_f32 v[110:111], v[90:91], v[116:117]
	v_cvt_pk_bf16_f32 v89, v94, v95
	v_cvt_pk_bf16_f32 v90, v112, v113
	s_nop 0
	v_addc_co_u32_e32 v93, vcc, 0, v167, vcc
	v_cvt_pk_bf16_f32 v91, v110, v111
	global_store_dwordx4 v[170:171], v[88:91], off
	s_nop 0
	v_fmac_f32_e32 v103, v94, v94
	v_fmac_f32_e32 v103, v95, v95
	v_fmac_f32_e32 v103, v112, v112
	v_fmac_f32_e32 v103, v113, v113
	v_fmac_f32_e32 v103, v110, v110
	v_fmac_f32_e32 v103, v111, v111
	v_lshlrev_b32_e32 v94, 16, v132
	v_and_b32_e32 v95, 0xffff0000, v132
	v_lshlrev_b32_e32 v110, 16, v133
	v_and_b32_e32 v111, 0xffff0000, v133
	v_lshlrev_b32_e32 v112, 16, v134
	v_and_b32_e32 v113, 0xffff0000, v134
	v_lshlrev_b32_e32 v114, 16, v135
	v_and_b32_e32 v115, 0xffff0000, v135
	v_pk_add_f32 v[86:87], v[86:87], v[110:111]
	v_pk_add_f32 v[84:85], v[84:85], v[94:95]
	v_pk_add_f32 v[110:111], v[80:81], v[112:113]
	v_cvt_pk_bf16_f32 v80, v84, v85
	v_pk_add_f32 v[94:95], v[82:83], v[114:115]
	v_cvt_pk_bf16_f32 v81, v86, v87
	v_cvt_pk_bf16_f32 v82, v110, v111
	s_mov_b64 s[40:41], 0x40000
	v_cvt_pk_bf16_f32 v83, v94, v95
	global_store_dwordx4 v[168:169], v[80:83], off offset:256
	s_mov_b32 s33, 0x48000
	v_mul_f32_e32 v125, v125, v125
	v_mul_f32_e32 v80, v85, v85
	v_fmac_f32_e32 v80, v84, v84
	v_fmac_f32_e32 v80, v86, v86
	v_fmac_f32_e32 v80, v87, v87
	v_fmac_f32_e32 v80, v110, v110
	v_fmac_f32_e32 v80, v111, v111
	v_fmac_f32_e32 v80, v94, v94
	v_fmac_f32_e32 v80, v95, v95
	v_lshl_add_u64 v[84:85], v[166:167], 0, s[40:41]
	v_add_f32_e32 v86, v103, v80
	s_waitcnt vmcnt(13)
	s_nop 1
	v_mov_b32_e32 v104, v208
	v_mov_b32_e32 v105, v209
	v_mov_b32_e32 v106, v210
	v_mov_b32_e32 v107, v211
	v_mov_b32_e32 v96, v212
	v_mov_b32_e32 v97, v213
	v_mov_b32_e32 v98, v214
	v_mov_b32_e32 v99, v215
	v_mov_b32_e32 v88, v216
	v_mov_b32_e32 v89, v217
	v_mov_b32_e32 v90, v218
	v_mov_b32_e32 v91, v219
	v_lshlrev_b32_e32 v94, 16, v104
	v_and_b32_e32 v95, 0xffff0000, v104
	s_nop 0
	v_pk_add_f32 v[76:77], v[76:77], v[94:95]
	v_lshlrev_b32_e32 v104, 16, v105
	v_and_b32_e32 v105, 0xffff0000, v105
	v_mul_f32_e32 v87, v77, v77
	v_pk_add_f32 v[78:79], v[78:79], v[104:105]
	v_fmac_f32_e32 v87, v76, v76
	v_lshlrev_b32_e32 v110, 16, v106
	v_and_b32_e32 v111, 0xffff0000, v106
	v_fmac_f32_e32 v87, v78, v78
	v_pk_add_f32 v[104:105], v[72:73], v[110:111]
	v_fmac_f32_e32 v87, v79, v79
	v_lshlrev_b32_e32 v106, 16, v107
	v_and_b32_e32 v107, 0xffff0000, v107
	v_fmac_f32_e32 v87, v104, v104
	v_pk_add_f32 v[94:95], v[74:75], v[106:107]
	v_fmac_f32_e32 v87, v105, v105
	v_fmac_f32_e32 v87, v94, v94
	v_cvt_pk_bf16_f32 v73, v78, v79
	v_cvt_pk_bf16_f32 v75, v94, v95
	v_fmac_f32_e32 v87, v95, v95
	v_lshlrev_b32_e32 v78, 16, v96
	v_and_b32_e32 v79, 0xffff0000, v96
	v_lshlrev_b32_e32 v94, 16, v97
	v_and_b32_e32 v95, 0xffff0000, v97
	v_lshlrev_b32_e32 v96, 16, v98
	v_and_b32_e32 v97, 0xffff0000, v98
	v_cvt_pk_bf16_f32 v72, v76, v77
	v_lshlrev_b32_e32 v98, 16, v99
	v_add_co_u32_e32 v76, vcc, s33, v166
	v_and_b32_e32 v99, 0xffff0000, v99
	v_pk_add_f32 v[70:71], v[70:71], v[94:95]
	v_pk_add_f32 v[68:69], v[68:69], v[78:79]
	v_pk_add_f32 v[94:95], v[64:65], v[96:97]
	v_cvt_pk_bf16_f32 v64, v68, v69
	v_cvt_pk_bf16_f32 v74, v104, v105
	v_addc_co_u32_e32 v77, vcc, 0, v167, vcc
	v_pk_add_f32 v[78:79], v[66:67], v[98:99]
	v_cvt_pk_bf16_f32 v65, v70, v71
	v_cvt_pk_bf16_f32 v66, v94, v95
	global_store_dwordx4 v[108:109], v[72:75], off
	v_cvt_pk_bf16_f32 v67, v78, v79
	global_store_dwordx4 v[100:101], v[64:67], off offset:256
	s_nop 0
	s_mov_b64 s[40:41], 0x48000
	v_mul_f32_e32 v64, v69, v69
	v_fmac_f32_e32 v64, v68, v68
	v_fmac_f32_e32 v64, v70, v70
	v_fmac_f32_e32 v64, v71, v71
	v_fmac_f32_e32 v64, v94, v94
	v_fmac_f32_e32 v64, v95, v95
	v_fmac_f32_e32 v64, v78, v78
	v_fmac_f32_e32 v64, v79, v79
	v_add_f32_e32 v68, v87, v64
	v_lshlrev_b32_e32 v64, 16, v89
	v_and_b32_e32 v65, 0xffff0000, v89
	v_lshl_add_u64 v[66:67], v[166:167], 0, s[40:41]
	v_lshlrev_b32_e32 v70, 16, v88
	v_and_b32_e32 v71, 0xffff0000, v88
	v_lshlrev_b32_e32 v78, 16, v90
	v_and_b32_e32 v79, 0xffff0000, v90
	v_lshlrev_b32_e32 v88, 16, v91
	v_and_b32_e32 v89, 0xffff0000, v91
	v_pk_add_f32 v[90:91], v[62:63], v[64:65]
	s_nop 0
	v_pk_add_f32 v[60:61], v[60:61], v[70:71]
	v_pk_add_f32 v[78:79], v[56:57], v[78:79]
	v_mul_f32_e32 v69, v61, v61
	v_fmac_f32_e32 v69, v60, v60
	v_fmac_f32_e32 v69, v90, v90
	v_fmac_f32_e32 v69, v91, v91
	v_fmac_f32_e32 v69, v78, v78
	v_pk_add_f32 v[70:71], v[58:59], v[88:89]
	v_fmac_f32_e32 v69, v79, v79
	v_fmac_f32_e32 v69, v70, v70
	v_cvt_pk_bf16_f32 v58, v78, v79
	v_cvt_pk_bf16_f32 v59, v70, v71
	v_fmac_f32_e32 v69, v71, v71
	s_waitcnt vmcnt(12)
	s_nop 1
	v_mov_b32_e32 v80, v220
	v_mov_b32_e32 v81, v221
	v_mov_b32_e32 v82, v222
	v_mov_b32_e32 v83, v223
	v_mov_b32_e32 v72, v224
	v_mov_b32_e32 v73, v225
	v_mov_b32_e32 v74, v226
	v_mov_b32_e32 v75, v227
	v_mov_b32_e32 v62, v228
	v_mov_b32_e32 v63, v229
	v_mov_b32_e32 v64, v230
	v_mov_b32_e32 v65, v231
	v_lshlrev_b32_e32 v70, 16, v80
	v_and_b32_e32 v71, 0xffff0000, v80
	v_lshlrev_b32_e32 v78, 16, v81
	v_and_b32_e32 v79, 0xffff0000, v81
	v_lshlrev_b32_e32 v80, 16, v82
	v_and_b32_e32 v81, 0xffff0000, v82
	v_lshlrev_b32_e32 v82, 16, v83
	v_and_b32_e32 v83, 0xffff0000, v83
	v_pk_add_f32 v[54:55], v[54:55], v[78:79]
	v_pk_add_f32 v[52:53], v[52:53], v[70:71]
	v_pk_add_f32 v[78:79], v[48:49], v[80:81]
	v_cvt_pk_bf16_f32 v48, v52, v53
	v_pk_add_f32 v[70:71], v[50:51], v[82:83]
	v_cvt_pk_bf16_f32 v49, v54, v55
	v_cvt_pk_bf16_f32 v50, v78, v79
	v_cvt_pk_bf16_f32 v56, v60, v61
	v_add_co_u32_e32 v60, vcc, s61, v166
	v_cvt_pk_bf16_f32 v51, v70, v71
	global_store_dwordx4 v[84:85], v[48:51], off offset:256
	v_cvt_pk_bf16_f32 v57, v90, v91
	s_nop 0
	v_addc_co_u32_e32 v61, vcc, 0, v167, vcc
	v_mul_f32_e32 v48, v53, v53
	v_fmac_f32_e32 v48, v52, v52
	v_fmac_f32_e32 v48, v54, v54
	v_fmac_f32_e32 v48, v55, v55
	global_store_dwordx4 v[92:93], v[56:59], off
	s_nop 0
	v_fmac_f32_e32 v48, v78, v78
	v_fmac_f32_e32 v48, v79, v79
	v_fmac_f32_e32 v48, v70, v70
	v_fmac_f32_e32 v48, v71, v71
	v_lshl_add_u64 v[52:53], v[166:167], 0, s[28:29]
	v_add_f32_e32 v54, v69, v48
	s_nop 0
	v_mul_f32_e32 v139, v139, v139
	v_fmac_f32_e32 v125, v124, v124
	v_fmac_f32_e32 v139, v138, v138
	v_fmac_f32_e32 v125, v126, v126
	v_fmac_f32_e32 v139, v136, v136
	v_fmac_f32_e32 v125, v127, v127
	v_fmac_f32_e32 v139, v137, v137
	v_fmac_f32_e32 v125, v120, v120
	v_fmac_f32_e32 v139, v142, v142
	v_lshlrev_b32_e32 v70, 16, v72
	v_and_b32_e32 v71, 0xffff0000, v72
	v_pk_add_f32 v[44:45], v[44:45], v[70:71]
	v_lshlrev_b32_e32 v72, 16, v73
	v_and_b32_e32 v73, 0xffff0000, v73
	v_mul_f32_e32 v55, v45, v45
	v_pk_add_f32 v[46:47], v[46:47], v[72:73]
	v_fmac_f32_e32 v55, v44, v44
	v_lshlrev_b32_e32 v78, 16, v74
	v_and_b32_e32 v79, 0xffff0000, v74
	v_fmac_f32_e32 v55, v46, v46
	v_pk_add_f32 v[72:73], v[40:41], v[78:79]
	v_fmac_f32_e32 v55, v47, v47
	v_lshlrev_b32_e32 v74, 16, v75
	v_and_b32_e32 v75, 0xffff0000, v75
	v_cvt_pk_bf16_f32 v40, v44, v45
	v_fmac_f32_e32 v55, v72, v72
	v_add_co_u32_e32 v44, vcc, s62, v166
	v_pk_add_f32 v[70:71], v[42:43], v[74:75]
	v_cvt_pk_bf16_f32 v41, v46, v47
	v_cvt_pk_bf16_f32 v42, v72, v73
	v_fmac_f32_e32 v55, v73, v73
	v_cvt_pk_bf16_f32 v43, v70, v71
	v_addc_co_u32_e32 v45, vcc, 0, v167, vcc
	global_store_dwordx4 v[76:77], v[40:43], off
	v_fmac_f32_e32 v55, v70, v70
	s_nop 0
	v_lshlrev_b32_e32 v46, 16, v62
	v_and_b32_e32 v47, 0xffff0000, v62
	v_fmac_f32_e32 v55, v71, v71
	v_lshlrev_b32_e32 v70, 16, v64
	v_and_b32_e32 v71, 0xffff0000, v64
	v_lshlrev_b32_e32 v64, 16, v65
	v_and_b32_e32 v65, 0xffff0000, v65
	v_pk_add_f32 v[36:37], v[36:37], v[46:47]
	v_lshlrev_b32_e32 v62, 16, v63
	v_and_b32_e32 v63, 0xffff0000, v63
	v_pk_add_f32 v[46:47], v[34:35], v[64:65]
	v_mul_f32_e32 v64, v37, v37
	v_pk_add_f32 v[38:39], v[38:39], v[62:63]
	v_pk_add_f32 v[62:63], v[32:33], v[70:71]
	v_cvt_pk_bf16_f32 v32, v36, v37
	v_cvt_pk_bf16_f32 v33, v38, v39
	v_cvt_pk_bf16_f32 v35, v46, v47
	v_fmac_f32_e32 v64, v36, v36
	v_cvt_pk_bf16_f32 v34, v62, v63
	v_lshl_add_u64 v[36:37], v[166:167], 0, s[30:31]
	global_store_dwordx4 v[66:67], v[32:35], off offset:256
	s_nop 0
	v_fmac_f32_e32 v64, v38, v38
	v_fmac_f32_e32 v64, v39, v39
	v_fmac_f32_e32 v64, v62, v62
	v_fmac_f32_e32 v64, v63, v63
	v_fmac_f32_e32 v64, v46, v46
	v_fmac_f32_e32 v64, v47, v47
	v_fmac_f32_e32 v125, v121, v121
	v_fmac_f32_e32 v139, v143, v143
	v_fmac_f32_e32 v125, v122, v122
	v_fmac_f32_e32 v139, v140, v140
	v_fmac_f32_e32 v125, v123, v123
	v_fmac_f32_e32 v139, v141, v141
	s_waitcnt vmcnt(12)
	s_nop 1
	v_mov_b32_e32 v56, v232
	v_mov_b32_e32 v57, v233
	v_mov_b32_e32 v58, v234
	v_mov_b32_e32 v59, v235
	v_mov_b32_e32 v48, v236
	v_mov_b32_e32 v49, v237
	v_mov_b32_e32 v50, v238
	v_mov_b32_e32 v51, v239
	v_mov_b32_e32 v40, v240
	v_mov_b32_e32 v41, v241
	v_mov_b32_e32 v42, v242
	v_mov_b32_e32 v43, v243
	v_mov_b32_e32 v32, v244
	v_mov_b32_e32 v33, v245
	v_mov_b32_e32 v34, v246
	v_mov_b32_e32 v35, v247
	v_lshlrev_b32_e32 v38, 16, v56
	v_and_b32_e32 v39, 0xffff0000, v56
	v_lshlrev_b32_e32 v46, 16, v57
	v_and_b32_e32 v47, 0xffff0000, v57
	v_lshlrev_b32_e32 v56, 16, v58
	v_and_b32_e32 v57, 0xffff0000, v58
	v_pk_add_f32 v[28:29], v[28:29], v[38:39]
	v_lshlrev_b32_e32 v58, 16, v59
	v_and_b32_e32 v59, 0xffff0000, v59
	v_pk_add_f32 v[30:31], v[30:31], v[46:47]
	v_pk_add_f32 v[46:47], v[24:25], v[56:57]
	v_mul_f32_e32 v56, v29, v29
	v_pk_add_f32 v[38:39], v[26:27], v[58:59]
	v_cvt_pk_bf16_f32 v24, v28, v29
	v_cvt_pk_bf16_f32 v25, v30, v31
	v_cvt_pk_bf16_f32 v26, v46, v47
	v_fmac_f32_e32 v56, v28, v28
	v_cvt_pk_bf16_f32 v27, v38, v39
	global_store_dwordx4 v[60:61], v[24:27], off
	v_fmac_f32_e32 v56, v30, v30
	v_lshlrev_b32_e32 v28, 16, v50
	v_lshlrev_b32_e32 v24, 16, v48
	v_and_b32_e32 v25, 0xffff0000, v48
	v_lshlrev_b32_e32 v26, 16, v49
	v_and_b32_e32 v27, 0xffff0000, v49
	v_and_b32_e32 v29, 0xffff0000, v50
	v_fmac_f32_e32 v56, v31, v31
	v_lshlrev_b32_e32 v30, 16, v51
	v_and_b32_e32 v31, 0xffff0000, v51
	v_pk_add_f32 v[22:23], v[22:23], v[26:27]
	v_pk_add_f32 v[20:21], v[20:21], v[24:25]
	v_pk_add_f32 v[26:27], v[12:13], v[28:29]
	v_cvt_pk_bf16_f32 v12, v20, v21
	v_pk_add_f32 v[24:25], v[14:15], v[30:31]
	v_cvt_pk_bf16_f32 v13, v22, v23
	v_cvt_pk_bf16_f32 v14, v26, v27
	v_fmac_f32_e32 v56, v46, v46
	v_cvt_pk_bf16_f32 v15, v24, v25
	global_store_dwordx4 v[52:53], v[12:15], off offset:256
	v_fmac_f32_e32 v56, v47, v47
	v_fmac_f32_e32 v56, v38, v38
	v_mul_f32_e32 v12, v21, v21
	v_fmac_f32_e32 v12, v20, v20
	v_fmac_f32_e32 v12, v22, v22
	v_fmac_f32_e32 v12, v23, v23
	v_fmac_f32_e32 v12, v26, v26
	v_fmac_f32_e32 v12, v27, v27
	v_fmac_f32_e32 v12, v24, v24
	v_fmac_f32_e32 v56, v39, v39
	v_fmac_f32_e32 v12, v25, v25
	v_add_f32_e32 v24, v56, v12
	v_lshlrev_b32_e32 v12, 16, v40
	v_and_b32_e32 v13, 0xffff0000, v40
	v_pk_add_f32 v[12:13], v[16:17], v[12:13]
	v_lshlrev_b32_e32 v14, 16, v41
	v_and_b32_e32 v15, 0xffff0000, v41
	v_lshlrev_b32_e32 v20, 16, v42
	v_and_b32_e32 v21, 0xffff0000, v42
	v_mul_f32_e32 v25, v13, v13
	v_lshlrev_b32_e32 v22, 16, v43
	v_and_b32_e32 v23, 0xffff0000, v43
	v_pk_add_f32 v[14:15], v[18:19], v[14:15]
	v_pk_add_f32 v[18:19], v[8:9], v[20:21]
	v_cvt_pk_bf16_f32 v8, v12, v13
	v_cvt_pk_bf16_f32 v9, v14, v15
	v_fmac_f32_e32 v25, v12, v12
	v_pk_add_f32 v[16:17], v[10:11], v[22:23]
	v_cvt_pk_bf16_f32 v10, v18, v19
	v_fmac_f32_e32 v25, v14, v14
	v_cvt_pk_bf16_f32 v11, v16, v17
	global_store_dwordx4 v[44:45], v[8:11], off
	v_fmac_f32_e32 v25, v15, v15
	v_lshlrev_b32_e32 v12, 16, v34
	v_lshlrev_b32_e32 v8, 16, v32
	v_and_b32_e32 v9, 0xffff0000, v32
	v_and_b32_e32 v13, 0xffff0000, v34
	v_pk_add_f32 v[4:5], v[4:5], v[8:9]
	v_fmac_f32_e32 v25, v18, v18
	v_lshlrev_b32_e32 v10, 16, v33
	v_and_b32_e32 v11, 0xffff0000, v33
	v_pk_add_f32 v[22:23], v[0:1], v[12:13]
	v_mul_f32_e32 v0, v5, v5
	v_fmac_f32_e32 v25, v19, v19
	v_pk_add_f32 v[18:19], v[6:7], v[10:11]
	v_fmac_f32_e32 v0, v4, v4
	v_fmac_f32_e32 v0, v18, v18
	v_fmac_f32_e32 v0, v19, v19
	v_lshlrev_b32_e32 v14, 16, v35
	v_and_b32_e32 v15, 0xffff0000, v35
	v_fmac_f32_e32 v0, v22, v22
	v_pk_add_f32 v[20:21], v[2:3], v[14:15]
	v_fmac_f32_e32 v0, v23, v23
	v_fmac_f32_e32 v25, v16, v16
	v_fmac_f32_e32 v0, v20, v20
	v_fmac_f32_e32 v25, v17, v17
	v_fmac_f32_e32 v0, v21, v21
	v_add_f32_e32 v118, v125, v139
	v_add_f32_e32 v55, v55, v64
	v_add_f32_e32 v14, v25, v0
	v_cvt_pk_bf16_f32 v16, v4, v5
	ds_bpermute_b32 v1, v181, v118
	ds_bpermute_b32 v2, v181, v102
	ds_bpermute_b32 v4, v181, v86
	ds_bpermute_b32 v6, v181, v68
	ds_bpermute_b32 v8, v181, v54
	ds_bpermute_b32 v10, v181, v55
	ds_bpermute_b32 v12, v181, v24
	ds_bpermute_b32 v15, v181, v14
	s_waitcnt lgkmcnt(0)
	v_add_f32_e32 v0, v118, v1
	v_add_f32_e32 v2, v102, v2
	v_add_f32_e32 v4, v86, v4
	v_add_f32_e32 v6, v68, v6
	v_add_f32_e32 v8, v54, v8
	v_add_f32_e32 v10, v55, v10
	v_add_f32_e32 v12, v24, v12
	v_add_f32_e32 v14, v14, v15
	ds_bpermute_b32 v1, v182, v0
	ds_bpermute_b32 v3, v182, v2
	ds_bpermute_b32 v5, v182, v4
	ds_bpermute_b32 v7, v182, v6
	ds_bpermute_b32 v9, v182, v8
	ds_bpermute_b32 v11, v182, v10
	ds_bpermute_b32 v13, v182, v12
	ds_bpermute_b32 v15, v182, v14
	v_cvt_pk_bf16_f32 v17, v18, v19
	v_cvt_pk_bf16_f32 v18, v22, v23
	v_cvt_pk_bf16_f32 v19, v20, v21
	global_store_dwordx4 v[36:37], v[16:19], off offset:256
	s_and_saveexec_b64 s[40:41], s[4:5]
	s_cbranch_execz .LBB0_958
	s_waitcnt lgkmcnt(6)
	v_add_f32_e32 v2, v2, v3
	v_add_f32_e32 v0, v0, v1
	v_add_u32_e32 v1, s76, v183
	s_waitcnt lgkmcnt(2)
	v_add_f32_e32 v10, v10, v11
	v_add_f32_e32 v8, v8, v9
	v_add_f32_e32 v6, v6, v7
	v_add_f32_e32 v4, v4, v5
	ds_write2st64_b32 v1, v0, v2 offset1:1
	ds_write2st64_b32 v1, v4, v6 offset0:2 offset1:3
	v_add_u32_e32 v0, s76, v187
	s_waitcnt lgkmcnt(2)
	v_add_f32_e32 v14, v14, v15
	v_add_f32_e32 v12, v12, v13
	ds_write2st64_b32 v0, v8, v10 offset1:1
	ds_write2st64_b32 v0, v12, v14 offset0:2 offset1:3
